# O2 top-k threshold search: per-lane VALU counting + DPP reduce instead of ballot/SALU popcounts, specialised on live key stages; no-tie fast path builds mask words with v_writelane
# speedup vs baseline: 1.4731x; 1.4731x over previous
; __global__ void __launch_bounds__(512, 2) mega_fwd(KArgs a) {
;     ...
;                                 float sc = odd ? sc2[1] : sc2[0];
;                                 if (sc == 0.f) sc = 0.f;
;                                 const unsigned ubits = __float_as_uint(sc);
;                                 kv = (ubits & 0x80000000u) ? ~ubits : (ubits | 0x80000000u);
;                                 if (32 * jj + 16 * odd + n > tq) kv = 0u;
;                             }
;                             key[jj] = kv;
;     ...
;                     const unsigned cand = tau | (1u << bit);
;                     int c0 = 0, c1 = 0;
; #pragma unroll
;                     for (int jj = 0; jj < 64; ++jj) { const unsigned long long bm = __ballot(key[jj] >= cand); c0 += __popc((unsigned)bm); c1 += __popc((unsigned)(bm >> 32)); }
.LBB0_3563:
	v_pk_add_f32 v[2:3], v[126:127], v[130:131]
	v_pk_add_f32 v[4:5], v[128:129], v[132:133]
	s_movk_i32 s5, 0x100
	v_cndmask_b32_e64 v3, v5, v3, s[10:11]
	v_cndmask_b32_e64 v2, v4, v2, s[10:11]
	v_cmp_neq_f32_e32 vcc, 0, v3
	v_cmp_gt_i32_e64 s[86:87], s5, v216
	s_mov_b64 s[0:1], s[86:87]
	v_cndmask_b32_e32 v4, 0, v3, vcc
	v_cmp_neq_f32_e32 vcc, 0, v2
	v_and_b32_e32 v3, 0x7fffffff, v4
	v_xor_b32_e32 v6, -1, v4
	v_cndmask_b32_e32 v5, 0, v2, vcc
	v_and_b32_e32 v2, 0x7fffffff, v5
	v_xor_b32_e32 v7, -1, v5
	v_pk_add_f32 v[2:3], v[2:3], 0 neg_lo:[1,1] neg_hi:[1,1]
	v_cmp_gt_i32_e32 vcc, 0, v5
	s_nop 1
	v_cndmask_b32_e32 v5, v2, v7, vcc
	v_cmp_gt_i32_e32 vcc, 0, v4
	s_nop 1
	v_cndmask_b32_e32 v2, v3, v6, vcc
	v_cmp_le_i32_e32 vcc, v1, v216
	v_pk_add_f32 v[6:7], v[136:137], v[140:141]
	s_nop 0
	v_cndmask_b32_e32 v3, 0, v2, vcc
	v_or_b32_e32 v2, 32, v1
	v_cmp_le_i32_e32 vcc, v2, v216
	s_nop 1
	v_cndmask_b32_e32 v2, 0, v5, vcc
	v_pk_add_f32 v[4:5], v[134:135], v[138:139]
	s_nop 0
	v_cndmask_b32_e64 v5, v7, v5, s[10:11]
	v_cndmask_b32_e64 v4, v6, v4, s[10:11]
	v_cmp_neq_f32_e32 vcc, 0, v5
	s_nop 1
	v_cndmask_b32_e32 v6, 0, v5, vcc
	v_cmp_neq_f32_e32 vcc, 0, v4
	v_and_b32_e32 v5, 0x7fffffff, v6
	v_xor_b32_e32 v8, -1, v6
	v_cndmask_b32_e32 v7, 0, v4, vcc
	v_and_b32_e32 v4, 0x7fffffff, v7
	v_xor_b32_e32 v9, -1, v7
	v_pk_add_f32 v[4:5], v[4:5], 0 neg_lo:[1,1] neg_hi:[1,1]
	v_cmp_gt_i32_e32 vcc, 0, v7
	s_nop 1
	v_cndmask_b32_e32 v7, v4, v9, vcc
	v_cmp_gt_i32_e32 vcc, 0, v6
	s_nop 1
	v_cndmask_b32_e32 v4, v5, v8, vcc
	v_or_b32_e32 v5, 64, v1
	v_cmp_le_i32_e32 vcc, v5, v216
	v_pk_add_f32 v[8:9], v[144:145], v[148:149]
	s_nop 0
	v_cndmask_b32_e32 v5, 0, v4, vcc
	v_or_b32_e32 v4, 0x60, v1
	v_cmp_le_i32_e32 vcc, v4, v216
	s_nop 1
	v_cndmask_b32_e32 v4, 0, v7, vcc
	v_pk_add_f32 v[6:7], v[142:143], v[146:147]
	s_nop 0
	v_cndmask_b32_e64 v7, v9, v7, s[10:11]
	v_cndmask_b32_e64 v6, v8, v6, s[10:11]
	v_cmp_neq_f32_e32 vcc, 0, v7
	s_nop 1
	v_cndmask_b32_e32 v8, 0, v7, vcc
	v_cmp_neq_f32_e32 vcc, 0, v6
	v_and_b32_e32 v7, 0x7fffffff, v8
	s_waitcnt vmcnt(3)
	v_xor_b32_e32 v10, -1, v8
	v_cndmask_b32_e32 v9, 0, v6, vcc
	v_and_b32_e32 v6, 0x7fffffff, v9
	v_xor_b32_e32 v11, -1, v9
	v_pk_add_f32 v[6:7], v[6:7], 0 neg_lo:[1,1] neg_hi:[1,1]
	v_cmp_gt_i32_e32 vcc, 0, v9
	s_nop 1
	v_cndmask_b32_e32 v9, v6, v11, vcc
	v_cmp_gt_i32_e32 vcc, 0, v8
	s_nop 1
	v_cndmask_b32_e32 v6, v7, v10, vcc
	v_or_b32_e32 v7, 0x80, v1
	v_cmp_le_i32_e32 vcc, v7, v216
	v_pk_add_f32 v[10:11], v[154:155], v[156:157]
	s_nop 0
	v_cndmask_b32_e32 v7, 0, v6, vcc
	v_or_b32_e32 v6, 0xa0, v1
	v_cmp_le_i32_e32 vcc, v6, v216
	s_nop 1
	v_cndmask_b32_e32 v6, 0, v9, vcc
	v_pk_add_f32 v[8:9], v[150:151], v[152:153]
	s_nop 0
	v_cndmask_b32_e64 v9, v11, v9, s[10:11]
	v_cndmask_b32_e64 v8, v10, v8, s[10:11]
	v_cmp_neq_f32_e32 vcc, 0, v9
	s_nop 1
	v_cndmask_b32_e32 v10, 0, v9, vcc
	v_cmp_neq_f32_e32 vcc, 0, v8
	v_and_b32_e32 v9, 0x7fffffff, v10
	v_xor_b32_e32 v12, -1, v10
	v_cndmask_b32_e32 v11, 0, v8, vcc
	v_and_b32_e32 v8, 0x7fffffff, v11
	v_xor_b32_e32 v13, -1, v11
	v_pk_add_f32 v[8:9], v[8:9], 0 neg_lo:[1,1] neg_hi:[1,1]
	v_cmp_gt_i32_e32 vcc, 0, v11
	s_nop 1
	v_cndmask_b32_e32 v11, v8, v13, vcc
	v_cmp_gt_i32_e32 vcc, 0, v10
	v_mov_b32_e32 v10, 0
	s_nop 0
	v_cndmask_b32_e32 v8, v9, v12, vcc
	v_or_b32_e32 v9, 0xc0, v1
	v_cmp_le_i32_e32 vcc, v9, v216
	s_nop 1
	v_cndmask_b32_e32 v9, 0, v8, vcc
	v_or_b32_e32 v8, 0xe0, v1
	v_cmp_le_i32_e32 vcc, v8, v216
	s_nop 1
	v_cndmask_b32_e32 v8, 0, v11, vcc
	v_mov_b32_e32 v11, 31
	s_waitcnt vmcnt(0)
	s_lshr_b32 s2, s6, 4
	s_cmp_eq_u32 s2, 0
	s_cbranch_scc1 .Lmy_sel_loop_1
	s_cmp_eq_u32 s2, 1
	s_cbranch_scc1 .Lmy_sel_loop_2
	s_cmp_eq_u32 s2, 2
	s_cbranch_scc1 .Lmy_sel_loop_3
	s_cmp_eq_u32 s2, 3
	s_cbranch_scc1 .Lmy_sel_loop_4
	s_cmp_eq_u32 s2, 4
	s_cbranch_scc1 .Lmy_sel_loop_5
	s_cmp_eq_u32 s2, 5
	s_cbranch_scc1 .Lmy_sel_loop_6
	s_cmp_eq_u32 s2, 6
	s_cbranch_scc1 .Lmy_sel_loop_7
.Lmy_sel_loop_8:
	v_lshl_or_b32 v12, 1, v11, v10
	v_mov_b32_e32 v13, 0
	v_cmp_ge_u32_e64 s[84:85], v3, v12
	v_cmp_ge_u32_e64 s[76:77], v2, v12
	v_cmp_ge_u32_e64 s[74:75], v5, v12
	v_addc_co_u32_e64 v13, vcc, 0, v13, s[84:85]
	v_cmp_ge_u32_e64 s[84:85], v4, v12
	v_addc_co_u32_e64 v13, vcc, 0, v13, s[76:77]
	v_cmp_ge_u32_e64 s[76:77], v7, v12
	v_addc_co_u32_e64 v13, vcc, 0, v13, s[74:75]
	v_cmp_ge_u32_e64 s[74:75], v6, v12
	v_addc_co_u32_e64 v13, vcc, 0, v13, s[84:85]
	v_cmp_ge_u32_e64 s[84:85], v9, v12
	v_addc_co_u32_e64 v13, vcc, 0, v13, s[76:77]
	v_cmp_ge_u32_e64 s[76:77], v8, v12
	v_addc_co_u32_e64 v13, vcc, 0, v13, s[74:75]
	v_cmp_ge_u32_e64 s[74:75], v102, v12
	v_addc_co_u32_e64 v13, vcc, 0, v13, s[84:85]
	v_cmp_ge_u32_e64 s[84:85], v97, v12
	v_addc_co_u32_e64 v13, vcc, 0, v13, s[76:77]
	v_cmp_ge_u32_e64 s[76:77], v104, v12
	v_addc_co_u32_e64 v13, vcc, 0, v13, s[74:75]
	v_cmp_ge_u32_e64 s[74:75], v99, v12
	v_addc_co_u32_e64 v13, vcc, 0, v13, s[84:85]
	v_cmp_ge_u32_e64 s[84:85], v106, v12
	v_addc_co_u32_e64 v13, vcc, 0, v13, s[76:77]
	v_cmp_ge_u32_e64 s[76:77], v101, v12
	v_addc_co_u32_e64 v13, vcc, 0, v13, s[74:75]
	v_cmp_ge_u32_e64 s[74:75], v108, v12
	v_addc_co_u32_e64 v13, vcc, 0, v13, s[84:85]
	v_cmp_ge_u32_e64 s[84:85], v103, v12
	v_addc_co_u32_e64 v13, vcc, 0, v13, s[76:77]
	v_cmp_ge_u32_e64 s[76:77], v110, v12
	v_addc_co_u32_e64 v13, vcc, 0, v13, s[74:75]
	v_cmp_ge_u32_e64 s[74:75], v105, v12
	v_addc_co_u32_e64 v13, vcc, 0, v13, s[84:85]
	v_cmp_ge_u32_e64 s[84:85], v112, v12
	v_addc_co_u32_e64 v13, vcc, 0, v13, s[76:77]
	v_cmp_ge_u32_e64 s[76:77], v107, v12
	v_addc_co_u32_e64 v13, vcc, 0, v13, s[74:75]
	v_cmp_ge_u32_e64 s[74:75], v114, v12
	v_addc_co_u32_e64 v13, vcc, 0, v13, s[84:85]
; __global__ void __launch_bounds__(512, 2) mega_fwd(KArgs a) {
;     ...
;                     int c0 = 0, c1 = 0;
; #pragma unroll
;                     for (int jj = 0; jj < 64; ++jj) { const unsigned long long bm = __ballot(key[jj] >= cand); c0 += __popc((unsigned)bm); c1 += __popc((unsigned)(bm >> 32)); }
;                     const int cnt = (lane < 32) ? c0 : c1;
;                     if (cnt >= 256) tau = cand;
;                     done_sel = done_sel || (cnt == 256);
;                     if (__ballot(!done_sel) == 0ull) break;
;                 }
	v_cmp_ge_u32_e64 s[84:85], v109, v12
	v_addc_co_u32_e64 v13, vcc, 0, v13, s[76:77]
	v_cmp_ge_u32_e64 s[76:77], v116, v12
	v_addc_co_u32_e64 v13, vcc, 0, v13, s[74:75]
	v_cmp_ge_u32_e64 s[74:75], v111, v12
	v_addc_co_u32_e64 v13, vcc, 0, v13, s[84:85]
	v_cmp_ge_u32_e64 s[84:85], v118, v12
	v_addc_co_u32_e64 v13, vcc, 0, v13, s[76:77]
	v_cmp_ge_u32_e64 s[76:77], v113, v12
	v_addc_co_u32_e64 v13, vcc, 0, v13, s[74:75]
	v_cmp_ge_u32_e64 s[74:75], v120, v12
	v_addc_co_u32_e64 v13, vcc, 0, v13, s[84:85]
	v_cmp_ge_u32_e64 s[84:85], v115, v12
	v_addc_co_u32_e64 v13, vcc, 0, v13, s[76:77]
	v_cmp_ge_u32_e64 s[76:77], v122, v12
	v_addc_co_u32_e64 v13, vcc, 0, v13, s[74:75]
	v_cmp_ge_u32_e64 s[74:75], v117, v12
	v_addc_co_u32_e64 v13, vcc, 0, v13, s[84:85]
	v_cmp_ge_u32_e64 s[84:85], v124, v12
	v_addc_co_u32_e64 v13, vcc, 0, v13, s[76:77]
	v_cmp_ge_u32_e64 s[76:77], v119, v12
	v_addc_co_u32_e64 v13, vcc, 0, v13, s[74:75]
	v_cmp_ge_u32_e64 s[74:75], v158, v12
	v_addc_co_u32_e64 v13, vcc, 0, v13, s[84:85]
	v_cmp_ge_u32_e64 s[84:85], v121, v12
	v_addc_co_u32_e64 v13, vcc, 0, v13, s[76:77]
	v_cmp_ge_u32_e64 s[76:77], v160, v12
	v_addc_co_u32_e64 v13, vcc, 0, v13, s[74:75]
	v_cmp_ge_u32_e64 s[74:75], v123, v12
	v_addc_co_u32_e64 v13, vcc, 0, v13, s[84:85]
	v_cmp_ge_u32_e64 s[84:85], v162, v12
	v_addc_co_u32_e64 v13, vcc, 0, v13, s[76:77]
	v_cmp_ge_u32_e64 s[76:77], v125, v12
	v_addc_co_u32_e64 v13, vcc, 0, v13, s[74:75]
	v_cmp_ge_u32_e64 s[74:75], v164, v12
	v_addc_co_u32_e64 v13, vcc, 0, v13, s[84:85]
	v_cmp_ge_u32_e64 s[84:85], v159, v12
	v_addc_co_u32_e64 v13, vcc, 0, v13, s[76:77]
	v_cmp_ge_u32_e64 s[76:77], v168, v12
	v_addc_co_u32_e64 v13, vcc, 0, v13, s[74:75]
	v_cmp_ge_u32_e64 s[74:75], v161, v12
	v_addc_co_u32_e64 v13, vcc, 0, v13, s[84:85]
	v_cmp_ge_u32_e64 s[84:85], v170, v12
	v_addc_co_u32_e64 v13, vcc, 0, v13, s[76:77]
	v_cmp_ge_u32_e64 s[76:77], v163, v12
	v_addc_co_u32_e64 v13, vcc, 0, v13, s[74:75]
	v_cmp_ge_u32_e64 s[74:75], v172, v12
	v_addc_co_u32_e64 v13, vcc, 0, v13, s[84:85]
	v_cmp_ge_u32_e64 s[84:85], v165, v12
	v_addc_co_u32_e64 v13, vcc, 0, v13, s[76:77]
	v_cmp_ge_u32_e64 s[76:77], v174, v12
	v_addc_co_u32_e64 v13, vcc, 0, v13, s[74:75]
	v_cmp_ge_u32_e64 s[74:75], v169, v12
	v_addc_co_u32_e64 v13, vcc, 0, v13, s[84:85]
	v_cmp_ge_u32_e64 s[84:85], v176, v12
	v_addc_co_u32_e64 v13, vcc, 0, v13, s[76:77]
	v_cmp_ge_u32_e64 s[76:77], v171, v12
	v_addc_co_u32_e64 v13, vcc, 0, v13, s[74:75]
	v_cmp_ge_u32_e64 s[74:75], v178, v12
	v_addc_co_u32_e64 v13, vcc, 0, v13, s[84:85]
	v_cmp_ge_u32_e64 s[84:85], v173, v12
	v_addc_co_u32_e64 v13, vcc, 0, v13, s[76:77]
	v_cmp_ge_u32_e64 s[76:77], v180, v12
	v_addc_co_u32_e64 v13, vcc, 0, v13, s[74:75]
	v_cmp_ge_u32_e64 s[74:75], v175, v12
	v_addc_co_u32_e64 v13, vcc, 0, v13, s[84:85]
	v_cmp_ge_u32_e64 s[84:85], v182, v12
	v_addc_co_u32_e64 v13, vcc, 0, v13, s[76:77]
	v_cmp_ge_u32_e64 s[76:77], v177, v12
	v_addc_co_u32_e64 v13, vcc, 0, v13, s[74:75]
	v_cmp_ge_u32_e64 s[74:75], v184, v12
	v_addc_co_u32_e64 v13, vcc, 0, v13, s[84:85]
	v_cmp_ge_u32_e64 s[84:85], v179, v12
	v_addc_co_u32_e64 v13, vcc, 0, v13, s[76:77]
	v_cmp_ge_u32_e64 s[76:77], v186, v12
	v_addc_co_u32_e64 v13, vcc, 0, v13, s[74:75]
	v_cmp_ge_u32_e64 s[74:75], v181, v12
	v_addc_co_u32_e64 v13, vcc, 0, v13, s[84:85]
	v_cmp_ge_u32_e64 s[84:85], v188, v12
	v_addc_co_u32_e64 v13, vcc, 0, v13, s[76:77]
	v_cmp_ge_u32_e64 s[76:77], v183, v12
	v_addc_co_u32_e64 v13, vcc, 0, v13, s[74:75]
	v_cmp_ge_u32_e64 s[74:75], v190, v12
	v_addc_co_u32_e64 v13, vcc, 0, v13, s[84:85]
	v_cmp_ge_u32_e64 s[84:85], v185, v12
	s_nop 1
	v_addc_co_u32_e64 v13, vcc, 0, v13, s[76:77]
	v_addc_co_u32_e64 v13, vcc, 0, v13, s[74:75]
	v_addc_co_u32_e64 v13, vcc, 0, v13, s[84:85]
	s_nop 1
	v_add_u32_dpp v13, v13, v13 quad_perm:[1,0,3,2] row_mask:0xf bank_mask:0xf
	s_nop 1
	v_add_u32_dpp v13, v13, v13 quad_perm:[2,3,0,1] row_mask:0xf bank_mask:0xf
	s_nop 1
	v_add_u32_dpp v13, v13, v13 row_half_mirror row_mask:0xf bank_mask:0xf
	s_nop 1
	v_add_u32_dpp v13, v13, v13 row_mirror row_mask:0xf bank_mask:0xf
	v_mov_b32_e32 v14, v13
	s_nop 1
	v_permlane16_swap_b32 v14, v13
	v_add_u32_e32 v13, v13, v14
	s_movk_i32 s2, 0xff
	v_cmp_lt_i32_e32 vcc, s2, v13
	s_nop 1
	v_cndmask_b32_e32 v10, v10, v12, vcc
	v_cmp_eq_u32_e32 vcc, s5, v13
	s_or_b64 s[0:1], s[0:1], vcc
	s_xor_b64 s[2:3], s[0:1], -1
	v_cndmask_b32_e64 v12, 0, 1, s[2:3]
	v_cmp_ne_u32_e32 vcc, 0, v12
	s_cmp_lg_u64 vcc, 0
	s_cselect_b64 s[2:3], -1, 0
	v_add_co_u32_e32 v11, vcc, -1, v11
	s_and_b64 s[2:3], s[2:3], vcc
	s_and_b64 vcc, exec, s[2:3]
	s_cbranch_vccnz .Lmy_sel_loop_8
	s_andn2_b64 s[2:3], exec, s[0:1]
	s_cbranch_scc0 .Lmy_sel_fast_8
	s_branch .Lmy_sel_slow
; __global__ void __launch_bounds__(512, 2) mega_fwd(KArgs a) {
;     ...
;                 if (all_valid) tau = 1u;
;                 int g0 = 0, g1 = 0, e0 = 0, e1 = 0;
; #pragma unroll
;                 for (int jj = 0; jj < 64; ++jj) {
;                     const unsigned long long bg = __ballot(key[jj] > tau), be = __ballot(key[jj] == tau);
;                     g0 += __popc((unsigned)bg); g1 += __popc((unsigned)(bg >> 32)); e0 += __popc((unsigned)be); e1 += __popc((unsigned)(be >> 32));
;                 }
;                 const int cgt = (lane < 32) ? g0 : g1, ceq = (lane < 32) ? e0 : e1;
;                 const int need_eq = all_valid ? (1 << 20) : 256 - cgt;
;                 const bool ties = (!all_valid) && (ceq > need_eq);
;                 unsigned w0 = 0u, w1 = 0u;
;                 if (__ballot(ties) == 0ull) {
; #pragma unroll
;                     for (int jj = 0; jj < 64; ++jj) {
;                         const unsigned long long bm = __ballot(key[jj] >= tau);
;                         if (lane == 0) { wscr[jj] = (unsigned)bm; wscr[64 + jj] = (unsigned)(bm >> 32); }
;                     }
.Lmy_sel_fast_8:
	v_cndmask_b32_e64 v12, v10, 1, s[86:87]
	v_mov_b32_e32 v13, 0
	v_mov_b32_e32 v14, 0
	v_cmp_ge_u32_e64 s[84:85], v3, v12
	v_cmp_ge_u32_e64 s[76:77], v2, v12
	v_cmp_ge_u32_e64 s[74:75], v5, v12
	v_writelane_b32 v13, s84, 0
	v_writelane_b32 v14, s85, 0
	v_cmp_ge_u32_e64 s[84:85], v4, v12
	v_writelane_b32 v13, s76, 1
	v_writelane_b32 v14, s77, 1
	v_cmp_ge_u32_e64 s[76:77], v7, v12
	v_writelane_b32 v13, s74, 2
	v_writelane_b32 v14, s75, 2
	v_cmp_ge_u32_e64 s[74:75], v6, v12
	v_writelane_b32 v13, s84, 3
	v_writelane_b32 v14, s85, 3
	v_cmp_ge_u32_e64 s[84:85], v9, v12
	v_writelane_b32 v13, s76, 4
	v_writelane_b32 v14, s77, 4
	v_cmp_ge_u32_e64 s[76:77], v8, v12
	v_writelane_b32 v13, s74, 5
	v_writelane_b32 v14, s75, 5
	v_cmp_ge_u32_e64 s[74:75], v102, v12
	v_writelane_b32 v13, s84, 6
	v_writelane_b32 v14, s85, 6
	v_cmp_ge_u32_e64 s[84:85], v97, v12
	v_writelane_b32 v13, s76, 7
	v_writelane_b32 v14, s77, 7
	v_cmp_ge_u32_e64 s[76:77], v104, v12
	v_writelane_b32 v13, s74, 8
	v_writelane_b32 v14, s75, 8
	v_cmp_ge_u32_e64 s[74:75], v99, v12
	v_writelane_b32 v13, s84, 9
	v_writelane_b32 v14, s85, 9
	v_cmp_ge_u32_e64 s[84:85], v106, v12
	v_writelane_b32 v13, s76, 10
	v_writelane_b32 v14, s77, 10
	v_cmp_ge_u32_e64 s[76:77], v101, v12
	v_writelane_b32 v13, s74, 11
	v_writelane_b32 v14, s75, 11
	v_cmp_ge_u32_e64 s[74:75], v108, v12
	v_writelane_b32 v13, s84, 12
	v_writelane_b32 v14, s85, 12
	v_cmp_ge_u32_e64 s[84:85], v103, v12
	v_writelane_b32 v13, s76, 13
	v_writelane_b32 v14, s77, 13
	v_cmp_ge_u32_e64 s[76:77], v110, v12
	v_writelane_b32 v13, s74, 14
	v_writelane_b32 v14, s75, 14
	v_cmp_ge_u32_e64 s[74:75], v105, v12
	v_writelane_b32 v13, s84, 15
	v_writelane_b32 v14, s85, 15
	v_cmp_ge_u32_e64 s[84:85], v112, v12
	v_writelane_b32 v13, s76, 16
	v_writelane_b32 v14, s77, 16
	v_cmp_ge_u32_e64 s[76:77], v107, v12
	v_writelane_b32 v13, s74, 17
	v_writelane_b32 v14, s75, 17
	v_cmp_ge_u32_e64 s[74:75], v114, v12
	v_writelane_b32 v13, s84, 18
	v_writelane_b32 v14, s85, 18
	v_cmp_ge_u32_e64 s[84:85], v109, v12
	v_writelane_b32 v13, s76, 19
	v_writelane_b32 v14, s77, 19
	v_cmp_ge_u32_e64 s[76:77], v116, v12
	v_writelane_b32 v13, s74, 20
	v_writelane_b32 v14, s75, 20
	v_cmp_ge_u32_e64 s[74:75], v111, v12
	v_writelane_b32 v13, s84, 21
	v_writelane_b32 v14, s85, 21
	v_cmp_ge_u32_e64 s[84:85], v118, v12
	v_writelane_b32 v13, s76, 22
	v_writelane_b32 v14, s77, 22
	v_cmp_ge_u32_e64 s[76:77], v113, v12
	v_writelane_b32 v13, s74, 23
	v_writelane_b32 v14, s75, 23
	v_cmp_ge_u32_e64 s[74:75], v120, v12
	v_writelane_b32 v13, s84, 24
	v_writelane_b32 v14, s85, 24
	v_cmp_ge_u32_e64 s[84:85], v115, v12
	v_writelane_b32 v13, s76, 25
	v_writelane_b32 v14, s77, 25
	v_cmp_ge_u32_e64 s[76:77], v122, v12
	v_writelane_b32 v13, s74, 26
	v_writelane_b32 v14, s75, 26
	v_cmp_ge_u32_e64 s[74:75], v117, v12
	v_writelane_b32 v13, s84, 27
	v_writelane_b32 v14, s85, 27
	v_cmp_ge_u32_e64 s[84:85], v124, v12
	v_writelane_b32 v13, s76, 28
	v_writelane_b32 v14, s77, 28
	v_cmp_ge_u32_e64 s[76:77], v119, v12
	v_writelane_b32 v13, s74, 29
	v_writelane_b32 v14, s75, 29
	v_cmp_ge_u32_e64 s[74:75], v158, v12
	v_writelane_b32 v13, s84, 30
	v_writelane_b32 v14, s85, 30
	v_cmp_ge_u32_e64 s[84:85], v121, v12
	v_writelane_b32 v13, s76, 31
	v_writelane_b32 v14, s77, 31
	v_cmp_ge_u32_e64 s[76:77], v160, v12
	v_writelane_b32 v13, s74, 32
	v_writelane_b32 v14, s75, 32
	v_cmp_ge_u32_e64 s[74:75], v123, v12
	v_writelane_b32 v13, s84, 33
	v_writelane_b32 v14, s85, 33
	v_cmp_ge_u32_e64 s[84:85], v162, v12
	v_writelane_b32 v13, s76, 34
	v_writelane_b32 v14, s77, 34
	v_cmp_ge_u32_e64 s[76:77], v125, v12
	v_writelane_b32 v13, s74, 35
	v_writelane_b32 v14, s75, 35
	v_cmp_ge_u32_e64 s[74:75], v164, v12
	v_writelane_b32 v13, s84, 36
	v_writelane_b32 v14, s85, 36
	v_cmp_ge_u32_e64 s[84:85], v159, v12
	v_writelane_b32 v13, s76, 37
	v_writelane_b32 v14, s77, 37
	v_cmp_ge_u32_e64 s[76:77], v168, v12
	v_writelane_b32 v13, s74, 38
	v_writelane_b32 v14, s75, 38
	v_cmp_ge_u32_e64 s[74:75], v161, v12
	v_writelane_b32 v13, s84, 39
	v_writelane_b32 v14, s85, 39
	v_cmp_ge_u32_e64 s[84:85], v170, v12
	v_writelane_b32 v13, s76, 40
	v_writelane_b32 v14, s77, 40
	v_cmp_ge_u32_e64 s[76:77], v163, v12
	v_writelane_b32 v13, s74, 41
	v_writelane_b32 v14, s75, 41
	v_cmp_ge_u32_e64 s[74:75], v172, v12
	v_writelane_b32 v13, s84, 42
	v_writelane_b32 v14, s85, 42
	v_cmp_ge_u32_e64 s[84:85], v165, v12
	v_writelane_b32 v13, s76, 43
	v_writelane_b32 v14, s77, 43
	v_cmp_ge_u32_e64 s[76:77], v174, v12
	v_writelane_b32 v13, s74, 44
	v_writelane_b32 v14, s75, 44
	v_cmp_ge_u32_e64 s[74:75], v169, v12
	v_writelane_b32 v13, s84, 45
	v_writelane_b32 v14, s85, 45
	v_cmp_ge_u32_e64 s[84:85], v176, v12
	v_writelane_b32 v13, s76, 46
	v_writelane_b32 v14, s77, 46
	v_cmp_ge_u32_e64 s[76:77], v171, v12
	v_writelane_b32 v13, s74, 47
	v_writelane_b32 v14, s75, 47
	v_cmp_ge_u32_e64 s[74:75], v178, v12
	v_writelane_b32 v13, s84, 48
	v_writelane_b32 v14, s85, 48
	v_cmp_ge_u32_e64 s[84:85], v173, v12
	v_writelane_b32 v13, s76, 49
	v_writelane_b32 v14, s77, 49
	v_cmp_ge_u32_e64 s[76:77], v180, v12
	v_writelane_b32 v13, s74, 50
	v_writelane_b32 v14, s75, 50
	v_cmp_ge_u32_e64 s[74:75], v175, v12
	v_writelane_b32 v13, s84, 51
	v_writelane_b32 v14, s85, 51
	v_cmp_ge_u32_e64 s[84:85], v182, v12
	v_writelane_b32 v13, s76, 52
	v_writelane_b32 v14, s77, 52
	v_cmp_ge_u32_e64 s[76:77], v177, v12
	v_writelane_b32 v13, s74, 53
	v_writelane_b32 v14, s75, 53
	v_cmp_ge_u32_e64 s[74:75], v184, v12
	v_writelane_b32 v13, s84, 54
	v_writelane_b32 v14, s85, 54
	v_cmp_ge_u32_e64 s[84:85], v179, v12
	v_writelane_b32 v13, s76, 55
	v_writelane_b32 v14, s77, 55
	v_cmp_ge_u32_e64 s[76:77], v186, v12
	v_writelane_b32 v13, s74, 56
	v_writelane_b32 v14, s75, 56
	v_cmp_ge_u32_e64 s[74:75], v181, v12
	v_writelane_b32 v13, s84, 57
	v_writelane_b32 v14, s85, 57
	v_cmp_ge_u32_e64 s[84:85], v188, v12
	v_writelane_b32 v13, s76, 58
	v_writelane_b32 v14, s77, 58
	v_cmp_ge_u32_e64 s[76:77], v183, v12
	v_writelane_b32 v13, s74, 59
	v_writelane_b32 v14, s75, 59
	v_cmp_ge_u32_e64 s[74:75], v190, v12
	v_writelane_b32 v13, s84, 60
	v_writelane_b32 v14, s85, 60
	v_cmp_ge_u32_e64 s[84:85], v185, v12
	s_nop 1
	v_writelane_b32 v13, s76, 61
	v_writelane_b32 v14, s77, 61
	v_writelane_b32 v13, s74, 62
	v_writelane_b32 v14, s75, 62
	v_writelane_b32 v13, s84, 63
	v_writelane_b32 v14, s85, 63
	ds_write2st64_b32 v209, v13, v14 offset1:1
	s_mov_b64 s[2:3], 0
	s_branch .LBB0_3695
; __global__ void __launch_bounds__(512, 2) mega_fwd(KArgs a) {
;     ...
;                     const unsigned cand = tau | (1u << bit);
;                     int c0 = 0, c1 = 0;
; #pragma unroll
;                     for (int jj = 0; jj < 64; ++jj) { const unsigned long long bm = __ballot(key[jj] >= cand); c0 += __popc((unsigned)bm); c1 += __popc((unsigned)(bm >> 32)); }
;                     const int cnt = (lane < 32) ? c0 : c1;
;                     if (cnt >= 256) tau = cand;
;                     done_sel = done_sel || (cnt == 256);
;                     if (__ballot(!done_sel) == 0ull) break;
;                 }
.Lmy_sel_loop_7:
	v_lshl_or_b32 v12, 1, v11, v10
	v_mov_b32_e32 v13, 0
	v_cmp_ge_u32_e64 s[84:85], v3, v12
	v_cmp_ge_u32_e64 s[76:77], v2, v12
	v_cmp_ge_u32_e64 s[74:75], v5, v12
	v_addc_co_u32_e64 v13, vcc, 0, v13, s[84:85]
	v_cmp_ge_u32_e64 s[84:85], v4, v12
	v_addc_co_u32_e64 v13, vcc, 0, v13, s[76:77]
	v_cmp_ge_u32_e64 s[76:77], v7, v12
	v_addc_co_u32_e64 v13, vcc, 0, v13, s[74:75]
	v_cmp_ge_u32_e64 s[74:75], v6, v12
	v_addc_co_u32_e64 v13, vcc, 0, v13, s[84:85]
	v_cmp_ge_u32_e64 s[84:85], v9, v12
	v_addc_co_u32_e64 v13, vcc, 0, v13, s[76:77]
	v_cmp_ge_u32_e64 s[76:77], v8, v12
	v_addc_co_u32_e64 v13, vcc, 0, v13, s[74:75]
	v_cmp_ge_u32_e64 s[74:75], v102, v12
	v_addc_co_u32_e64 v13, vcc, 0, v13, s[84:85]
	v_cmp_ge_u32_e64 s[84:85], v97, v12
	v_addc_co_u32_e64 v13, vcc, 0, v13, s[76:77]
	v_cmp_ge_u32_e64 s[76:77], v104, v12
	v_addc_co_u32_e64 v13, vcc, 0, v13, s[74:75]
	v_cmp_ge_u32_e64 s[74:75], v99, v12
	v_addc_co_u32_e64 v13, vcc, 0, v13, s[84:85]
	v_cmp_ge_u32_e64 s[84:85], v106, v12
	v_addc_co_u32_e64 v13, vcc, 0, v13, s[76:77]
	v_cmp_ge_u32_e64 s[76:77], v101, v12
	v_addc_co_u32_e64 v13, vcc, 0, v13, s[74:75]
	v_cmp_ge_u32_e64 s[74:75], v108, v12
	v_addc_co_u32_e64 v13, vcc, 0, v13, s[84:85]
	v_cmp_ge_u32_e64 s[84:85], v103, v12
	v_addc_co_u32_e64 v13, vcc, 0, v13, s[76:77]
	v_cmp_ge_u32_e64 s[76:77], v110, v12
	v_addc_co_u32_e64 v13, vcc, 0, v13, s[74:75]
	v_cmp_ge_u32_e64 s[74:75], v105, v12
	v_addc_co_u32_e64 v13, vcc, 0, v13, s[84:85]
	v_cmp_ge_u32_e64 s[84:85], v112, v12
	v_addc_co_u32_e64 v13, vcc, 0, v13, s[76:77]
	v_cmp_ge_u32_e64 s[76:77], v107, v12
	v_addc_co_u32_e64 v13, vcc, 0, v13, s[74:75]
	v_cmp_ge_u32_e64 s[74:75], v114, v12
	v_addc_co_u32_e64 v13, vcc, 0, v13, s[84:85]
	v_cmp_ge_u32_e64 s[84:85], v109, v12
	v_addc_co_u32_e64 v13, vcc, 0, v13, s[76:77]
	v_cmp_ge_u32_e64 s[76:77], v116, v12
	v_addc_co_u32_e64 v13, vcc, 0, v13, s[74:75]
	v_cmp_ge_u32_e64 s[74:75], v111, v12
	v_addc_co_u32_e64 v13, vcc, 0, v13, s[84:85]
	v_cmp_ge_u32_e64 s[84:85], v118, v12
	v_addc_co_u32_e64 v13, vcc, 0, v13, s[76:77]
	v_cmp_ge_u32_e64 s[76:77], v113, v12
	v_addc_co_u32_e64 v13, vcc, 0, v13, s[74:75]
	v_cmp_ge_u32_e64 s[74:75], v120, v12
	v_addc_co_u32_e64 v13, vcc, 0, v13, s[84:85]
	v_cmp_ge_u32_e64 s[84:85], v115, v12
	v_addc_co_u32_e64 v13, vcc, 0, v13, s[76:77]
	v_cmp_ge_u32_e64 s[76:77], v122, v12
	v_addc_co_u32_e64 v13, vcc, 0, v13, s[74:75]
	v_cmp_ge_u32_e64 s[74:75], v117, v12
	v_addc_co_u32_e64 v13, vcc, 0, v13, s[84:85]
	v_cmp_ge_u32_e64 s[84:85], v124, v12
	v_addc_co_u32_e64 v13, vcc, 0, v13, s[76:77]
	v_cmp_ge_u32_e64 s[76:77], v119, v12
	v_addc_co_u32_e64 v13, vcc, 0, v13, s[74:75]
	v_cmp_ge_u32_e64 s[74:75], v158, v12
	v_addc_co_u32_e64 v13, vcc, 0, v13, s[84:85]
	v_cmp_ge_u32_e64 s[84:85], v121, v12
	v_addc_co_u32_e64 v13, vcc, 0, v13, s[76:77]
	v_cmp_ge_u32_e64 s[76:77], v160, v12
	v_addc_co_u32_e64 v13, vcc, 0, v13, s[74:75]
	v_cmp_ge_u32_e64 s[74:75], v123, v12
	v_addc_co_u32_e64 v13, vcc, 0, v13, s[84:85]
	v_cmp_ge_u32_e64 s[84:85], v162, v12
	v_addc_co_u32_e64 v13, vcc, 0, v13, s[76:77]
	v_cmp_ge_u32_e64 s[76:77], v125, v12
	v_addc_co_u32_e64 v13, vcc, 0, v13, s[74:75]
	v_cmp_ge_u32_e64 s[74:75], v164, v12
	v_addc_co_u32_e64 v13, vcc, 0, v13, s[84:85]
	v_cmp_ge_u32_e64 s[84:85], v159, v12
	v_addc_co_u32_e64 v13, vcc, 0, v13, s[76:77]
	v_cmp_ge_u32_e64 s[76:77], v168, v12
	v_addc_co_u32_e64 v13, vcc, 0, v13, s[74:75]
	v_cmp_ge_u32_e64 s[74:75], v161, v12
	v_addc_co_u32_e64 v13, vcc, 0, v13, s[84:85]
	v_cmp_ge_u32_e64 s[84:85], v170, v12
	v_addc_co_u32_e64 v13, vcc, 0, v13, s[76:77]
	v_cmp_ge_u32_e64 s[76:77], v163, v12
	v_addc_co_u32_e64 v13, vcc, 0, v13, s[74:75]
	v_cmp_ge_u32_e64 s[74:75], v172, v12
	v_addc_co_u32_e64 v13, vcc, 0, v13, s[84:85]
	v_cmp_ge_u32_e64 s[84:85], v165, v12
	v_addc_co_u32_e64 v13, vcc, 0, v13, s[76:77]
	v_cmp_ge_u32_e64 s[76:77], v174, v12
	v_addc_co_u32_e64 v13, vcc, 0, v13, s[74:75]
	v_cmp_ge_u32_e64 s[74:75], v169, v12
	v_addc_co_u32_e64 v13, vcc, 0, v13, s[84:85]
	v_cmp_ge_u32_e64 s[84:85], v176, v12
	v_addc_co_u32_e64 v13, vcc, 0, v13, s[76:77]
	v_cmp_ge_u32_e64 s[76:77], v171, v12
	v_addc_co_u32_e64 v13, vcc, 0, v13, s[74:75]
	v_cmp_ge_u32_e64 s[74:75], v178, v12
	v_addc_co_u32_e64 v13, vcc, 0, v13, s[84:85]
	v_cmp_ge_u32_e64 s[84:85], v173, v12
	v_addc_co_u32_e64 v13, vcc, 0, v13, s[76:77]
	v_cmp_ge_u32_e64 s[76:77], v180, v12
	v_addc_co_u32_e64 v13, vcc, 0, v13, s[74:75]
	v_cmp_ge_u32_e64 s[74:75], v175, v12
	v_addc_co_u32_e64 v13, vcc, 0, v13, s[84:85]
	v_cmp_ge_u32_e64 s[84:85], v182, v12
	v_addc_co_u32_e64 v13, vcc, 0, v13, s[76:77]
	v_cmp_ge_u32_e64 s[76:77], v177, v12
	s_nop 1
	v_addc_co_u32_e64 v13, vcc, 0, v13, s[74:75]
	v_addc_co_u32_e64 v13, vcc, 0, v13, s[84:85]
	v_addc_co_u32_e64 v13, vcc, 0, v13, s[76:77]
	s_nop 1
	v_add_u32_dpp v13, v13, v13 quad_perm:[1,0,3,2] row_mask:0xf bank_mask:0xf
	s_nop 1
	v_add_u32_dpp v13, v13, v13 quad_perm:[2,3,0,1] row_mask:0xf bank_mask:0xf
	s_nop 1
	v_add_u32_dpp v13, v13, v13 row_half_mirror row_mask:0xf bank_mask:0xf
	s_nop 1
	v_add_u32_dpp v13, v13, v13 row_mirror row_mask:0xf bank_mask:0xf
	v_mov_b32_e32 v14, v13
	s_nop 1
	v_permlane16_swap_b32 v14, v13
	v_add_u32_e32 v13, v13, v14
	s_movk_i32 s2, 0xff
	v_cmp_lt_i32_e32 vcc, s2, v13
	s_nop 1
	v_cndmask_b32_e32 v10, v10, v12, vcc
	v_cmp_eq_u32_e32 vcc, s5, v13
	s_or_b64 s[0:1], s[0:1], vcc
	s_xor_b64 s[2:3], s[0:1], -1
	v_cndmask_b32_e64 v12, 0, 1, s[2:3]
	v_cmp_ne_u32_e32 vcc, 0, v12
	s_cmp_lg_u64 vcc, 0
	s_cselect_b64 s[2:3], -1, 0
	v_add_co_u32_e32 v11, vcc, -1, v11
	s_and_b64 s[2:3], s[2:3], vcc
	s_and_b64 vcc, exec, s[2:3]
	s_cbranch_vccnz .Lmy_sel_loop_7
	s_andn2_b64 s[2:3], exec, s[0:1]
	s_cbranch_scc0 .Lmy_sel_fast_7
	s_branch .Lmy_sel_slow
; __global__ void __launch_bounds__(512, 2) mega_fwd(KArgs a) {
;     ...
;                 if (all_valid) tau = 1u;
;                 int g0 = 0, g1 = 0, e0 = 0, e1 = 0;
; #pragma unroll
;                 for (int jj = 0; jj < 64; ++jj) {
;                     const unsigned long long bg = __ballot(key[jj] > tau), be = __ballot(key[jj] == tau);
;                     g0 += __popc((unsigned)bg); g1 += __popc((unsigned)(bg >> 32)); e0 += __popc((unsigned)be); e1 += __popc((unsigned)(be >> 32));
;                 }
;                 const int cgt = (lane < 32) ? g0 : g1, ceq = (lane < 32) ? e0 : e1;
;                 const int need_eq = all_valid ? (1 << 20) : 256 - cgt;
;                 const bool ties = (!all_valid) && (ceq > need_eq);
;                 unsigned w0 = 0u, w1 = 0u;
;                 if (__ballot(ties) == 0ull) {
; #pragma unroll
;                     for (int jj = 0; jj < 64; ++jj) {
;                         const unsigned long long bm = __ballot(key[jj] >= tau);
;                         if (lane == 0) { wscr[jj] = (unsigned)bm; wscr[64 + jj] = (unsigned)(bm >> 32); }
;                     }
.Lmy_sel_fast_7:
	v_cndmask_b32_e64 v12, v10, 1, s[86:87]
	v_mov_b32_e32 v13, 0
	v_mov_b32_e32 v14, 0
	v_cmp_ge_u32_e64 s[84:85], v3, v12
	v_cmp_ge_u32_e64 s[76:77], v2, v12
	v_cmp_ge_u32_e64 s[74:75], v5, v12
	v_writelane_b32 v13, s84, 0
	v_writelane_b32 v14, s85, 0
	v_cmp_ge_u32_e64 s[84:85], v4, v12
	v_writelane_b32 v13, s76, 1
	v_writelane_b32 v14, s77, 1
	v_cmp_ge_u32_e64 s[76:77], v7, v12
	v_writelane_b32 v13, s74, 2
	v_writelane_b32 v14, s75, 2
	v_cmp_ge_u32_e64 s[74:75], v6, v12
	v_writelane_b32 v13, s84, 3
	v_writelane_b32 v14, s85, 3
	v_cmp_ge_u32_e64 s[84:85], v9, v12
	v_writelane_b32 v13, s76, 4
	v_writelane_b32 v14, s77, 4
	v_cmp_ge_u32_e64 s[76:77], v8, v12
	v_writelane_b32 v13, s74, 5
	v_writelane_b32 v14, s75, 5
	v_cmp_ge_u32_e64 s[74:75], v102, v12
	v_writelane_b32 v13, s84, 6
	v_writelane_b32 v14, s85, 6
	v_cmp_ge_u32_e64 s[84:85], v97, v12
	v_writelane_b32 v13, s76, 7
	v_writelane_b32 v14, s77, 7
	v_cmp_ge_u32_e64 s[76:77], v104, v12
	v_writelane_b32 v13, s74, 8
	v_writelane_b32 v14, s75, 8
	v_cmp_ge_u32_e64 s[74:75], v99, v12
	v_writelane_b32 v13, s84, 9
	v_writelane_b32 v14, s85, 9
	v_cmp_ge_u32_e64 s[84:85], v106, v12
	v_writelane_b32 v13, s76, 10
	v_writelane_b32 v14, s77, 10
	v_cmp_ge_u32_e64 s[76:77], v101, v12
	v_writelane_b32 v13, s74, 11
	v_writelane_b32 v14, s75, 11
	v_cmp_ge_u32_e64 s[74:75], v108, v12
	v_writelane_b32 v13, s84, 12
	v_writelane_b32 v14, s85, 12
	v_cmp_ge_u32_e64 s[84:85], v103, v12
	v_writelane_b32 v13, s76, 13
	v_writelane_b32 v14, s77, 13
	v_cmp_ge_u32_e64 s[76:77], v110, v12
	v_writelane_b32 v13, s74, 14
	v_writelane_b32 v14, s75, 14
	v_cmp_ge_u32_e64 s[74:75], v105, v12
	v_writelane_b32 v13, s84, 15
	v_writelane_b32 v14, s85, 15
	v_cmp_ge_u32_e64 s[84:85], v112, v12
	v_writelane_b32 v13, s76, 16
	v_writelane_b32 v14, s77, 16
	v_cmp_ge_u32_e64 s[76:77], v107, v12
	v_writelane_b32 v13, s74, 17
	v_writelane_b32 v14, s75, 17
	v_cmp_ge_u32_e64 s[74:75], v114, v12
	v_writelane_b32 v13, s84, 18
	v_writelane_b32 v14, s85, 18
	v_cmp_ge_u32_e64 s[84:85], v109, v12
	v_writelane_b32 v13, s76, 19
	v_writelane_b32 v14, s77, 19
	v_cmp_ge_u32_e64 s[76:77], v116, v12
	v_writelane_b32 v13, s74, 20
	v_writelane_b32 v14, s75, 20
	v_cmp_ge_u32_e64 s[74:75], v111, v12
	v_writelane_b32 v13, s84, 21
	v_writelane_b32 v14, s85, 21
	v_cmp_ge_u32_e64 s[84:85], v118, v12
	v_writelane_b32 v13, s76, 22
	v_writelane_b32 v14, s77, 22
	v_cmp_ge_u32_e64 s[76:77], v113, v12
	v_writelane_b32 v13, s74, 23
	v_writelane_b32 v14, s75, 23
	v_cmp_ge_u32_e64 s[74:75], v120, v12
	v_writelane_b32 v13, s84, 24
	v_writelane_b32 v14, s85, 24
	v_cmp_ge_u32_e64 s[84:85], v115, v12
	v_writelane_b32 v13, s76, 25
	v_writelane_b32 v14, s77, 25
	v_cmp_ge_u32_e64 s[76:77], v122, v12
	v_writelane_b32 v13, s74, 26
	v_writelane_b32 v14, s75, 26
	v_cmp_ge_u32_e64 s[74:75], v117, v12
	v_writelane_b32 v13, s84, 27
	v_writelane_b32 v14, s85, 27
	v_cmp_ge_u32_e64 s[84:85], v124, v12
	v_writelane_b32 v13, s76, 28
	v_writelane_b32 v14, s77, 28
	v_cmp_ge_u32_e64 s[76:77], v119, v12
	v_writelane_b32 v13, s74, 29
	v_writelane_b32 v14, s75, 29
	v_cmp_ge_u32_e64 s[74:75], v158, v12
	v_writelane_b32 v13, s84, 30
	v_writelane_b32 v14, s85, 30
	v_cmp_ge_u32_e64 s[84:85], v121, v12
	v_writelane_b32 v13, s76, 31
	v_writelane_b32 v14, s77, 31
	v_cmp_ge_u32_e64 s[76:77], v160, v12
	v_writelane_b32 v13, s74, 32
	v_writelane_b32 v14, s75, 32
	v_cmp_ge_u32_e64 s[74:75], v123, v12
	v_writelane_b32 v13, s84, 33
	v_writelane_b32 v14, s85, 33
	v_cmp_ge_u32_e64 s[84:85], v162, v12
	v_writelane_b32 v13, s76, 34
	v_writelane_b32 v14, s77, 34
	v_cmp_ge_u32_e64 s[76:77], v125, v12
	v_writelane_b32 v13, s74, 35
	v_writelane_b32 v14, s75, 35
	v_cmp_ge_u32_e64 s[74:75], v164, v12
	v_writelane_b32 v13, s84, 36
	v_writelane_b32 v14, s85, 36
	v_cmp_ge_u32_e64 s[84:85], v159, v12
	v_writelane_b32 v13, s76, 37
	v_writelane_b32 v14, s77, 37
	v_cmp_ge_u32_e64 s[76:77], v168, v12
	v_writelane_b32 v13, s74, 38
	v_writelane_b32 v14, s75, 38
	v_cmp_ge_u32_e64 s[74:75], v161, v12
	v_writelane_b32 v13, s84, 39
	v_writelane_b32 v14, s85, 39
	v_cmp_ge_u32_e64 s[84:85], v170, v12
	v_writelane_b32 v13, s76, 40
	v_writelane_b32 v14, s77, 40
	v_cmp_ge_u32_e64 s[76:77], v163, v12
	v_writelane_b32 v13, s74, 41
	v_writelane_b32 v14, s75, 41
	v_cmp_ge_u32_e64 s[74:75], v172, v12
	v_writelane_b32 v13, s84, 42
	v_writelane_b32 v14, s85, 42
	v_cmp_ge_u32_e64 s[84:85], v165, v12
	v_writelane_b32 v13, s76, 43
	v_writelane_b32 v14, s77, 43
	v_cmp_ge_u32_e64 s[76:77], v174, v12
	v_writelane_b32 v13, s74, 44
	v_writelane_b32 v14, s75, 44
	v_cmp_ge_u32_e64 s[74:75], v169, v12
	v_writelane_b32 v13, s84, 45
	v_writelane_b32 v14, s85, 45
	v_cmp_ge_u32_e64 s[84:85], v176, v12
	v_writelane_b32 v13, s76, 46
	v_writelane_b32 v14, s77, 46
	v_cmp_ge_u32_e64 s[76:77], v171, v12
	v_writelane_b32 v13, s74, 47
	v_writelane_b32 v14, s75, 47
	v_cmp_ge_u32_e64 s[74:75], v178, v12
	v_writelane_b32 v13, s84, 48
	v_writelane_b32 v14, s85, 48
	v_cmp_ge_u32_e64 s[84:85], v173, v12
	v_writelane_b32 v13, s76, 49
	v_writelane_b32 v14, s77, 49
	v_cmp_ge_u32_e64 s[76:77], v180, v12
	v_writelane_b32 v13, s74, 50
	v_writelane_b32 v14, s75, 50
	v_cmp_ge_u32_e64 s[74:75], v175, v12
	v_writelane_b32 v13, s84, 51
	v_writelane_b32 v14, s85, 51
	v_cmp_ge_u32_e64 s[84:85], v182, v12
	v_writelane_b32 v13, s76, 52
	v_writelane_b32 v14, s77, 52
	v_cmp_ge_u32_e64 s[76:77], v177, v12
	s_nop 1
	v_writelane_b32 v13, s74, 53
	v_writelane_b32 v14, s75, 53
	v_writelane_b32 v13, s84, 54
	v_writelane_b32 v14, s85, 54
	v_writelane_b32 v13, s76, 55
	v_writelane_b32 v14, s77, 55
	ds_write2st64_b32 v209, v13, v14 offset1:1
	s_mov_b64 s[2:3], 0
	s_branch .LBB0_3695
; __global__ void __launch_bounds__(512, 2) mega_fwd(KArgs a) {
;     ...
;                     const unsigned cand = tau | (1u << bit);
;                     int c0 = 0, c1 = 0;
; #pragma unroll
;                     for (int jj = 0; jj < 64; ++jj) { const unsigned long long bm = __ballot(key[jj] >= cand); c0 += __popc((unsigned)bm); c1 += __popc((unsigned)(bm >> 32)); }
;                     const int cnt = (lane < 32) ? c0 : c1;
;                     if (cnt >= 256) tau = cand;
;                     done_sel = done_sel || (cnt == 256);
;                     if (__ballot(!done_sel) == 0ull) break;
;                 }
.Lmy_sel_loop_6:
	v_lshl_or_b32 v12, 1, v11, v10
	v_mov_b32_e32 v13, 0
	v_cmp_ge_u32_e64 s[84:85], v3, v12
	v_cmp_ge_u32_e64 s[76:77], v2, v12
	v_cmp_ge_u32_e64 s[74:75], v5, v12
	v_addc_co_u32_e64 v13, vcc, 0, v13, s[84:85]
	v_cmp_ge_u32_e64 s[84:85], v4, v12
	v_addc_co_u32_e64 v13, vcc, 0, v13, s[76:77]
	v_cmp_ge_u32_e64 s[76:77], v7, v12
	v_addc_co_u32_e64 v13, vcc, 0, v13, s[74:75]
	v_cmp_ge_u32_e64 s[74:75], v6, v12
	v_addc_co_u32_e64 v13, vcc, 0, v13, s[84:85]
	v_cmp_ge_u32_e64 s[84:85], v9, v12
	v_addc_co_u32_e64 v13, vcc, 0, v13, s[76:77]
	v_cmp_ge_u32_e64 s[76:77], v8, v12
	v_addc_co_u32_e64 v13, vcc, 0, v13, s[74:75]
	v_cmp_ge_u32_e64 s[74:75], v102, v12
	v_addc_co_u32_e64 v13, vcc, 0, v13, s[84:85]
	v_cmp_ge_u32_e64 s[84:85], v97, v12
	v_addc_co_u32_e64 v13, vcc, 0, v13, s[76:77]
	v_cmp_ge_u32_e64 s[76:77], v104, v12
	v_addc_co_u32_e64 v13, vcc, 0, v13, s[74:75]
	v_cmp_ge_u32_e64 s[74:75], v99, v12
	v_addc_co_u32_e64 v13, vcc, 0, v13, s[84:85]
	v_cmp_ge_u32_e64 s[84:85], v106, v12
	v_addc_co_u32_e64 v13, vcc, 0, v13, s[76:77]
	v_cmp_ge_u32_e64 s[76:77], v101, v12
	v_addc_co_u32_e64 v13, vcc, 0, v13, s[74:75]
	v_cmp_ge_u32_e64 s[74:75], v108, v12
	v_addc_co_u32_e64 v13, vcc, 0, v13, s[84:85]
	v_cmp_ge_u32_e64 s[84:85], v103, v12
	v_addc_co_u32_e64 v13, vcc, 0, v13, s[76:77]
	v_cmp_ge_u32_e64 s[76:77], v110, v12
	v_addc_co_u32_e64 v13, vcc, 0, v13, s[74:75]
	v_cmp_ge_u32_e64 s[74:75], v105, v12
	v_addc_co_u32_e64 v13, vcc, 0, v13, s[84:85]
	v_cmp_ge_u32_e64 s[84:85], v112, v12
	v_addc_co_u32_e64 v13, vcc, 0, v13, s[76:77]
	v_cmp_ge_u32_e64 s[76:77], v107, v12
	v_addc_co_u32_e64 v13, vcc, 0, v13, s[74:75]
	v_cmp_ge_u32_e64 s[74:75], v114, v12
	v_addc_co_u32_e64 v13, vcc, 0, v13, s[84:85]
	v_cmp_ge_u32_e64 s[84:85], v109, v12
	v_addc_co_u32_e64 v13, vcc, 0, v13, s[76:77]
	v_cmp_ge_u32_e64 s[76:77], v116, v12
	v_addc_co_u32_e64 v13, vcc, 0, v13, s[74:75]
	v_cmp_ge_u32_e64 s[74:75], v111, v12
	v_addc_co_u32_e64 v13, vcc, 0, v13, s[84:85]
	v_cmp_ge_u32_e64 s[84:85], v118, v12
	v_addc_co_u32_e64 v13, vcc, 0, v13, s[76:77]
	v_cmp_ge_u32_e64 s[76:77], v113, v12
	v_addc_co_u32_e64 v13, vcc, 0, v13, s[74:75]
	v_cmp_ge_u32_e64 s[74:75], v120, v12
	v_addc_co_u32_e64 v13, vcc, 0, v13, s[84:85]
	v_cmp_ge_u32_e64 s[84:85], v115, v12
	v_addc_co_u32_e64 v13, vcc, 0, v13, s[76:77]
	v_cmp_ge_u32_e64 s[76:77], v122, v12
	v_addc_co_u32_e64 v13, vcc, 0, v13, s[74:75]
	v_cmp_ge_u32_e64 s[74:75], v117, v12
	v_addc_co_u32_e64 v13, vcc, 0, v13, s[84:85]
	v_cmp_ge_u32_e64 s[84:85], v124, v12
	v_addc_co_u32_e64 v13, vcc, 0, v13, s[76:77]
	v_cmp_ge_u32_e64 s[76:77], v119, v12
	v_addc_co_u32_e64 v13, vcc, 0, v13, s[74:75]
	v_cmp_ge_u32_e64 s[74:75], v158, v12
	v_addc_co_u32_e64 v13, vcc, 0, v13, s[84:85]
	v_cmp_ge_u32_e64 s[84:85], v121, v12
	v_addc_co_u32_e64 v13, vcc, 0, v13, s[76:77]
	v_cmp_ge_u32_e64 s[76:77], v160, v12
	v_addc_co_u32_e64 v13, vcc, 0, v13, s[74:75]
	v_cmp_ge_u32_e64 s[74:75], v123, v12
	v_addc_co_u32_e64 v13, vcc, 0, v13, s[84:85]
	v_cmp_ge_u32_e64 s[84:85], v162, v12
	v_addc_co_u32_e64 v13, vcc, 0, v13, s[76:77]
	v_cmp_ge_u32_e64 s[76:77], v125, v12
	v_addc_co_u32_e64 v13, vcc, 0, v13, s[74:75]
	v_cmp_ge_u32_e64 s[74:75], v164, v12
	v_addc_co_u32_e64 v13, vcc, 0, v13, s[84:85]
	v_cmp_ge_u32_e64 s[84:85], v159, v12
	v_addc_co_u32_e64 v13, vcc, 0, v13, s[76:77]
	v_cmp_ge_u32_e64 s[76:77], v168, v12
	v_addc_co_u32_e64 v13, vcc, 0, v13, s[74:75]
	v_cmp_ge_u32_e64 s[74:75], v161, v12
	v_addc_co_u32_e64 v13, vcc, 0, v13, s[84:85]
	v_cmp_ge_u32_e64 s[84:85], v170, v12
	v_addc_co_u32_e64 v13, vcc, 0, v13, s[76:77]
	v_cmp_ge_u32_e64 s[76:77], v163, v12
	v_addc_co_u32_e64 v13, vcc, 0, v13, s[74:75]
	v_cmp_ge_u32_e64 s[74:75], v172, v12
	v_addc_co_u32_e64 v13, vcc, 0, v13, s[84:85]
	v_cmp_ge_u32_e64 s[84:85], v165, v12
	v_addc_co_u32_e64 v13, vcc, 0, v13, s[76:77]
	v_cmp_ge_u32_e64 s[76:77], v174, v12
	v_addc_co_u32_e64 v13, vcc, 0, v13, s[74:75]
	v_cmp_ge_u32_e64 s[74:75], v169, v12
	s_nop 1
	v_addc_co_u32_e64 v13, vcc, 0, v13, s[84:85]
	v_addc_co_u32_e64 v13, vcc, 0, v13, s[76:77]
	v_addc_co_u32_e64 v13, vcc, 0, v13, s[74:75]
	s_nop 1
	v_add_u32_dpp v13, v13, v13 quad_perm:[1,0,3,2] row_mask:0xf bank_mask:0xf
	s_nop 1
	v_add_u32_dpp v13, v13, v13 quad_perm:[2,3,0,1] row_mask:0xf bank_mask:0xf
	s_nop 1
	v_add_u32_dpp v13, v13, v13 row_half_mirror row_mask:0xf bank_mask:0xf
	s_nop 1
	v_add_u32_dpp v13, v13, v13 row_mirror row_mask:0xf bank_mask:0xf
	v_mov_b32_e32 v14, v13
	s_nop 1
	v_permlane16_swap_b32 v14, v13
	v_add_u32_e32 v13, v13, v14
	s_movk_i32 s2, 0xff
	v_cmp_lt_i32_e32 vcc, s2, v13
	s_nop 1
	v_cndmask_b32_e32 v10, v10, v12, vcc
	v_cmp_eq_u32_e32 vcc, s5, v13
	s_or_b64 s[0:1], s[0:1], vcc
	s_xor_b64 s[2:3], s[0:1], -1
	v_cndmask_b32_e64 v12, 0, 1, s[2:3]
	v_cmp_ne_u32_e32 vcc, 0, v12
	s_cmp_lg_u64 vcc, 0
	s_cselect_b64 s[2:3], -1, 0
	v_add_co_u32_e32 v11, vcc, -1, v11
	s_and_b64 s[2:3], s[2:3], vcc
	s_and_b64 vcc, exec, s[2:3]
	s_cbranch_vccnz .Lmy_sel_loop_6
	s_andn2_b64 s[2:3], exec, s[0:1]
	s_cbranch_scc0 .Lmy_sel_fast_6
	s_branch .Lmy_sel_slow
; __global__ void __launch_bounds__(512, 2) mega_fwd(KArgs a) {
;     ...
;                 if (all_valid) tau = 1u;
;                 int g0 = 0, g1 = 0, e0 = 0, e1 = 0;
; #pragma unroll
;                 for (int jj = 0; jj < 64; ++jj) {
;                     const unsigned long long bg = __ballot(key[jj] > tau), be = __ballot(key[jj] == tau);
;                     g0 += __popc((unsigned)bg); g1 += __popc((unsigned)(bg >> 32)); e0 += __popc((unsigned)be); e1 += __popc((unsigned)(be >> 32));
;                 }
;                 const int cgt = (lane < 32) ? g0 : g1, ceq = (lane < 32) ? e0 : e1;
;                 const int need_eq = all_valid ? (1 << 20) : 256 - cgt;
;                 const bool ties = (!all_valid) && (ceq > need_eq);
;                 unsigned w0 = 0u, w1 = 0u;
;                 if (__ballot(ties) == 0ull) {
; #pragma unroll
;                     for (int jj = 0; jj < 64; ++jj) {
;                         const unsigned long long bm = __ballot(key[jj] >= tau);
;                         if (lane == 0) { wscr[jj] = (unsigned)bm; wscr[64 + jj] = (unsigned)(bm >> 32); }
;                     }
.Lmy_sel_fast_6:
	v_cndmask_b32_e64 v12, v10, 1, s[86:87]
	v_mov_b32_e32 v13, 0
	v_mov_b32_e32 v14, 0
	v_cmp_ge_u32_e64 s[84:85], v3, v12
	v_cmp_ge_u32_e64 s[76:77], v2, v12
	v_cmp_ge_u32_e64 s[74:75], v5, v12
	v_writelane_b32 v13, s84, 0
	v_writelane_b32 v14, s85, 0
	v_cmp_ge_u32_e64 s[84:85], v4, v12
	v_writelane_b32 v13, s76, 1
	v_writelane_b32 v14, s77, 1
	v_cmp_ge_u32_e64 s[76:77], v7, v12
	v_writelane_b32 v13, s74, 2
	v_writelane_b32 v14, s75, 2
	v_cmp_ge_u32_e64 s[74:75], v6, v12
	v_writelane_b32 v13, s84, 3
	v_writelane_b32 v14, s85, 3
	v_cmp_ge_u32_e64 s[84:85], v9, v12
	v_writelane_b32 v13, s76, 4
	v_writelane_b32 v14, s77, 4
	v_cmp_ge_u32_e64 s[76:77], v8, v12
	v_writelane_b32 v13, s74, 5
	v_writelane_b32 v14, s75, 5
	v_cmp_ge_u32_e64 s[74:75], v102, v12
	v_writelane_b32 v13, s84, 6
	v_writelane_b32 v14, s85, 6
	v_cmp_ge_u32_e64 s[84:85], v97, v12
	v_writelane_b32 v13, s76, 7
	v_writelane_b32 v14, s77, 7
	v_cmp_ge_u32_e64 s[76:77], v104, v12
	v_writelane_b32 v13, s74, 8
	v_writelane_b32 v14, s75, 8
	v_cmp_ge_u32_e64 s[74:75], v99, v12
	v_writelane_b32 v13, s84, 9
	v_writelane_b32 v14, s85, 9
	v_cmp_ge_u32_e64 s[84:85], v106, v12
	v_writelane_b32 v13, s76, 10
	v_writelane_b32 v14, s77, 10
	v_cmp_ge_u32_e64 s[76:77], v101, v12
	v_writelane_b32 v13, s74, 11
	v_writelane_b32 v14, s75, 11
	v_cmp_ge_u32_e64 s[74:75], v108, v12
	v_writelane_b32 v13, s84, 12
	v_writelane_b32 v14, s85, 12
	v_cmp_ge_u32_e64 s[84:85], v103, v12
	v_writelane_b32 v13, s76, 13
	v_writelane_b32 v14, s77, 13
	v_cmp_ge_u32_e64 s[76:77], v110, v12
	v_writelane_b32 v13, s74, 14
	v_writelane_b32 v14, s75, 14
	v_cmp_ge_u32_e64 s[74:75], v105, v12
	v_writelane_b32 v13, s84, 15
	v_writelane_b32 v14, s85, 15
	v_cmp_ge_u32_e64 s[84:85], v112, v12
	v_writelane_b32 v13, s76, 16
	v_writelane_b32 v14, s77, 16
	v_cmp_ge_u32_e64 s[76:77], v107, v12
	v_writelane_b32 v13, s74, 17
	v_writelane_b32 v14, s75, 17
	v_cmp_ge_u32_e64 s[74:75], v114, v12
	v_writelane_b32 v13, s84, 18
	v_writelane_b32 v14, s85, 18
	v_cmp_ge_u32_e64 s[84:85], v109, v12
	v_writelane_b32 v13, s76, 19
	v_writelane_b32 v14, s77, 19
	v_cmp_ge_u32_e64 s[76:77], v116, v12
	v_writelane_b32 v13, s74, 20
	v_writelane_b32 v14, s75, 20
	v_cmp_ge_u32_e64 s[74:75], v111, v12
	v_writelane_b32 v13, s84, 21
	v_writelane_b32 v14, s85, 21
	v_cmp_ge_u32_e64 s[84:85], v118, v12
	v_writelane_b32 v13, s76, 22
	v_writelane_b32 v14, s77, 22
	v_cmp_ge_u32_e64 s[76:77], v113, v12
	v_writelane_b32 v13, s74, 23
	v_writelane_b32 v14, s75, 23
	v_cmp_ge_u32_e64 s[74:75], v120, v12
	v_writelane_b32 v13, s84, 24
	v_writelane_b32 v14, s85, 24
	v_cmp_ge_u32_e64 s[84:85], v115, v12
	v_writelane_b32 v13, s76, 25
	v_writelane_b32 v14, s77, 25
	v_cmp_ge_u32_e64 s[76:77], v122, v12
	v_writelane_b32 v13, s74, 26
	v_writelane_b32 v14, s75, 26
	v_cmp_ge_u32_e64 s[74:75], v117, v12
	v_writelane_b32 v13, s84, 27
	v_writelane_b32 v14, s85, 27
	v_cmp_ge_u32_e64 s[84:85], v124, v12
	v_writelane_b32 v13, s76, 28
	v_writelane_b32 v14, s77, 28
	v_cmp_ge_u32_e64 s[76:77], v119, v12
	v_writelane_b32 v13, s74, 29
	v_writelane_b32 v14, s75, 29
	v_cmp_ge_u32_e64 s[74:75], v158, v12
	v_writelane_b32 v13, s84, 30
	v_writelane_b32 v14, s85, 30
	v_cmp_ge_u32_e64 s[84:85], v121, v12
	v_writelane_b32 v13, s76, 31
	v_writelane_b32 v14, s77, 31
	v_cmp_ge_u32_e64 s[76:77], v160, v12
	v_writelane_b32 v13, s74, 32
	v_writelane_b32 v14, s75, 32
	v_cmp_ge_u32_e64 s[74:75], v123, v12
	v_writelane_b32 v13, s84, 33
	v_writelane_b32 v14, s85, 33
	v_cmp_ge_u32_e64 s[84:85], v162, v12
	v_writelane_b32 v13, s76, 34
	v_writelane_b32 v14, s77, 34
	v_cmp_ge_u32_e64 s[76:77], v125, v12
	v_writelane_b32 v13, s74, 35
	v_writelane_b32 v14, s75, 35
	v_cmp_ge_u32_e64 s[74:75], v164, v12
	v_writelane_b32 v13, s84, 36
	v_writelane_b32 v14, s85, 36
	v_cmp_ge_u32_e64 s[84:85], v159, v12
	v_writelane_b32 v13, s76, 37
	v_writelane_b32 v14, s77, 37
	v_cmp_ge_u32_e64 s[76:77], v168, v12
	v_writelane_b32 v13, s74, 38
	v_writelane_b32 v14, s75, 38
	v_cmp_ge_u32_e64 s[74:75], v161, v12
	v_writelane_b32 v13, s84, 39
	v_writelane_b32 v14, s85, 39
	v_cmp_ge_u32_e64 s[84:85], v170, v12
	v_writelane_b32 v13, s76, 40
	v_writelane_b32 v14, s77, 40
	v_cmp_ge_u32_e64 s[76:77], v163, v12
	v_writelane_b32 v13, s74, 41
	v_writelane_b32 v14, s75, 41
	v_cmp_ge_u32_e64 s[74:75], v172, v12
	v_writelane_b32 v13, s84, 42
	v_writelane_b32 v14, s85, 42
	v_cmp_ge_u32_e64 s[84:85], v165, v12
	v_writelane_b32 v13, s76, 43
	v_writelane_b32 v14, s77, 43
	v_cmp_ge_u32_e64 s[76:77], v174, v12
	v_writelane_b32 v13, s74, 44
	v_writelane_b32 v14, s75, 44
	v_cmp_ge_u32_e64 s[74:75], v169, v12
	s_nop 1
	v_writelane_b32 v13, s84, 45
	v_writelane_b32 v14, s85, 45
	v_writelane_b32 v13, s76, 46
	v_writelane_b32 v14, s77, 46
	v_writelane_b32 v13, s74, 47
	v_writelane_b32 v14, s75, 47
	ds_write2st64_b32 v209, v13, v14 offset1:1
	s_mov_b64 s[2:3], 0
	s_branch .LBB0_3695
; __global__ void __launch_bounds__(512, 2) mega_fwd(KArgs a) {
;     ...
;                     const unsigned cand = tau | (1u << bit);
;                     int c0 = 0, c1 = 0;
; #pragma unroll
;                     for (int jj = 0; jj < 64; ++jj) { const unsigned long long bm = __ballot(key[jj] >= cand); c0 += __popc((unsigned)bm); c1 += __popc((unsigned)(bm >> 32)); }
;                     const int cnt = (lane < 32) ? c0 : c1;
;                     if (cnt >= 256) tau = cand;
;                     done_sel = done_sel || (cnt == 256);
;                     if (__ballot(!done_sel) == 0ull) break;
;                 }
.Lmy_sel_loop_5:
	v_lshl_or_b32 v12, 1, v11, v10
	v_mov_b32_e32 v13, 0
	v_cmp_ge_u32_e64 s[84:85], v3, v12
	v_cmp_ge_u32_e64 s[76:77], v2, v12
	v_cmp_ge_u32_e64 s[74:75], v5, v12
	v_addc_co_u32_e64 v13, vcc, 0, v13, s[84:85]
	v_cmp_ge_u32_e64 s[84:85], v4, v12
	v_addc_co_u32_e64 v13, vcc, 0, v13, s[76:77]
	v_cmp_ge_u32_e64 s[76:77], v7, v12
	v_addc_co_u32_e64 v13, vcc, 0, v13, s[74:75]
	v_cmp_ge_u32_e64 s[74:75], v6, v12
	v_addc_co_u32_e64 v13, vcc, 0, v13, s[84:85]
	v_cmp_ge_u32_e64 s[84:85], v9, v12
	v_addc_co_u32_e64 v13, vcc, 0, v13, s[76:77]
	v_cmp_ge_u32_e64 s[76:77], v8, v12
	v_addc_co_u32_e64 v13, vcc, 0, v13, s[74:75]
	v_cmp_ge_u32_e64 s[74:75], v102, v12
	v_addc_co_u32_e64 v13, vcc, 0, v13, s[84:85]
	v_cmp_ge_u32_e64 s[84:85], v97, v12
	v_addc_co_u32_e64 v13, vcc, 0, v13, s[76:77]
	v_cmp_ge_u32_e64 s[76:77], v104, v12
	v_addc_co_u32_e64 v13, vcc, 0, v13, s[74:75]
	v_cmp_ge_u32_e64 s[74:75], v99, v12
	v_addc_co_u32_e64 v13, vcc, 0, v13, s[84:85]
	v_cmp_ge_u32_e64 s[84:85], v106, v12
	v_addc_co_u32_e64 v13, vcc, 0, v13, s[76:77]
	v_cmp_ge_u32_e64 s[76:77], v101, v12
	v_addc_co_u32_e64 v13, vcc, 0, v13, s[74:75]
	v_cmp_ge_u32_e64 s[74:75], v108, v12
	v_addc_co_u32_e64 v13, vcc, 0, v13, s[84:85]
	v_cmp_ge_u32_e64 s[84:85], v103, v12
	v_addc_co_u32_e64 v13, vcc, 0, v13, s[76:77]
	v_cmp_ge_u32_e64 s[76:77], v110, v12
	v_addc_co_u32_e64 v13, vcc, 0, v13, s[74:75]
	v_cmp_ge_u32_e64 s[74:75], v105, v12
	v_addc_co_u32_e64 v13, vcc, 0, v13, s[84:85]
	v_cmp_ge_u32_e64 s[84:85], v112, v12
	v_addc_co_u32_e64 v13, vcc, 0, v13, s[76:77]
	v_cmp_ge_u32_e64 s[76:77], v107, v12
	v_addc_co_u32_e64 v13, vcc, 0, v13, s[74:75]
	v_cmp_ge_u32_e64 s[74:75], v114, v12
	v_addc_co_u32_e64 v13, vcc, 0, v13, s[84:85]
	v_cmp_ge_u32_e64 s[84:85], v109, v12
	v_addc_co_u32_e64 v13, vcc, 0, v13, s[76:77]
	v_cmp_ge_u32_e64 s[76:77], v116, v12
	v_addc_co_u32_e64 v13, vcc, 0, v13, s[74:75]
	v_cmp_ge_u32_e64 s[74:75], v111, v12
	v_addc_co_u32_e64 v13, vcc, 0, v13, s[84:85]
	v_cmp_ge_u32_e64 s[84:85], v118, v12
	v_addc_co_u32_e64 v13, vcc, 0, v13, s[76:77]
	v_cmp_ge_u32_e64 s[76:77], v113, v12
	v_addc_co_u32_e64 v13, vcc, 0, v13, s[74:75]
	v_cmp_ge_u32_e64 s[74:75], v120, v12
	v_addc_co_u32_e64 v13, vcc, 0, v13, s[84:85]
	v_cmp_ge_u32_e64 s[84:85], v115, v12
	v_addc_co_u32_e64 v13, vcc, 0, v13, s[76:77]
	v_cmp_ge_u32_e64 s[76:77], v122, v12
	v_addc_co_u32_e64 v13, vcc, 0, v13, s[74:75]
	v_cmp_ge_u32_e64 s[74:75], v117, v12
	v_addc_co_u32_e64 v13, vcc, 0, v13, s[84:85]
	v_cmp_ge_u32_e64 s[84:85], v124, v12
	v_addc_co_u32_e64 v13, vcc, 0, v13, s[76:77]
	v_cmp_ge_u32_e64 s[76:77], v119, v12
	v_addc_co_u32_e64 v13, vcc, 0, v13, s[74:75]
	v_cmp_ge_u32_e64 s[74:75], v158, v12
	v_addc_co_u32_e64 v13, vcc, 0, v13, s[84:85]
	v_cmp_ge_u32_e64 s[84:85], v121, v12
	v_addc_co_u32_e64 v13, vcc, 0, v13, s[76:77]
	v_cmp_ge_u32_e64 s[76:77], v160, v12
	v_addc_co_u32_e64 v13, vcc, 0, v13, s[74:75]
	v_cmp_ge_u32_e64 s[74:75], v123, v12
	v_addc_co_u32_e64 v13, vcc, 0, v13, s[84:85]
	v_cmp_ge_u32_e64 s[84:85], v162, v12
	v_addc_co_u32_e64 v13, vcc, 0, v13, s[76:77]
	v_cmp_ge_u32_e64 s[76:77], v125, v12
	v_addc_co_u32_e64 v13, vcc, 0, v13, s[74:75]
	v_cmp_ge_u32_e64 s[74:75], v164, v12
	v_addc_co_u32_e64 v13, vcc, 0, v13, s[84:85]
	v_cmp_ge_u32_e64 s[84:85], v159, v12
	s_nop 1
	v_addc_co_u32_e64 v13, vcc, 0, v13, s[76:77]
	v_addc_co_u32_e64 v13, vcc, 0, v13, s[74:75]
	v_addc_co_u32_e64 v13, vcc, 0, v13, s[84:85]
	s_nop 1
	v_add_u32_dpp v13, v13, v13 quad_perm:[1,0,3,2] row_mask:0xf bank_mask:0xf
	s_nop 1
	v_add_u32_dpp v13, v13, v13 quad_perm:[2,3,0,1] row_mask:0xf bank_mask:0xf
	s_nop 1
	v_add_u32_dpp v13, v13, v13 row_half_mirror row_mask:0xf bank_mask:0xf
	s_nop 1
	v_add_u32_dpp v13, v13, v13 row_mirror row_mask:0xf bank_mask:0xf
	v_mov_b32_e32 v14, v13
	s_nop 1
	v_permlane16_swap_b32 v14, v13
	v_add_u32_e32 v13, v13, v14
	s_movk_i32 s2, 0xff
	v_cmp_lt_i32_e32 vcc, s2, v13
	s_nop 1
	v_cndmask_b32_e32 v10, v10, v12, vcc
	v_cmp_eq_u32_e32 vcc, s5, v13
	s_or_b64 s[0:1], s[0:1], vcc
	s_xor_b64 s[2:3], s[0:1], -1
	v_cndmask_b32_e64 v12, 0, 1, s[2:3]
	v_cmp_ne_u32_e32 vcc, 0, v12
	s_cmp_lg_u64 vcc, 0
	s_cselect_b64 s[2:3], -1, 0
	v_add_co_u32_e32 v11, vcc, -1, v11
	s_and_b64 s[2:3], s[2:3], vcc
	s_and_b64 vcc, exec, s[2:3]
	s_cbranch_vccnz .Lmy_sel_loop_5
	s_andn2_b64 s[2:3], exec, s[0:1]
	s_cbranch_scc0 .Lmy_sel_fast_5
	s_branch .Lmy_sel_slow
; __global__ void __launch_bounds__(512, 2) mega_fwd(KArgs a) {
;     ...
;                     const unsigned cand = tau | (1u << bit);
;                     int c0 = 0, c1 = 0;
; #pragma unroll
;                     for (int jj = 0; jj < 64; ++jj) { const unsigned long long bm = __ballot(key[jj] >= cand); c0 += __popc((unsigned)bm); c1 += __popc((unsigned)(bm >> 32)); }
;                     const int cnt = (lane < 32) ? c0 : c1;
;     ...
;                 if (all_valid) tau = 1u;
;                 int g0 = 0, g1 = 0, e0 = 0, e1 = 0;
; #pragma unroll
;                 for (int jj = 0; jj < 64; ++jj) {
;                     const unsigned long long bg = __ballot(key[jj] > tau), be = __ballot(key[jj] == tau);
;                     g0 += __popc((unsigned)bg); g1 += __popc((unsigned)(bg >> 32)); e0 += __popc((unsigned)be); e1 += __popc((unsigned)(be >> 32));
;                 }
;                 const int cgt = (lane < 32) ? g0 : g1, ceq = (lane < 32) ? e0 : e1;
;                 const int need_eq = all_valid ? (1 << 20) : 256 - cgt;
;                 const bool ties = (!all_valid) && (ceq > need_eq);
;                 unsigned w0 = 0u, w1 = 0u;
;                 if (__ballot(ties) == 0ull) {
; #pragma unroll
;                     for (int jj = 0; jj < 64; ++jj) {
;                         const unsigned long long bm = __ballot(key[jj] >= tau);
;                         if (lane == 0) { wscr[jj] = (unsigned)bm; wscr[64 + jj] = (unsigned)(bm >> 32); }
;                     }
.Lmy_sel_fast_5:
	v_cndmask_b32_e64 v12, v10, 1, s[86:87]
	v_mov_b32_e32 v13, 0
	v_mov_b32_e32 v14, 0
	v_cmp_ge_u32_e64 s[84:85], v3, v12
	v_cmp_ge_u32_e64 s[76:77], v2, v12
	v_cmp_ge_u32_e64 s[74:75], v5, v12
	v_writelane_b32 v13, s84, 0
	v_writelane_b32 v14, s85, 0
	v_cmp_ge_u32_e64 s[84:85], v4, v12
	v_writelane_b32 v13, s76, 1
	v_writelane_b32 v14, s77, 1
	v_cmp_ge_u32_e64 s[76:77], v7, v12
	v_writelane_b32 v13, s74, 2
	v_writelane_b32 v14, s75, 2
	v_cmp_ge_u32_e64 s[74:75], v6, v12
	v_writelane_b32 v13, s84, 3
	v_writelane_b32 v14, s85, 3
	v_cmp_ge_u32_e64 s[84:85], v9, v12
	v_writelane_b32 v13, s76, 4
	v_writelane_b32 v14, s77, 4
	v_cmp_ge_u32_e64 s[76:77], v8, v12
	v_writelane_b32 v13, s74, 5
	v_writelane_b32 v14, s75, 5
	v_cmp_ge_u32_e64 s[74:75], v102, v12
	v_writelane_b32 v13, s84, 6
	v_writelane_b32 v14, s85, 6
	v_cmp_ge_u32_e64 s[84:85], v97, v12
	v_writelane_b32 v13, s76, 7
	v_writelane_b32 v14, s77, 7
	v_cmp_ge_u32_e64 s[76:77], v104, v12
	v_writelane_b32 v13, s74, 8
	v_writelane_b32 v14, s75, 8
	v_cmp_ge_u32_e64 s[74:75], v99, v12
	v_writelane_b32 v13, s84, 9
	v_writelane_b32 v14, s85, 9
	v_cmp_ge_u32_e64 s[84:85], v106, v12
	v_writelane_b32 v13, s76, 10
	v_writelane_b32 v14, s77, 10
	v_cmp_ge_u32_e64 s[76:77], v101, v12
	v_writelane_b32 v13, s74, 11
	v_writelane_b32 v14, s75, 11
	v_cmp_ge_u32_e64 s[74:75], v108, v12
	v_writelane_b32 v13, s84, 12
	v_writelane_b32 v14, s85, 12
	v_cmp_ge_u32_e64 s[84:85], v103, v12
	v_writelane_b32 v13, s76, 13
	v_writelane_b32 v14, s77, 13
	v_cmp_ge_u32_e64 s[76:77], v110, v12
	v_writelane_b32 v13, s74, 14
	v_writelane_b32 v14, s75, 14
	v_cmp_ge_u32_e64 s[74:75], v105, v12
	v_writelane_b32 v13, s84, 15
	v_writelane_b32 v14, s85, 15
	v_cmp_ge_u32_e64 s[84:85], v112, v12
	v_writelane_b32 v13, s76, 16
	v_writelane_b32 v14, s77, 16
	v_cmp_ge_u32_e64 s[76:77], v107, v12
	v_writelane_b32 v13, s74, 17
	v_writelane_b32 v14, s75, 17
	v_cmp_ge_u32_e64 s[74:75], v114, v12
	v_writelane_b32 v13, s84, 18
	v_writelane_b32 v14, s85, 18
	v_cmp_ge_u32_e64 s[84:85], v109, v12
	v_writelane_b32 v13, s76, 19
	v_writelane_b32 v14, s77, 19
	v_cmp_ge_u32_e64 s[76:77], v116, v12
	v_writelane_b32 v13, s74, 20
	v_writelane_b32 v14, s75, 20
	v_cmp_ge_u32_e64 s[74:75], v111, v12
	v_writelane_b32 v13, s84, 21
	v_writelane_b32 v14, s85, 21
	v_cmp_ge_u32_e64 s[84:85], v118, v12
	v_writelane_b32 v13, s76, 22
	v_writelane_b32 v14, s77, 22
	v_cmp_ge_u32_e64 s[76:77], v113, v12
	v_writelane_b32 v13, s74, 23
	v_writelane_b32 v14, s75, 23
	v_cmp_ge_u32_e64 s[74:75], v120, v12
	v_writelane_b32 v13, s84, 24
	v_writelane_b32 v14, s85, 24
	v_cmp_ge_u32_e64 s[84:85], v115, v12
	v_writelane_b32 v13, s76, 25
	v_writelane_b32 v14, s77, 25
	v_cmp_ge_u32_e64 s[76:77], v122, v12
	v_writelane_b32 v13, s74, 26
	v_writelane_b32 v14, s75, 26
	v_cmp_ge_u32_e64 s[74:75], v117, v12
	v_writelane_b32 v13, s84, 27
	v_writelane_b32 v14, s85, 27
	v_cmp_ge_u32_e64 s[84:85], v124, v12
	v_writelane_b32 v13, s76, 28
	v_writelane_b32 v14, s77, 28
	v_cmp_ge_u32_e64 s[76:77], v119, v12
	v_writelane_b32 v13, s74, 29
	v_writelane_b32 v14, s75, 29
	v_cmp_ge_u32_e64 s[74:75], v158, v12
	v_writelane_b32 v13, s84, 30
	v_writelane_b32 v14, s85, 30
	v_cmp_ge_u32_e64 s[84:85], v121, v12
	v_writelane_b32 v13, s76, 31
	v_writelane_b32 v14, s77, 31
	v_cmp_ge_u32_e64 s[76:77], v160, v12
	v_writelane_b32 v13, s74, 32
	v_writelane_b32 v14, s75, 32
	v_cmp_ge_u32_e64 s[74:75], v123, v12
	v_writelane_b32 v13, s84, 33
	v_writelane_b32 v14, s85, 33
	v_cmp_ge_u32_e64 s[84:85], v162, v12
	v_writelane_b32 v13, s76, 34
	v_writelane_b32 v14, s77, 34
	v_cmp_ge_u32_e64 s[76:77], v125, v12
	v_writelane_b32 v13, s74, 35
	v_writelane_b32 v14, s75, 35
	v_cmp_ge_u32_e64 s[74:75], v164, v12
	v_writelane_b32 v13, s84, 36
	v_writelane_b32 v14, s85, 36
	v_cmp_ge_u32_e64 s[84:85], v159, v12
	s_nop 1
	v_writelane_b32 v13, s76, 37
	v_writelane_b32 v14, s77, 37
	v_writelane_b32 v13, s74, 38
	v_writelane_b32 v14, s75, 38
	v_writelane_b32 v13, s84, 39
	v_writelane_b32 v14, s85, 39
	ds_write2st64_b32 v209, v13, v14 offset1:1
	s_mov_b64 s[2:3], 0
	s_branch .LBB0_3695
.Lmy_sel_loop_4:
	v_lshl_or_b32 v12, 1, v11, v10
	v_mov_b32_e32 v13, 0
	v_cmp_ge_u32_e64 s[84:85], v3, v12
	v_cmp_ge_u32_e64 s[76:77], v2, v12
	v_cmp_ge_u32_e64 s[74:75], v5, v12
	v_addc_co_u32_e64 v13, vcc, 0, v13, s[84:85]
	v_cmp_ge_u32_e64 s[84:85], v4, v12
	v_addc_co_u32_e64 v13, vcc, 0, v13, s[76:77]
	v_cmp_ge_u32_e64 s[76:77], v7, v12
	v_addc_co_u32_e64 v13, vcc, 0, v13, s[74:75]
	v_cmp_ge_u32_e64 s[74:75], v6, v12
	v_addc_co_u32_e64 v13, vcc, 0, v13, s[84:85]
	v_cmp_ge_u32_e64 s[84:85], v9, v12
	v_addc_co_u32_e64 v13, vcc, 0, v13, s[76:77]
	v_cmp_ge_u32_e64 s[76:77], v8, v12
	v_addc_co_u32_e64 v13, vcc, 0, v13, s[74:75]
	v_cmp_ge_u32_e64 s[74:75], v102, v12
	v_addc_co_u32_e64 v13, vcc, 0, v13, s[84:85]
	v_cmp_ge_u32_e64 s[84:85], v97, v12
	v_addc_co_u32_e64 v13, vcc, 0, v13, s[76:77]
	v_cmp_ge_u32_e64 s[76:77], v104, v12
	v_addc_co_u32_e64 v13, vcc, 0, v13, s[74:75]
	v_cmp_ge_u32_e64 s[74:75], v99, v12
	v_addc_co_u32_e64 v13, vcc, 0, v13, s[84:85]
	v_cmp_ge_u32_e64 s[84:85], v106, v12
	v_addc_co_u32_e64 v13, vcc, 0, v13, s[76:77]
	v_cmp_ge_u32_e64 s[76:77], v101, v12
	v_addc_co_u32_e64 v13, vcc, 0, v13, s[74:75]
	v_cmp_ge_u32_e64 s[74:75], v108, v12
	v_addc_co_u32_e64 v13, vcc, 0, v13, s[84:85]
	v_cmp_ge_u32_e64 s[84:85], v103, v12
	v_addc_co_u32_e64 v13, vcc, 0, v13, s[76:77]
	v_cmp_ge_u32_e64 s[76:77], v110, v12
	v_addc_co_u32_e64 v13, vcc, 0, v13, s[74:75]
	v_cmp_ge_u32_e64 s[74:75], v105, v12
	v_addc_co_u32_e64 v13, vcc, 0, v13, s[84:85]
	v_cmp_ge_u32_e64 s[84:85], v112, v12
	v_addc_co_u32_e64 v13, vcc, 0, v13, s[76:77]
; __global__ void __launch_bounds__(512, 2) mega_fwd(KArgs a) {
;     ...
;                     for (int jj = 0; jj < 64; ++jj) { const unsigned long long bm = __ballot(key[jj] >= cand); c0 += __popc((unsigned)bm); c1 += __popc((unsigned)(bm >> 32)); }
;                     const int cnt = (lane < 32) ? c0 : c1;
;                     if (cnt >= 256) tau = cand;
;                     done_sel = done_sel || (cnt == 256);
;                     if (__ballot(!done_sel) == 0ull) break;
;                 }
;                 if (all_valid) tau = 1u;
;                 int g0 = 0, g1 = 0, e0 = 0, e1 = 0;
; #pragma unroll
;                 for (int jj = 0; jj < 64; ++jj) {
;                     const unsigned long long bg = __ballot(key[jj] > tau), be = __ballot(key[jj] == tau);
;                     g0 += __popc((unsigned)bg); g1 += __popc((unsigned)(bg >> 32)); e0 += __popc((unsigned)be); e1 += __popc((unsigned)(be >> 32));
;                 }
;                 const int cgt = (lane < 32) ? g0 : g1, ceq = (lane < 32) ? e0 : e1;
;                 const int need_eq = all_valid ? (1 << 20) : 256 - cgt;
;                 const bool ties = (!all_valid) && (ceq > need_eq);
;                 unsigned w0 = 0u, w1 = 0u;
;                 if (__ballot(ties) == 0ull) {
; #pragma unroll
;                     for (int jj = 0; jj < 64; ++jj) {
;                         const unsigned long long bm = __ballot(key[jj] >= tau);
;                         if (lane == 0) { wscr[jj] = (unsigned)bm; wscr[64 + jj] = (unsigned)(bm >> 32); }
;                     }
	v_cmp_ge_u32_e64 s[76:77], v107, v12
	v_addc_co_u32_e64 v13, vcc, 0, v13, s[74:75]
	v_cmp_ge_u32_e64 s[74:75], v114, v12
	v_addc_co_u32_e64 v13, vcc, 0, v13, s[84:85]
	v_cmp_ge_u32_e64 s[84:85], v109, v12
	v_addc_co_u32_e64 v13, vcc, 0, v13, s[76:77]
	v_cmp_ge_u32_e64 s[76:77], v116, v12
	v_addc_co_u32_e64 v13, vcc, 0, v13, s[74:75]
	v_cmp_ge_u32_e64 s[74:75], v111, v12
	v_addc_co_u32_e64 v13, vcc, 0, v13, s[84:85]
	v_cmp_ge_u32_e64 s[84:85], v118, v12
	v_addc_co_u32_e64 v13, vcc, 0, v13, s[76:77]
	v_cmp_ge_u32_e64 s[76:77], v113, v12
	v_addc_co_u32_e64 v13, vcc, 0, v13, s[74:75]
	v_cmp_ge_u32_e64 s[74:75], v120, v12
	v_addc_co_u32_e64 v13, vcc, 0, v13, s[84:85]
	v_cmp_ge_u32_e64 s[84:85], v115, v12
	v_addc_co_u32_e64 v13, vcc, 0, v13, s[76:77]
	v_cmp_ge_u32_e64 s[76:77], v122, v12
	v_addc_co_u32_e64 v13, vcc, 0, v13, s[74:75]
	v_cmp_ge_u32_e64 s[74:75], v117, v12
	v_addc_co_u32_e64 v13, vcc, 0, v13, s[84:85]
	v_cmp_ge_u32_e64 s[84:85], v124, v12
	v_addc_co_u32_e64 v13, vcc, 0, v13, s[76:77]
	v_cmp_ge_u32_e64 s[76:77], v119, v12
	s_nop 1
	v_addc_co_u32_e64 v13, vcc, 0, v13, s[74:75]
	v_addc_co_u32_e64 v13, vcc, 0, v13, s[84:85]
	v_addc_co_u32_e64 v13, vcc, 0, v13, s[76:77]
	s_nop 1
	v_add_u32_dpp v13, v13, v13 quad_perm:[1,0,3,2] row_mask:0xf bank_mask:0xf
	s_nop 1
	v_add_u32_dpp v13, v13, v13 quad_perm:[2,3,0,1] row_mask:0xf bank_mask:0xf
	s_nop 1
	v_add_u32_dpp v13, v13, v13 row_half_mirror row_mask:0xf bank_mask:0xf
	s_nop 1
	v_add_u32_dpp v13, v13, v13 row_mirror row_mask:0xf bank_mask:0xf
	v_mov_b32_e32 v14, v13
	s_nop 1
	v_permlane16_swap_b32 v14, v13
	v_add_u32_e32 v13, v13, v14
	s_movk_i32 s2, 0xff
	v_cmp_lt_i32_e32 vcc, s2, v13
	s_nop 1
	v_cndmask_b32_e32 v10, v10, v12, vcc
	v_cmp_eq_u32_e32 vcc, s5, v13
	s_or_b64 s[0:1], s[0:1], vcc
	s_xor_b64 s[2:3], s[0:1], -1
	v_cndmask_b32_e64 v12, 0, 1, s[2:3]
	v_cmp_ne_u32_e32 vcc, 0, v12
	s_cmp_lg_u64 vcc, 0
	s_cselect_b64 s[2:3], -1, 0
	v_add_co_u32_e32 v11, vcc, -1, v11
	s_and_b64 s[2:3], s[2:3], vcc
	s_and_b64 vcc, exec, s[2:3]
	s_cbranch_vccnz .Lmy_sel_loop_4
	s_andn2_b64 s[2:3], exec, s[0:1]
	s_cbranch_scc0 .Lmy_sel_fast_4
	s_branch .Lmy_sel_slow
.Lmy_sel_fast_4:
	v_cndmask_b32_e64 v12, v10, 1, s[86:87]
	v_mov_b32_e32 v13, 0
	v_mov_b32_e32 v14, 0
	v_cmp_ge_u32_e64 s[84:85], v3, v12
	v_cmp_ge_u32_e64 s[76:77], v2, v12
	v_cmp_ge_u32_e64 s[74:75], v5, v12
	v_writelane_b32 v13, s84, 0
	v_writelane_b32 v14, s85, 0
	v_cmp_ge_u32_e64 s[84:85], v4, v12
	v_writelane_b32 v13, s76, 1
	v_writelane_b32 v14, s77, 1
	v_cmp_ge_u32_e64 s[76:77], v7, v12
	v_writelane_b32 v13, s74, 2
	v_writelane_b32 v14, s75, 2
	v_cmp_ge_u32_e64 s[74:75], v6, v12
	v_writelane_b32 v13, s84, 3
	v_writelane_b32 v14, s85, 3
	v_cmp_ge_u32_e64 s[84:85], v9, v12
	v_writelane_b32 v13, s76, 4
	v_writelane_b32 v14, s77, 4
	v_cmp_ge_u32_e64 s[76:77], v8, v12
	v_writelane_b32 v13, s74, 5
	v_writelane_b32 v14, s75, 5
	v_cmp_ge_u32_e64 s[74:75], v102, v12
	v_writelane_b32 v13, s84, 6
	v_writelane_b32 v14, s85, 6
	v_cmp_ge_u32_e64 s[84:85], v97, v12
	v_writelane_b32 v13, s76, 7
	v_writelane_b32 v14, s77, 7
	v_cmp_ge_u32_e64 s[76:77], v104, v12
	v_writelane_b32 v13, s74, 8
	v_writelane_b32 v14, s75, 8
	v_cmp_ge_u32_e64 s[74:75], v99, v12
	v_writelane_b32 v13, s84, 9
	v_writelane_b32 v14, s85, 9
	v_cmp_ge_u32_e64 s[84:85], v106, v12
	v_writelane_b32 v13, s76, 10
	v_writelane_b32 v14, s77, 10
	v_cmp_ge_u32_e64 s[76:77], v101, v12
	v_writelane_b32 v13, s74, 11
	v_writelane_b32 v14, s75, 11
	v_cmp_ge_u32_e64 s[74:75], v108, v12
	v_writelane_b32 v13, s84, 12
	v_writelane_b32 v14, s85, 12
	v_cmp_ge_u32_e64 s[84:85], v103, v12
	v_writelane_b32 v13, s76, 13
	v_writelane_b32 v14, s77, 13
	v_cmp_ge_u32_e64 s[76:77], v110, v12
	v_writelane_b32 v13, s74, 14
	v_writelane_b32 v14, s75, 14
	v_cmp_ge_u32_e64 s[74:75], v105, v12
	v_writelane_b32 v13, s84, 15
	v_writelane_b32 v14, s85, 15
	v_cmp_ge_u32_e64 s[84:85], v112, v12
	v_writelane_b32 v13, s76, 16
	v_writelane_b32 v14, s77, 16
	v_cmp_ge_u32_e64 s[76:77], v107, v12
	v_writelane_b32 v13, s74, 17
	v_writelane_b32 v14, s75, 17
	v_cmp_ge_u32_e64 s[74:75], v114, v12
	v_writelane_b32 v13, s84, 18
	v_writelane_b32 v14, s85, 18
	v_cmp_ge_u32_e64 s[84:85], v109, v12
	v_writelane_b32 v13, s76, 19
	v_writelane_b32 v14, s77, 19
	v_cmp_ge_u32_e64 s[76:77], v116, v12
	v_writelane_b32 v13, s74, 20
	v_writelane_b32 v14, s75, 20
	v_cmp_ge_u32_e64 s[74:75], v111, v12
	v_writelane_b32 v13, s84, 21
	v_writelane_b32 v14, s85, 21
	v_cmp_ge_u32_e64 s[84:85], v118, v12
	v_writelane_b32 v13, s76, 22
	v_writelane_b32 v14, s77, 22
	v_cmp_ge_u32_e64 s[76:77], v113, v12
	v_writelane_b32 v13, s74, 23
	v_writelane_b32 v14, s75, 23
	v_cmp_ge_u32_e64 s[74:75], v120, v12
	v_writelane_b32 v13, s84, 24
	v_writelane_b32 v14, s85, 24
	v_cmp_ge_u32_e64 s[84:85], v115, v12
	v_writelane_b32 v13, s76, 25
	v_writelane_b32 v14, s77, 25
	v_cmp_ge_u32_e64 s[76:77], v122, v12
	v_writelane_b32 v13, s74, 26
	v_writelane_b32 v14, s75, 26
	v_cmp_ge_u32_e64 s[74:75], v117, v12
	v_writelane_b32 v13, s84, 27
	v_writelane_b32 v14, s85, 27
	v_cmp_ge_u32_e64 s[84:85], v124, v12
	v_writelane_b32 v13, s76, 28
	v_writelane_b32 v14, s77, 28
	v_cmp_ge_u32_e64 s[76:77], v119, v12
	s_nop 1
	v_writelane_b32 v13, s74, 29
	v_writelane_b32 v14, s75, 29
	v_writelane_b32 v13, s84, 30
	v_writelane_b32 v14, s85, 30
	v_writelane_b32 v13, s76, 31
	v_writelane_b32 v14, s77, 31
	ds_write2st64_b32 v209, v13, v14 offset1:1
	s_mov_b64 s[2:3], 0
	s_branch .LBB0_3695
; __global__ void __launch_bounds__(512, 2) mega_fwd(KArgs a) {
;     ...
;                     const unsigned cand = tau | (1u << bit);
;                     int c0 = 0, c1 = 0;
; #pragma unroll
;                     for (int jj = 0; jj < 64; ++jj) { const unsigned long long bm = __ballot(key[jj] >= cand); c0 += __popc((unsigned)bm); c1 += __popc((unsigned)(bm >> 32)); }
;                     const int cnt = (lane < 32) ? c0 : c1;
;                     if (cnt >= 256) tau = cand;
;                     done_sel = done_sel || (cnt == 256);
;                     if (__ballot(!done_sel) == 0ull) break;
;                 }
;                 if (all_valid) tau = 1u;
;                 int g0 = 0, g1 = 0, e0 = 0, e1 = 0;
; #pragma unroll
;                 for (int jj = 0; jj < 64; ++jj) {
;                     const unsigned long long bg = __ballot(key[jj] > tau), be = __ballot(key[jj] == tau);
;                     g0 += __popc((unsigned)bg); g1 += __popc((unsigned)(bg >> 32)); e0 += __popc((unsigned)be); e1 += __popc((unsigned)(be >> 32));
;                 }
;                 const int cgt = (lane < 32) ? g0 : g1, ceq = (lane < 32) ? e0 : e1;
;                 const int need_eq = all_valid ? (1 << 20) : 256 - cgt;
;                 const bool ties = (!all_valid) && (ceq > need_eq);
;                 unsigned w0 = 0u, w1 = 0u;
;                 if (__ballot(ties) == 0ull) {
; #pragma unroll
;                     for (int jj = 0; jj < 64; ++jj) {
;                         const unsigned long long bm = __ballot(key[jj] >= tau);
;                         if (lane == 0) { wscr[jj] = (unsigned)bm; wscr[64 + jj] = (unsigned)(bm >> 32); }
;                     }
.Lmy_sel_loop_3:
	v_lshl_or_b32 v12, 1, v11, v10
	v_mov_b32_e32 v13, 0
	v_cmp_ge_u32_e64 s[84:85], v3, v12
	v_cmp_ge_u32_e64 s[76:77], v2, v12
	v_cmp_ge_u32_e64 s[74:75], v5, v12
	v_addc_co_u32_e64 v13, vcc, 0, v13, s[84:85]
	v_cmp_ge_u32_e64 s[84:85], v4, v12
	v_addc_co_u32_e64 v13, vcc, 0, v13, s[76:77]
	v_cmp_ge_u32_e64 s[76:77], v7, v12
	v_addc_co_u32_e64 v13, vcc, 0, v13, s[74:75]
	v_cmp_ge_u32_e64 s[74:75], v6, v12
	v_addc_co_u32_e64 v13, vcc, 0, v13, s[84:85]
	v_cmp_ge_u32_e64 s[84:85], v9, v12
	v_addc_co_u32_e64 v13, vcc, 0, v13, s[76:77]
	v_cmp_ge_u32_e64 s[76:77], v8, v12
	v_addc_co_u32_e64 v13, vcc, 0, v13, s[74:75]
	v_cmp_ge_u32_e64 s[74:75], v102, v12
	v_addc_co_u32_e64 v13, vcc, 0, v13, s[84:85]
	v_cmp_ge_u32_e64 s[84:85], v97, v12
	v_addc_co_u32_e64 v13, vcc, 0, v13, s[76:77]
	v_cmp_ge_u32_e64 s[76:77], v104, v12
	v_addc_co_u32_e64 v13, vcc, 0, v13, s[74:75]
	v_cmp_ge_u32_e64 s[74:75], v99, v12
	v_addc_co_u32_e64 v13, vcc, 0, v13, s[84:85]
	v_cmp_ge_u32_e64 s[84:85], v106, v12
	v_addc_co_u32_e64 v13, vcc, 0, v13, s[76:77]
	v_cmp_ge_u32_e64 s[76:77], v101, v12
	v_addc_co_u32_e64 v13, vcc, 0, v13, s[74:75]
	v_cmp_ge_u32_e64 s[74:75], v108, v12
	v_addc_co_u32_e64 v13, vcc, 0, v13, s[84:85]
	v_cmp_ge_u32_e64 s[84:85], v103, v12
	v_addc_co_u32_e64 v13, vcc, 0, v13, s[76:77]
	v_cmp_ge_u32_e64 s[76:77], v110, v12
	v_addc_co_u32_e64 v13, vcc, 0, v13, s[74:75]
	v_cmp_ge_u32_e64 s[74:75], v105, v12
	v_addc_co_u32_e64 v13, vcc, 0, v13, s[84:85]
	v_cmp_ge_u32_e64 s[84:85], v112, v12
	v_addc_co_u32_e64 v13, vcc, 0, v13, s[76:77]
	v_cmp_ge_u32_e64 s[76:77], v107, v12
	v_addc_co_u32_e64 v13, vcc, 0, v13, s[74:75]
	v_cmp_ge_u32_e64 s[74:75], v114, v12
	v_addc_co_u32_e64 v13, vcc, 0, v13, s[84:85]
	v_cmp_ge_u32_e64 s[84:85], v109, v12
	v_addc_co_u32_e64 v13, vcc, 0, v13, s[76:77]
	v_cmp_ge_u32_e64 s[76:77], v116, v12
	v_addc_co_u32_e64 v13, vcc, 0, v13, s[74:75]
	v_cmp_ge_u32_e64 s[74:75], v111, v12
	s_nop 1
	v_addc_co_u32_e64 v13, vcc, 0, v13, s[84:85]
	v_addc_co_u32_e64 v13, vcc, 0, v13, s[76:77]
	v_addc_co_u32_e64 v13, vcc, 0, v13, s[74:75]
	s_nop 1
	v_add_u32_dpp v13, v13, v13 quad_perm:[1,0,3,2] row_mask:0xf bank_mask:0xf
	s_nop 1
	v_add_u32_dpp v13, v13, v13 quad_perm:[2,3,0,1] row_mask:0xf bank_mask:0xf
	s_nop 1
	v_add_u32_dpp v13, v13, v13 row_half_mirror row_mask:0xf bank_mask:0xf
	s_nop 1
	v_add_u32_dpp v13, v13, v13 row_mirror row_mask:0xf bank_mask:0xf
	v_mov_b32_e32 v14, v13
	s_nop 1
	v_permlane16_swap_b32 v14, v13
	v_add_u32_e32 v13, v13, v14
	s_movk_i32 s2, 0xff
	v_cmp_lt_i32_e32 vcc, s2, v13
	s_nop 1
	v_cndmask_b32_e32 v10, v10, v12, vcc
	v_cmp_eq_u32_e32 vcc, s5, v13
	s_or_b64 s[0:1], s[0:1], vcc
	s_xor_b64 s[2:3], s[0:1], -1
	v_cndmask_b32_e64 v12, 0, 1, s[2:3]
	v_cmp_ne_u32_e32 vcc, 0, v12
	s_cmp_lg_u64 vcc, 0
	s_cselect_b64 s[2:3], -1, 0
	v_add_co_u32_e32 v11, vcc, -1, v11
	s_and_b64 s[2:3], s[2:3], vcc
	s_and_b64 vcc, exec, s[2:3]
	s_cbranch_vccnz .Lmy_sel_loop_3
	s_andn2_b64 s[2:3], exec, s[0:1]
	s_cbranch_scc0 .Lmy_sel_fast_3
	s_branch .Lmy_sel_slow
.Lmy_sel_fast_3:
	v_cndmask_b32_e64 v12, v10, 1, s[86:87]
	v_mov_b32_e32 v13, 0
	v_mov_b32_e32 v14, 0
	v_cmp_ge_u32_e64 s[84:85], v3, v12
	v_cmp_ge_u32_e64 s[76:77], v2, v12
	v_cmp_ge_u32_e64 s[74:75], v5, v12
	v_writelane_b32 v13, s84, 0
	v_writelane_b32 v14, s85, 0
	v_cmp_ge_u32_e64 s[84:85], v4, v12
	v_writelane_b32 v13, s76, 1
	v_writelane_b32 v14, s77, 1
	v_cmp_ge_u32_e64 s[76:77], v7, v12
	v_writelane_b32 v13, s74, 2
	v_writelane_b32 v14, s75, 2
	v_cmp_ge_u32_e64 s[74:75], v6, v12
	v_writelane_b32 v13, s84, 3
	v_writelane_b32 v14, s85, 3
	v_cmp_ge_u32_e64 s[84:85], v9, v12
	v_writelane_b32 v13, s76, 4
	v_writelane_b32 v14, s77, 4
	v_cmp_ge_u32_e64 s[76:77], v8, v12
	v_writelane_b32 v13, s74, 5
	v_writelane_b32 v14, s75, 5
	v_cmp_ge_u32_e64 s[74:75], v102, v12
	v_writelane_b32 v13, s84, 6
	v_writelane_b32 v14, s85, 6
	v_cmp_ge_u32_e64 s[84:85], v97, v12
	v_writelane_b32 v13, s76, 7
	v_writelane_b32 v14, s77, 7
	v_cmp_ge_u32_e64 s[76:77], v104, v12
	v_writelane_b32 v13, s74, 8
	v_writelane_b32 v14, s75, 8
	v_cmp_ge_u32_e64 s[74:75], v99, v12
	v_writelane_b32 v13, s84, 9
	v_writelane_b32 v14, s85, 9
	v_cmp_ge_u32_e64 s[84:85], v106, v12
	v_writelane_b32 v13, s76, 10
	v_writelane_b32 v14, s77, 10
	v_cmp_ge_u32_e64 s[76:77], v101, v12
	v_writelane_b32 v13, s74, 11
	v_writelane_b32 v14, s75, 11
	v_cmp_ge_u32_e64 s[74:75], v108, v12
	v_writelane_b32 v13, s84, 12
	v_writelane_b32 v14, s85, 12
	v_cmp_ge_u32_e64 s[84:85], v103, v12
	v_writelane_b32 v13, s76, 13
	v_writelane_b32 v14, s77, 13
	v_cmp_ge_u32_e64 s[76:77], v110, v12
	v_writelane_b32 v13, s74, 14
	v_writelane_b32 v14, s75, 14
	v_cmp_ge_u32_e64 s[74:75], v105, v12
	v_writelane_b32 v13, s84, 15
	v_writelane_b32 v14, s85, 15
	v_cmp_ge_u32_e64 s[84:85], v112, v12
	v_writelane_b32 v13, s76, 16
	v_writelane_b32 v14, s77, 16
	v_cmp_ge_u32_e64 s[76:77], v107, v12
	v_writelane_b32 v13, s74, 17
	v_writelane_b32 v14, s75, 17
	v_cmp_ge_u32_e64 s[74:75], v114, v12
	v_writelane_b32 v13, s84, 18
	v_writelane_b32 v14, s85, 18
	v_cmp_ge_u32_e64 s[84:85], v109, v12
	v_writelane_b32 v13, s76, 19
	v_writelane_b32 v14, s77, 19
	v_cmp_ge_u32_e64 s[76:77], v116, v12
	v_writelane_b32 v13, s74, 20
	v_writelane_b32 v14, s75, 20
	v_cmp_ge_u32_e64 s[74:75], v111, v12
	s_nop 1
	v_writelane_b32 v13, s84, 21
	v_writelane_b32 v14, s85, 21
	v_writelane_b32 v13, s76, 22
	v_writelane_b32 v14, s77, 22
	v_writelane_b32 v13, s74, 23
	v_writelane_b32 v14, s75, 23
	ds_write2st64_b32 v209, v13, v14 offset1:1
	s_mov_b64 s[2:3], 0
	s_branch .LBB0_3695
; __global__ void __launch_bounds__(512, 2) mega_fwd(KArgs a) {
;     ...
;                     const unsigned cand = tau | (1u << bit);
;                     int c0 = 0, c1 = 0;
; #pragma unroll
;                     for (int jj = 0; jj < 64; ++jj) { const unsigned long long bm = __ballot(key[jj] >= cand); c0 += __popc((unsigned)bm); c1 += __popc((unsigned)(bm >> 32)); }
;                     const int cnt = (lane < 32) ? c0 : c1;
;                     if (cnt >= 256) tau = cand;
;                     done_sel = done_sel || (cnt == 256);
;                     if (__ballot(!done_sel) == 0ull) break;
;                 }
;                 if (all_valid) tau = 1u;
;                 int g0 = 0, g1 = 0, e0 = 0, e1 = 0;
; #pragma unroll
;                 for (int jj = 0; jj < 64; ++jj) {
;                     const unsigned long long bg = __ballot(key[jj] > tau), be = __ballot(key[jj] == tau);
;                     g0 += __popc((unsigned)bg); g1 += __popc((unsigned)(bg >> 32)); e0 += __popc((unsigned)be); e1 += __popc((unsigned)(be >> 32));
;                 }
;                 const int cgt = (lane < 32) ? g0 : g1, ceq = (lane < 32) ? e0 : e1;
;                 const int need_eq = all_valid ? (1 << 20) : 256 - cgt;
;                 const bool ties = (!all_valid) && (ceq > need_eq);
;                 unsigned w0 = 0u, w1 = 0u;
;                 if (__ballot(ties) == 0ull) {
; #pragma unroll
;                     for (int jj = 0; jj < 64; ++jj) {
;                         const unsigned long long bm = __ballot(key[jj] >= tau);
;                         if (lane == 0) { wscr[jj] = (unsigned)bm; wscr[64 + jj] = (unsigned)(bm >> 32); }
;                     }
.Lmy_sel_loop_2:
	v_lshl_or_b32 v12, 1, v11, v10
	v_mov_b32_e32 v13, 0
	v_cmp_ge_u32_e64 s[84:85], v3, v12
	v_cmp_ge_u32_e64 s[76:77], v2, v12
	v_cmp_ge_u32_e64 s[74:75], v5, v12
	v_addc_co_u32_e64 v13, vcc, 0, v13, s[84:85]
	v_cmp_ge_u32_e64 s[84:85], v4, v12
	v_addc_co_u32_e64 v13, vcc, 0, v13, s[76:77]
	v_cmp_ge_u32_e64 s[76:77], v7, v12
	v_addc_co_u32_e64 v13, vcc, 0, v13, s[74:75]
	v_cmp_ge_u32_e64 s[74:75], v6, v12
	v_addc_co_u32_e64 v13, vcc, 0, v13, s[84:85]
	v_cmp_ge_u32_e64 s[84:85], v9, v12
	v_addc_co_u32_e64 v13, vcc, 0, v13, s[76:77]
	v_cmp_ge_u32_e64 s[76:77], v8, v12
	v_addc_co_u32_e64 v13, vcc, 0, v13, s[74:75]
	v_cmp_ge_u32_e64 s[74:75], v102, v12
	v_addc_co_u32_e64 v13, vcc, 0, v13, s[84:85]
	v_cmp_ge_u32_e64 s[84:85], v97, v12
	v_addc_co_u32_e64 v13, vcc, 0, v13, s[76:77]
	v_cmp_ge_u32_e64 s[76:77], v104, v12
	v_addc_co_u32_e64 v13, vcc, 0, v13, s[74:75]
	v_cmp_ge_u32_e64 s[74:75], v99, v12
	v_addc_co_u32_e64 v13, vcc, 0, v13, s[84:85]
	v_cmp_ge_u32_e64 s[84:85], v106, v12
	v_addc_co_u32_e64 v13, vcc, 0, v13, s[76:77]
	v_cmp_ge_u32_e64 s[76:77], v101, v12
	v_addc_co_u32_e64 v13, vcc, 0, v13, s[74:75]
	v_cmp_ge_u32_e64 s[74:75], v108, v12
	v_addc_co_u32_e64 v13, vcc, 0, v13, s[84:85]
	v_cmp_ge_u32_e64 s[84:85], v103, v12
	s_nop 1
	v_addc_co_u32_e64 v13, vcc, 0, v13, s[76:77]
	v_addc_co_u32_e64 v13, vcc, 0, v13, s[74:75]
	v_addc_co_u32_e64 v13, vcc, 0, v13, s[84:85]
	s_nop 1
	v_add_u32_dpp v13, v13, v13 quad_perm:[1,0,3,2] row_mask:0xf bank_mask:0xf
	s_nop 1
	v_add_u32_dpp v13, v13, v13 quad_perm:[2,3,0,1] row_mask:0xf bank_mask:0xf
	s_nop 1
	v_add_u32_dpp v13, v13, v13 row_half_mirror row_mask:0xf bank_mask:0xf
	s_nop 1
	v_add_u32_dpp v13, v13, v13 row_mirror row_mask:0xf bank_mask:0xf
	v_mov_b32_e32 v14, v13
	s_nop 1
	v_permlane16_swap_b32 v14, v13
	v_add_u32_e32 v13, v13, v14
	s_movk_i32 s2, 0xff
	v_cmp_lt_i32_e32 vcc, s2, v13
	s_nop 1
	v_cndmask_b32_e32 v10, v10, v12, vcc
	v_cmp_eq_u32_e32 vcc, s5, v13
	s_or_b64 s[0:1], s[0:1], vcc
	s_xor_b64 s[2:3], s[0:1], -1
	v_cndmask_b32_e64 v12, 0, 1, s[2:3]
	v_cmp_ne_u32_e32 vcc, 0, v12
	s_cmp_lg_u64 vcc, 0
	s_cselect_b64 s[2:3], -1, 0
	v_add_co_u32_e32 v11, vcc, -1, v11
	s_and_b64 s[2:3], s[2:3], vcc
	s_and_b64 vcc, exec, s[2:3]
	s_cbranch_vccnz .Lmy_sel_loop_2
	s_andn2_b64 s[2:3], exec, s[0:1]
	s_cbranch_scc0 .Lmy_sel_fast_2
	s_branch .Lmy_sel_slow
.Lmy_sel_fast_2:
	v_cndmask_b32_e64 v12, v10, 1, s[86:87]
	v_mov_b32_e32 v13, 0
	v_mov_b32_e32 v14, 0
	v_cmp_ge_u32_e64 s[84:85], v3, v12
	v_cmp_ge_u32_e64 s[76:77], v2, v12
	v_cmp_ge_u32_e64 s[74:75], v5, v12
	v_writelane_b32 v13, s84, 0
	v_writelane_b32 v14, s85, 0
	v_cmp_ge_u32_e64 s[84:85], v4, v12
	v_writelane_b32 v13, s76, 1
	v_writelane_b32 v14, s77, 1
	v_cmp_ge_u32_e64 s[76:77], v7, v12
	v_writelane_b32 v13, s74, 2
	v_writelane_b32 v14, s75, 2
	v_cmp_ge_u32_e64 s[74:75], v6, v12
	v_writelane_b32 v13, s84, 3
	v_writelane_b32 v14, s85, 3
	v_cmp_ge_u32_e64 s[84:85], v9, v12
	v_writelane_b32 v13, s76, 4
	v_writelane_b32 v14, s77, 4
	v_cmp_ge_u32_e64 s[76:77], v8, v12
	v_writelane_b32 v13, s74, 5
	v_writelane_b32 v14, s75, 5
	v_cmp_ge_u32_e64 s[74:75], v102, v12
	v_writelane_b32 v13, s84, 6
	v_writelane_b32 v14, s85, 6
	v_cmp_ge_u32_e64 s[84:85], v97, v12
	v_writelane_b32 v13, s76, 7
	v_writelane_b32 v14, s77, 7
	v_cmp_ge_u32_e64 s[76:77], v104, v12
	v_writelane_b32 v13, s74, 8
	v_writelane_b32 v14, s75, 8
	v_cmp_ge_u32_e64 s[74:75], v99, v12
	v_writelane_b32 v13, s84, 9
	v_writelane_b32 v14, s85, 9
	v_cmp_ge_u32_e64 s[84:85], v106, v12
	v_writelane_b32 v13, s76, 10
	v_writelane_b32 v14, s77, 10
	v_cmp_ge_u32_e64 s[76:77], v101, v12
	v_writelane_b32 v13, s74, 11
	v_writelane_b32 v14, s75, 11
	v_cmp_ge_u32_e64 s[74:75], v108, v12
	v_writelane_b32 v13, s84, 12
	v_writelane_b32 v14, s85, 12
	v_cmp_ge_u32_e64 s[84:85], v103, v12
	s_nop 1
	v_writelane_b32 v13, s76, 13
	v_writelane_b32 v14, s77, 13
	v_writelane_b32 v13, s74, 14
	v_writelane_b32 v14, s75, 14
	v_writelane_b32 v13, s84, 15
	v_writelane_b32 v14, s85, 15
	ds_write2st64_b32 v209, v13, v14 offset1:1
	s_mov_b64 s[2:3], 0
	s_branch .LBB0_3695
.Lmy_sel_loop_1:
	v_lshl_or_b32 v12, 1, v11, v10
	v_mov_b32_e32 v13, 0
	v_cmp_ge_u32_e64 s[84:85], v3, v12
	v_cmp_ge_u32_e64 s[76:77], v2, v12
	v_cmp_ge_u32_e64 s[74:75], v5, v12
	v_addc_co_u32_e64 v13, vcc, 0, v13, s[84:85]
	v_cmp_ge_u32_e64 s[84:85], v4, v12
	v_addc_co_u32_e64 v13, vcc, 0, v13, s[76:77]
	v_cmp_ge_u32_e64 s[76:77], v7, v12
	v_addc_co_u32_e64 v13, vcc, 0, v13, s[74:75]
	v_cmp_ge_u32_e64 s[74:75], v6, v12
	v_addc_co_u32_e64 v13, vcc, 0, v13, s[84:85]
	v_cmp_ge_u32_e64 s[84:85], v9, v12
	v_addc_co_u32_e64 v13, vcc, 0, v13, s[76:77]
	v_cmp_ge_u32_e64 s[76:77], v8, v12
	s_nop 1
	v_addc_co_u32_e64 v13, vcc, 0, v13, s[74:75]
	v_addc_co_u32_e64 v13, vcc, 0, v13, s[84:85]
	v_addc_co_u32_e64 v13, vcc, 0, v13, s[76:77]
	s_nop 1
	v_add_u32_dpp v13, v13, v13 quad_perm:[1,0,3,2] row_mask:0xf bank_mask:0xf
	s_nop 1
	v_add_u32_dpp v13, v13, v13 quad_perm:[2,3,0,1] row_mask:0xf bank_mask:0xf
	s_nop 1
	v_add_u32_dpp v13, v13, v13 row_half_mirror row_mask:0xf bank_mask:0xf
	s_nop 1
	v_add_u32_dpp v13, v13, v13 row_mirror row_mask:0xf bank_mask:0xf
	v_mov_b32_e32 v14, v13
	s_nop 1
	v_permlane16_swap_b32 v14, v13
	v_add_u32_e32 v13, v13, v14
	s_movk_i32 s2, 0xff
	v_cmp_lt_i32_e32 vcc, s2, v13
	s_nop 1
	v_cndmask_b32_e32 v10, v10, v12, vcc
	v_cmp_eq_u32_e32 vcc, s5, v13
	s_or_b64 s[0:1], s[0:1], vcc
	s_xor_b64 s[2:3], s[0:1], -1
	v_cndmask_b32_e64 v12, 0, 1, s[2:3]
	v_cmp_ne_u32_e32 vcc, 0, v12
	s_cmp_lg_u64 vcc, 0
	s_cselect_b64 s[2:3], -1, 0
	v_add_co_u32_e32 v11, vcc, -1, v11
	s_and_b64 s[2:3], s[2:3], vcc
	s_and_b64 vcc, exec, s[2:3]
	s_cbranch_vccnz .Lmy_sel_loop_1
	s_andn2_b64 s[2:3], exec, s[0:1]
	s_cbranch_scc0 .Lmy_sel_fast_1
	s_branch .Lmy_sel_slow
; __global__ void __launch_bounds__(512, 2) mega_fwd(KArgs a) {
;     ...
; #pragma unroll
;                 for (int jj = 0; jj < 64; ++jj) {
;                     const unsigned long long bg = __ballot(key[jj] > tau), be = __ballot(key[jj] == tau);
;                     g0 += __popc((unsigned)bg); g1 += __popc((unsigned)(bg >> 32)); e0 += __popc((unsigned)be); e1 += __popc((unsigned)(be >> 32));
;                 }
;     ...
;                 unsigned w0 = 0u, w1 = 0u;
;                 if (__ballot(ties) == 0ull) {
; #pragma unroll
;                     for (int jj = 0; jj < 64; ++jj) {
;                         const unsigned long long bm = __ballot(key[jj] >= tau);
;                         if (lane == 0) { wscr[jj] = (unsigned)bm; wscr[64 + jj] = (unsigned)(bm >> 32); }
;                     }
.Lmy_sel_fast_1:
	v_cndmask_b32_e64 v12, v10, 1, s[86:87]
	v_mov_b32_e32 v13, 0
	v_mov_b32_e32 v14, 0
	v_cmp_ge_u32_e64 s[84:85], v3, v12
	v_cmp_ge_u32_e64 s[76:77], v2, v12
	v_cmp_ge_u32_e64 s[74:75], v5, v12
	v_writelane_b32 v13, s84, 0
	v_writelane_b32 v14, s85, 0
	v_cmp_ge_u32_e64 s[84:85], v4, v12
	v_writelane_b32 v13, s76, 1
	v_writelane_b32 v14, s77, 1
	v_cmp_ge_u32_e64 s[76:77], v7, v12
	v_writelane_b32 v13, s74, 2
	v_writelane_b32 v14, s75, 2
	v_cmp_ge_u32_e64 s[74:75], v6, v12
	v_writelane_b32 v13, s84, 3
	v_writelane_b32 v14, s85, 3
	v_cmp_ge_u32_e64 s[84:85], v9, v12
	v_writelane_b32 v13, s76, 4
	v_writelane_b32 v14, s77, 4
	v_cmp_ge_u32_e64 s[76:77], v8, v12
	s_nop 1
	v_writelane_b32 v13, s74, 5
	v_writelane_b32 v14, s75, 5
	v_writelane_b32 v13, s84, 6
	v_writelane_b32 v14, s85, 6
	v_writelane_b32 v13, s76, 7
	v_writelane_b32 v14, s77, 7
	ds_write2st64_b32 v209, v13, v14 offset1:1
	s_mov_b64 s[2:3], 0
	s_branch .LBB0_3695
.Lmy_sel_slow:
	v_cndmask_b32_e64 v12, v10, 1, s[86:87]
	v_cmp_gt_u32_e64 s[84:85], v3, v12
	v_cmp_gt_u32_e64 s[76:77], v2, v12
	s_bcnt1_i32_b32 s0, s84
	s_bcnt1_i32_b32 s4, s76
	v_cmp_eq_u32_e64 s[74:75], v3, v12
	s_bcnt1_i32_b32 s1, s85
	v_cmp_eq_u32_e64 s[72:73], v2, v12
	s_add_i32 s4, s4, s0
	s_bcnt1_i32_b32 s0, s77
	s_bcnt1_i32_b32 s2, s74
	s_add_i32 s0, s0, s1
	s_bcnt1_i32_b32 s1, s72
	s_bcnt1_i32_b32 s3, s75
	s_add_i32 s1, s1, s2
	s_bcnt1_i32_b32 s2, s73
	v_cmp_gt_u32_e64 s[68:69], v5, v12
	s_add_i32 s2, s2, s3
	s_bcnt1_i32_b32 s3, s68
	v_cmp_eq_u32_e64 s[64:65], v5, v12
	s_add_i32 s3, s3, s4
	s_bcnt1_i32_b32 s4, s69
	s_add_i32 s4, s4, s0
	s_bcnt1_i32_b32 s0, s64
	s_add_i32 s0, s0, s1
	s_bcnt1_i32_b32 s1, s65
	v_cmp_gt_u32_e64 s[60:61], v4, v12
	s_add_i32 s1, s1, s2
	s_bcnt1_i32_b32 s2, s60
	v_cmp_eq_u32_e64 s[56:57], v4, v12
	s_add_i32 s2, s2, s3
	s_bcnt1_i32_b32 s3, s61
	s_add_i32 s3, s3, s4
	s_bcnt1_i32_b32 s4, s56
	s_add_i32 s4, s4, s0
	s_bcnt1_i32_b32 s0, s57
	v_cmp_gt_u32_e64 s[48:49], v7, v12
	s_add_i32 s0, s0, s1
	s_bcnt1_i32_b32 s1, s48
	v_cmp_eq_u32_e64 s[52:53], v7, v12
	s_add_i32 s1, s1, s2
	s_bcnt1_i32_b32 s2, s49
	s_add_i32 s2, s2, s3
	s_bcnt1_i32_b32 s3, s52
	s_add_i32 s3, s3, s4
	s_bcnt1_i32_b32 s4, s53
	v_cmp_gt_u32_e64 s[40:41], v6, v12
	s_add_i32 s4, s4, s0
	s_bcnt1_i32_b32 s0, s40
	v_cmp_eq_u32_e64 s[44:45], v6, v12
	s_add_i32 s0, s0, s1
	s_bcnt1_i32_b32 s1, s41
	s_add_i32 s1, s1, s2
	s_bcnt1_i32_b32 s2, s44
	s_add_i32 s2, s2, s3
	s_bcnt1_i32_b32 s3, s45
	v_cmp_gt_u32_e64 s[30:31], v9, v12
	s_add_i32 s3, s3, s4
	s_bcnt1_i32_b32 s4, s30
	v_cmp_eq_u32_e64 s[36:37], v9, v12
	s_add_i32 s4, s4, s0
	s_bcnt1_i32_b32 s0, s31
	s_add_i32 s0, s0, s1
	s_bcnt1_i32_b32 s1, s36
	s_add_i32 s1, s1, s2
	s_bcnt1_i32_b32 s2, s37
	v_cmp_gt_u32_e64 s[42:43], v8, v12
	s_add_i32 s2, s2, s3
	s_bcnt1_i32_b32 s3, s42
	v_cmp_eq_u32_e64 s[26:27], v8, v12
	s_add_i32 s3, s3, s4
	s_bcnt1_i32_b32 s4, s43
	s_add_i32 s4, s4, s0
	s_bcnt1_i32_b32 s0, s26
	s_add_i32 s0, s0, s1
	s_bcnt1_i32_b32 s1, s27
	v_cmp_gt_u32_e64 s[38:39], v102, v12
	s_add_i32 s1, s1, s2
	s_bcnt1_i32_b32 s2, s38
	v_cmp_eq_u32_e64 s[18:19], v102, v12
	s_add_i32 s2, s2, s3
	s_bcnt1_i32_b32 s3, s39
	s_add_i32 s3, s3, s4
	s_bcnt1_i32_b32 s4, s18
	s_add_i32 s4, s4, s0
	s_bcnt1_i32_b32 s0, s19
	v_cmp_gt_u32_e64 s[34:35], v97, v12
	s_add_i32 s0, s0, s1
	s_bcnt1_i32_b32 s1, s34
	v_cmp_eq_u32_e64 s[10:11], v97, v12
	s_add_i32 s2, s1, s2
	s_bcnt1_i32_b32 s1, s35
	s_add_i32 s3, s1, s3
	s_bcnt1_i32_b32 s1, s10
	v_cmp_gt_u32_e64 s[28:29], v104, v12
	s_add_i32 s4, s1, s4
	s_bcnt1_i32_b32 s1, s11
	s_bcnt1_i32_b32 s6, s28
	s_add_i32 s5, s1, s0
	v_cmp_eq_u32_e64 s[0:1], v104, v12
	s_add_i32 s6, s6, s2
	s_bcnt1_i32_b32 s2, s29
	s_add_i32 s2, s2, s3
	s_bcnt1_i32_b32 s3, s0
	s_add_i32 s3, s3, s4
	s_bcnt1_i32_b32 s4, s1
	v_cmp_gt_u32_e64 s[94:95], v99, v12
	s_add_i32 s4, s4, s5
	s_bcnt1_i32_b32 s5, s94
	v_cmp_eq_u32_e64 s[82:83], v99, v12
	s_add_i32 s5, s5, s6
	s_bcnt1_i32_b32 s6, s95
	s_add_i32 s6, s6, s2
	s_bcnt1_i32_b32 s2, s82
	s_add_i32 s2, s2, s3
	s_bcnt1_i32_b32 s3, s83
	v_cmp_gt_u32_e64 s[90:91], v106, v12
	s_add_i32 s3, s3, s4
	s_bcnt1_i32_b32 s4, s90
	v_cmp_eq_u32_e64 s[24:25], v106, v12
	s_add_i32 s4, s4, s5
	s_bcnt1_i32_b32 s5, s91
	s_add_i32 s5, s5, s6
	s_bcnt1_i32_b32 s6, s24
	s_add_i32 s6, s6, s2
	s_bcnt1_i32_b32 s2, s25
	v_cmp_gt_u32_e64 s[14:15], v101, v12
	s_add_i32 s2, s2, s3
	s_bcnt1_i32_b32 s3, s14
	v_cmp_eq_u32_e64 s[20:21], v101, v12
	s_add_i32 s3, s3, s4
	v_writelane_b32 v252, s14, 42
	s_bcnt1_i32_b32 s4, s15
	s_add_i32 s4, s4, s5
	s_bcnt1_i32_b32 s5, s20
	v_writelane_b32 v252, s15, 43
	s_add_i32 s5, s5, s6
	s_bcnt1_i32_b32 s6, s21
	v_cmp_gt_u32_e64 s[14:15], v108, v12
	s_add_i32 s6, s6, s2
	s_bcnt1_i32_b32 s2, s14
	v_cmp_eq_u32_e64 s[16:17], v108, v12
	s_add_i32 s2, s2, s3
	v_writelane_b32 v252, s14, 44
	s_bcnt1_i32_b32 s3, s15
	s_add_i32 s3, s3, s4
	s_bcnt1_i32_b32 s4, s16
	v_writelane_b32 v252, s15, 45
	s_add_i32 s4, s4, s5
	s_bcnt1_i32_b32 s5, s17
	v_cmp_gt_u32_e64 s[14:15], v103, v12
	s_add_i32 s5, s5, s6
	s_bcnt1_i32_b32 s6, s14
	v_cmp_eq_u32_e64 s[88:89], v103, v12
	s_add_i32 s6, s6, s2
	v_writelane_b32 v252, s14, 46
	s_bcnt1_i32_b32 s2, s15
	s_add_i32 s2, s2, s3
	s_bcnt1_i32_b32 s3, s88
	v_writelane_b32 v252, s15, 47
	s_add_i32 s3, s3, s4
	s_bcnt1_i32_b32 s4, s89
	v_cmp_gt_u32_e64 s[14:15], v110, v12
	s_add_i32 s4, s4, s5
	s_bcnt1_i32_b32 s5, s14
	v_cmp_eq_u32_e64 s[80:81], v110, v12
	s_add_i32 s5, s5, s6
	v_writelane_b32 v252, s14, 48
	s_bcnt1_i32_b32 s6, s15
	s_add_i32 s6, s6, s2
	s_bcnt1_i32_b32 s2, s80
	v_writelane_b32 v252, s15, 49
	s_add_i32 s2, s2, s3
	s_bcnt1_i32_b32 s3, s81
	v_cmp_gt_u32_e64 s[14:15], v105, v12
; __global__ void __launch_bounds__(512, 2) mega_fwd(KArgs a) {
;     ...
; #pragma unroll
;                 for (int jj = 0; jj < 64; ++jj) {
;                     const unsigned long long bg = __ballot(key[jj] > tau), be = __ballot(key[jj] == tau);
;                     g0 += __popc((unsigned)bg); g1 += __popc((unsigned)(bg >> 32)); e0 += __popc((unsigned)be); e1 += __popc((unsigned)(be >> 32));
;                 }
	s_add_i32 s3, s3, s4
	s_bcnt1_i32_b32 s4, s14
	v_cmp_eq_u32_e64 s[70:71], v105, v12
	s_add_i32 s4, s4, s5
	v_writelane_b32 v252, s14, 50
	s_bcnt1_i32_b32 s5, s15
	s_add_i32 s5, s5, s6
	s_bcnt1_i32_b32 s6, s70
	v_writelane_b32 v252, s15, 51
	s_add_i32 s6, s6, s2
	s_bcnt1_i32_b32 s2, s71
	v_cmp_gt_u32_e64 s[14:15], v112, v12
	s_add_i32 s2, s2, s3
	s_bcnt1_i32_b32 s3, s14
	v_cmp_eq_u32_e64 s[66:67], v112, v12
	s_add_i32 s3, s3, s4
	v_writelane_b32 v252, s14, 52
	s_bcnt1_i32_b32 s4, s15
	s_add_i32 s4, s4, s5
	s_bcnt1_i32_b32 s5, s66
	v_writelane_b32 v252, s15, 53
	s_add_i32 s5, s5, s6
	s_bcnt1_i32_b32 s6, s67
	v_cmp_gt_u32_e64 s[14:15], v107, v12
	s_add_i32 s6, s6, s2
	s_bcnt1_i32_b32 s2, s14
	v_cmp_eq_u32_e64 s[62:63], v107, v12
	s_add_i32 s2, s2, s3
	v_writelane_b32 v252, s14, 54
	s_bcnt1_i32_b32 s3, s15
	s_add_i32 s3, s3, s4
	s_bcnt1_i32_b32 s4, s62
	v_writelane_b32 v252, s15, 55
	s_add_i32 s4, s4, s5
	s_bcnt1_i32_b32 s5, s63
	v_cmp_gt_u32_e64 s[14:15], v114, v12
	s_add_i32 s5, s5, s6
	s_bcnt1_i32_b32 s6, s14
	v_cmp_eq_u32_e64 s[58:59], v114, v12
	s_add_i32 s6, s6, s2
	v_writelane_b32 v252, s14, 56
	s_bcnt1_i32_b32 s2, s15
	s_add_i32 s2, s2, s3
	s_bcnt1_i32_b32 s3, s58
	v_writelane_b32 v252, s15, 57
	s_add_i32 s3, s3, s4
	s_bcnt1_i32_b32 s4, s59
	v_cmp_gt_u32_e64 s[14:15], v109, v12
	s_add_i32 s4, s4, s5
	s_bcnt1_i32_b32 s5, s14
	s_add_i32 s5, s5, s6
	v_writelane_b32 v252, s14, 58
	s_bcnt1_i32_b32 s6, s15
	v_cmp_eq_u32_e64 s[54:55], v109, v12
	s_add_i32 s6, s6, s2
	s_bcnt1_i32_b32 s2, s54
	v_writelane_b32 v252, s15, 59
	s_add_i32 s2, s2, s3
	s_bcnt1_i32_b32 s3, s55
	v_cmp_gt_u32_e64 s[14:15], v116, v12
	s_add_i32 s3, s3, s4
	s_bcnt1_i32_b32 s4, s14
	s_add_i32 s4, s4, s5
	v_writelane_b32 v252, s14, 60
	s_bcnt1_i32_b32 s5, s15
	v_cmp_eq_u32_e64 s[50:51], v116, v12
	s_add_i32 s5, s5, s6
	s_bcnt1_i32_b32 s6, s50
	v_writelane_b32 v252, s15, 61
	s_add_i32 s6, s6, s2
	s_bcnt1_i32_b32 s2, s51
	v_cmp_gt_u32_e64 s[14:15], v111, v12
	s_add_i32 s2, s2, s3
	s_bcnt1_i32_b32 s3, s14
	s_add_i32 s3, s3, s4
	v_writelane_b32 v252, s14, 62
	s_bcnt1_i32_b32 s4, s15
	v_cmp_eq_u32_e64 s[46:47], v111, v12
	s_add_i32 s4, s4, s5
	s_bcnt1_i32_b32 s5, s46
	v_writelane_b32 v252, s15, 63
	s_add_i32 s5, s5, s6
	s_bcnt1_i32_b32 s6, s47
	v_cmp_gt_u32_e64 s[14:15], v118, v12
	s_add_i32 s6, s6, s2
	s_bcnt1_i32_b32 s2, s14
	s_add_i32 s2, s2, s3
	v_writelane_b32 v255, s14, 0
	s_bcnt1_i32_b32 s3, s15
	v_cmp_eq_u32_e64 s[22:23], v118, v12
	s_add_i32 s3, s3, s4
	s_bcnt1_i32_b32 s4, s22
	v_writelane_b32 v255, s15, 1
	s_add_i32 s4, s4, s5
	s_bcnt1_i32_b32 s5, s23
	v_cmp_gt_u32_e64 s[14:15], v113, v12
	s_add_i32 s5, s5, s6
	s_bcnt1_i32_b32 s6, s14
	v_writelane_b32 v255, s14, 2
	s_add_i32 s6, s6, s2
	s_bcnt1_i32_b32 s2, s15
	v_writelane_b32 v255, s15, 3
	v_cmp_eq_u32_e64 s[14:15], v113, v12
	s_add_i32 s2, s2, s3
	s_bcnt1_i32_b32 s3, s14
	s_add_i32 s3, s3, s4
	s_bcnt1_i32_b32 s4, s15
	v_cmp_gt_u32_e64 s[96:97], v120, v12
	s_add_i32 s7, s4, s5
	s_bcnt1_i32_b32 s4, s96
	s_add_i32 s6, s4, s6
	v_writelane_b32 v255, s96, 4
	s_bcnt1_i32_b32 s4, s97
	s_add_i32 s2, s4, s2
	v_cmp_eq_u32_e64 s[4:5], v120, v12
	v_writelane_b32 v255, s97, 5
	s_bcnt1_i32_b32 s96, s4
	s_add_i32 s96, s96, s3
	s_bcnt1_i32_b32 s3, s5
	v_cmp_gt_u32_e32 vcc, v115, v12
	s_add_i32 s3, s3, s7
	s_bcnt1_i32_b32 s7, vcc_lo
	s_add_i32 s97, s7, s6
	v_writelane_b32 v255, vcc_lo, 6
	s_bcnt1_i32_b32 s6, vcc_hi
	s_add_i32 s2, s6, s2
	v_writelane_b32 v255, vcc_hi, 7
	v_cmp_eq_u32_e64 s[6:7], v115, v12
	s_bcnt1_i32_b32 vcc_lo, s6
	s_add_i32 vcc_lo, vcc_lo, s96
	v_writelane_b32 v255, s6, 8
	s_bcnt1_i32_b32 s96, s7
	s_add_i32 s3, s96, s3
	v_writelane_b32 v255, s7, 9
	v_cmp_gt_u32_e64 s[6:7], v122, v12
	s_bcnt1_i32_b32 s96, s6
	s_add_i32 vcc_hi, s96, s97
	v_writelane_b32 v255, s6, 10
	s_bcnt1_i32_b32 s96, s7
	s_add_i32 s2, s96, s2
	v_writelane_b32 v255, s7, 11
	v_cmp_eq_u32_e64 s[6:7], v122, v12
	s_bcnt1_i32_b32 s79, s6
	s_add_i32 s79, s79, vcc_lo
	s_bcnt1_i32_b32 vcc_lo, s7
	v_cmp_gt_u32_e64 s[96:97], v117, v12
	s_add_i32 vcc_lo, vcc_lo, s3
	s_bcnt1_i32_b32 s3, s96
	v_writelane_b32 v255, s96, 12
	s_add_i32 s3, s3, vcc_hi
	s_bcnt1_i32_b32 vcc_hi, s97
	v_writelane_b32 v255, s97, 13
	v_cmp_eq_u32_e64 s[96:97], v117, v12
	s_add_i32 vcc_hi, vcc_hi, s2
	s_bcnt1_i32_b32 s2, s96
	v_writelane_b32 v255, s96, 14
	s_add_i32 s2, s2, s79
	s_bcnt1_i32_b32 s79, s97
	v_writelane_b32 v255, s97, 15
	v_cmp_gt_u32_e64 s[96:97], v124, v12
	s_add_i32 s79, s79, vcc_lo
	s_bcnt1_i32_b32 vcc_lo, s96
	v_writelane_b32 v255, s96, 16
	s_add_i32 vcc_lo, vcc_lo, s3
	s_bcnt1_i32_b32 s3, s97
	v_writelane_b32 v255, s97, 17
	v_cmp_eq_u32_e64 s[96:97], v124, v12
	s_add_i32 s3, s3, vcc_hi
	s_bcnt1_i32_b32 vcc_hi, s96
	v_writelane_b32 v255, s96, 18
	s_add_i32 vcc_hi, vcc_hi, s2
	s_bcnt1_i32_b32 s2, s97
	v_writelane_b32 v255, s97, 19
	v_cmp_gt_u32_e64 s[96:97], v119, v12
	s_add_i32 s2, s2, s79
	s_bcnt1_i32_b32 s79, s96
	v_writelane_b32 v255, s96, 20
	s_add_i32 s79, s79, vcc_lo
	s_bcnt1_i32_b32 vcc_lo, s97
	v_writelane_b32 v255, s97, 21
	v_cmp_eq_u32_e64 s[96:97], v119, v12
	s_add_i32 vcc_lo, vcc_lo, s3
	s_bcnt1_i32_b32 s3, s96
	v_writelane_b32 v255, s96, 22
	s_add_i32 s3, s3, vcc_hi
	s_bcnt1_i32_b32 vcc_hi, s97
	v_writelane_b32 v255, s97, 23
	v_cmp_gt_u32_e64 s[96:97], v158, v12
	s_add_i32 vcc_hi, vcc_hi, s2
	s_bcnt1_i32_b32 s2, s96
	v_writelane_b32 v255, s96, 24
	s_add_i32 s2, s2, s79
	s_bcnt1_i32_b32 s79, s97
	v_writelane_b32 v255, s97, 25
	v_cmp_eq_u32_e64 s[96:97], v158, v12
	s_add_i32 s79, s79, vcc_lo
	s_bcnt1_i32_b32 vcc_lo, s96
	v_writelane_b32 v255, s96, 26
	s_add_i32 vcc_lo, vcc_lo, s3
	s_bcnt1_i32_b32 s3, s97
	v_writelane_b32 v255, s97, 27
	v_cmp_gt_u32_e64 s[96:97], v121, v12
; __global__ void __launch_bounds__(512, 2) mega_fwd(KArgs a) {
;     ...
; #pragma unroll
;                 for (int jj = 0; jj < 64; ++jj) {
;                     const unsigned long long bg = __ballot(key[jj] > tau), be = __ballot(key[jj] == tau);
;                     g0 += __popc((unsigned)bg); g1 += __popc((unsigned)(bg >> 32)); e0 += __popc((unsigned)be); e1 += __popc((unsigned)(be >> 32));
;                 }
	s_add_i32 s3, s3, vcc_hi
	s_bcnt1_i32_b32 vcc_hi, s96
	v_writelane_b32 v255, s96, 28
	s_add_i32 vcc_hi, vcc_hi, s2
	s_bcnt1_i32_b32 s2, s97
	v_writelane_b32 v255, s97, 29
	v_cmp_eq_u32_e64 s[96:97], v121, v12
	s_add_i32 s2, s2, s79
	s_bcnt1_i32_b32 s79, s96
	v_writelane_b32 v255, s96, 30
	s_add_i32 s79, s79, vcc_lo
	s_bcnt1_i32_b32 vcc_lo, s97
	v_writelane_b32 v255, s97, 31
	v_cmp_gt_u32_e64 s[96:97], v160, v12
	s_add_i32 vcc_lo, vcc_lo, s3
	s_bcnt1_i32_b32 s3, s96
	v_writelane_b32 v255, s96, 32
	s_add_i32 s3, s3, vcc_hi
	s_bcnt1_i32_b32 vcc_hi, s97
	v_writelane_b32 v255, s97, 33
	v_cmp_eq_u32_e64 s[96:97], v160, v12
	s_add_i32 vcc_hi, vcc_hi, s2
	s_bcnt1_i32_b32 s2, s96
	v_writelane_b32 v255, s96, 34
	s_add_i32 s2, s2, s79
	s_bcnt1_i32_b32 s79, s97
	v_writelane_b32 v255, s97, 35
	v_cmp_gt_u32_e64 s[96:97], v123, v12
	s_add_i32 s79, s79, vcc_lo
	s_bcnt1_i32_b32 vcc_lo, s96
	v_writelane_b32 v255, s96, 36
	s_add_i32 vcc_lo, vcc_lo, s3
	s_bcnt1_i32_b32 s3, s97
	v_writelane_b32 v255, s97, 37
	v_cmp_eq_u32_e64 s[96:97], v123, v12
	s_add_i32 s3, s3, vcc_hi
	s_bcnt1_i32_b32 vcc_hi, s96
	v_writelane_b32 v255, s96, 38
	s_add_i32 vcc_hi, vcc_hi, s2
	s_bcnt1_i32_b32 s2, s97
	v_writelane_b32 v255, s97, 39
	v_cmp_gt_u32_e64 s[96:97], v162, v12
	s_add_i32 s2, s2, s79
	s_bcnt1_i32_b32 s79, s96
	v_writelane_b32 v255, s96, 40
	s_add_i32 s79, s79, vcc_lo
	s_bcnt1_i32_b32 vcc_lo, s97
	v_writelane_b32 v255, s97, 41
	v_cmp_eq_u32_e64 s[96:97], v162, v12
	s_add_i32 vcc_lo, vcc_lo, s3
	s_bcnt1_i32_b32 s3, s96
	v_writelane_b32 v255, s96, 42
	s_add_i32 s3, s3, vcc_hi
	s_bcnt1_i32_b32 vcc_hi, s97
	v_writelane_b32 v255, s97, 43
	v_cmp_gt_u32_e64 s[96:97], v125, v12
	s_add_i32 vcc_hi, vcc_hi, s2
	s_bcnt1_i32_b32 s2, s96
	v_writelane_b32 v255, s96, 44
	s_add_i32 s2, s2, s79
	s_bcnt1_i32_b32 s79, s97
	v_writelane_b32 v255, s97, 45
	v_cmp_eq_u32_e64 s[96:97], v125, v12
	s_add_i32 s79, s79, vcc_lo
	s_bcnt1_i32_b32 vcc_lo, s96
	v_writelane_b32 v255, s96, 46
	s_add_i32 vcc_lo, vcc_lo, s3
	s_bcnt1_i32_b32 s3, s97
	v_writelane_b32 v255, s97, 47
	v_cmp_gt_u32_e64 s[96:97], v164, v12
	s_add_i32 s3, s3, vcc_hi
	s_bcnt1_i32_b32 vcc_hi, s96
	v_writelane_b32 v255, s96, 48
	s_add_i32 vcc_hi, vcc_hi, s2
	s_bcnt1_i32_b32 s2, s97
	v_writelane_b32 v255, s97, 49
	v_cmp_eq_u32_e64 s[96:97], v164, v12
	s_add_i32 s2, s2, s79
	s_bcnt1_i32_b32 s79, s96
	v_writelane_b32 v255, s96, 50
	s_add_i32 s79, s79, vcc_lo
	s_bcnt1_i32_b32 vcc_lo, s97
	v_writelane_b32 v255, s97, 51
	v_cmp_gt_u32_e64 s[96:97], v159, v12
	s_add_i32 vcc_lo, vcc_lo, s3
	s_bcnt1_i32_b32 s3, s96
	v_writelane_b32 v255, s96, 52
	s_add_i32 s3, s3, vcc_hi
	s_bcnt1_i32_b32 vcc_hi, s97
	v_writelane_b32 v255, s97, 53
	v_cmp_eq_u32_e64 s[96:97], v159, v12
	s_add_i32 vcc_hi, vcc_hi, s2
	s_bcnt1_i32_b32 s2, s96
	v_writelane_b32 v255, s96, 54
	s_add_i32 s2, s2, s79
	s_bcnt1_i32_b32 s79, s97
	v_writelane_b32 v255, s97, 55
	v_cmp_gt_u32_e64 s[96:97], v168, v12
	s_add_i32 s79, s79, vcc_lo
	s_bcnt1_i32_b32 vcc_lo, s96
	v_writelane_b32 v255, s96, 56
	s_add_i32 vcc_lo, vcc_lo, s3
	s_bcnt1_i32_b32 s3, s97
	v_writelane_b32 v255, s97, 57
	v_cmp_eq_u32_e64 s[96:97], v168, v12
	s_add_i32 s3, s3, vcc_hi
	s_bcnt1_i32_b32 vcc_hi, s96
	v_writelane_b32 v255, s96, 58
	s_add_i32 vcc_hi, vcc_hi, s2
	s_bcnt1_i32_b32 s2, s97
	v_writelane_b32 v255, s97, 59
	v_cmp_gt_u32_e64 s[96:97], v161, v12
	s_add_i32 s2, s2, s79
	s_bcnt1_i32_b32 s79, s96
	v_writelane_b32 v255, s96, 60
	s_add_i32 s79, s79, vcc_lo
	s_bcnt1_i32_b32 vcc_lo, s97
	v_writelane_b32 v255, s97, 61
	v_cmp_eq_u32_e64 s[96:97], v161, v12
	s_add_i32 vcc_lo, vcc_lo, s3
	s_bcnt1_i32_b32 s3, s96
	v_writelane_b32 v255, s96, 62
	s_add_i32 s3, s3, vcc_hi
	s_bcnt1_i32_b32 vcc_hi, s97
	v_writelane_b32 v255, s97, 63
	v_cmp_gt_u32_e64 s[96:97], v170, v12
	s_add_i32 vcc_hi, vcc_hi, s2
	s_bcnt1_i32_b32 s2, s96
	v_writelane_b32 v253, s96, 0
	s_add_i32 s2, s2, s79
	s_bcnt1_i32_b32 s79, s97
	v_writelane_b32 v253, s97, 1
	v_cmp_eq_u32_e64 s[96:97], v170, v12
	s_add_i32 s79, s79, vcc_lo
	s_bcnt1_i32_b32 vcc_lo, s96
	v_writelane_b32 v253, s96, 2
	s_add_i32 vcc_lo, vcc_lo, s3
	s_bcnt1_i32_b32 s3, s97
	v_writelane_b32 v253, s97, 3
	v_cmp_gt_u32_e64 s[96:97], v163, v12
	s_add_i32 s3, s3, vcc_hi
	s_bcnt1_i32_b32 vcc_hi, s96
	v_writelane_b32 v253, s96, 4
	s_add_i32 vcc_hi, vcc_hi, s2
	s_bcnt1_i32_b32 s2, s97
	v_writelane_b32 v253, s97, 5
	v_cmp_eq_u32_e64 s[96:97], v163, v12
	s_add_i32 s2, s2, s79
	s_bcnt1_i32_b32 s79, s96
	v_writelane_b32 v253, s96, 6
	s_add_i32 s79, s79, vcc_lo
	s_bcnt1_i32_b32 vcc_lo, s97
	v_writelane_b32 v253, s97, 7
	v_cmp_gt_u32_e64 s[96:97], v172, v12
	s_add_i32 vcc_lo, vcc_lo, s3
	s_bcnt1_i32_b32 s3, s96
	v_writelane_b32 v253, s96, 8
	s_add_i32 s3, s3, vcc_hi
	s_bcnt1_i32_b32 vcc_hi, s97
	v_writelane_b32 v253, s97, 9
	v_cmp_eq_u32_e64 s[96:97], v172, v12
	s_add_i32 vcc_hi, vcc_hi, s2
	s_bcnt1_i32_b32 s2, s96
	v_writelane_b32 v253, s96, 10
	s_add_i32 s2, s2, s79
	s_bcnt1_i32_b32 s79, s97
	v_writelane_b32 v253, s97, 11
	v_cmp_gt_u32_e64 s[96:97], v165, v12
	s_add_i32 s79, s79, vcc_lo
	s_bcnt1_i32_b32 vcc_lo, s96
	v_writelane_b32 v253, s96, 12
	s_add_i32 vcc_lo, vcc_lo, s3
	s_bcnt1_i32_b32 s3, s97
	v_writelane_b32 v253, s97, 13
	v_cmp_eq_u32_e64 s[96:97], v165, v12
	s_add_i32 s3, s3, vcc_hi
	s_bcnt1_i32_b32 vcc_hi, s96
	v_writelane_b32 v253, s96, 14
	s_add_i32 vcc_hi, vcc_hi, s2
	s_bcnt1_i32_b32 s2, s97
	v_writelane_b32 v253, s97, 15
	v_cmp_gt_u32_e64 s[96:97], v174, v12
	s_add_i32 s2, s2, s79
	s_bcnt1_i32_b32 s79, s96
	v_writelane_b32 v253, s96, 16
	s_add_i32 s79, s79, vcc_lo
	s_bcnt1_i32_b32 vcc_lo, s97
	v_writelane_b32 v253, s97, 17
	v_cmp_eq_u32_e64 s[96:97], v174, v12
	s_add_i32 vcc_lo, vcc_lo, s3
; __global__ void __launch_bounds__(512, 2) mega_fwd(KArgs a) {
;     ...
; #pragma unroll
;                 for (int jj = 0; jj < 64; ++jj) {
;                     const unsigned long long bg = __ballot(key[jj] > tau), be = __ballot(key[jj] == tau);
;                     g0 += __popc((unsigned)bg); g1 += __popc((unsigned)(bg >> 32)); e0 += __popc((unsigned)be); e1 += __popc((unsigned)(be >> 32));
;                 }
	s_bcnt1_i32_b32 s3, s96
	v_writelane_b32 v253, s96, 18
	s_add_i32 s3, s3, vcc_hi
	s_bcnt1_i32_b32 vcc_hi, s97
	v_writelane_b32 v253, s97, 19
	v_cmp_gt_u32_e64 s[96:97], v169, v12
	s_add_i32 vcc_hi, vcc_hi, s2
	s_bcnt1_i32_b32 s2, s96
	v_writelane_b32 v253, s96, 20
	s_add_i32 s2, s2, s79
	s_bcnt1_i32_b32 s79, s97
	v_writelane_b32 v253, s97, 21
	v_cmp_eq_u32_e64 s[96:97], v169, v12
	s_add_i32 s79, s79, vcc_lo
	s_bcnt1_i32_b32 vcc_lo, s96
	v_writelane_b32 v253, s96, 22
	s_add_i32 vcc_lo, vcc_lo, s3
	s_bcnt1_i32_b32 s3, s97
	v_writelane_b32 v253, s97, 23
	v_cmp_gt_u32_e64 s[96:97], v176, v12
	s_add_i32 s3, s3, vcc_hi
	s_bcnt1_i32_b32 vcc_hi, s96
	v_writelane_b32 v253, s96, 24
	s_add_i32 vcc_hi, vcc_hi, s2
	s_bcnt1_i32_b32 s2, s97
	v_writelane_b32 v253, s97, 25
	v_cmp_eq_u32_e64 s[96:97], v176, v12
	s_add_i32 s2, s2, s79
	s_bcnt1_i32_b32 s79, s96
	v_writelane_b32 v253, s96, 26
	s_add_i32 s79, s79, vcc_lo
	s_bcnt1_i32_b32 vcc_lo, s97
	v_writelane_b32 v253, s97, 27
	v_cmp_gt_u32_e64 s[96:97], v171, v12
	s_add_i32 vcc_lo, vcc_lo, s3
	s_bcnt1_i32_b32 s3, s96
	v_writelane_b32 v253, s96, 28
	s_add_i32 s3, s3, vcc_hi
	s_bcnt1_i32_b32 vcc_hi, s97
	v_writelane_b32 v253, s97, 29
	v_cmp_eq_u32_e64 s[96:97], v171, v12
	s_add_i32 vcc_hi, vcc_hi, s2
	s_bcnt1_i32_b32 s2, s96
	v_writelane_b32 v253, s96, 30
	s_add_i32 s2, s2, s79
	s_bcnt1_i32_b32 s79, s97
	v_writelane_b32 v253, s97, 31
	v_cmp_gt_u32_e64 s[96:97], v178, v12
	s_add_i32 s79, s79, vcc_lo
	s_bcnt1_i32_b32 vcc_lo, s96
	v_writelane_b32 v253, s96, 32
	s_add_i32 vcc_lo, vcc_lo, s3
	s_bcnt1_i32_b32 s3, s97
	v_writelane_b32 v253, s97, 33
	v_cmp_eq_u32_e64 s[96:97], v178, v12
	s_add_i32 s3, s3, vcc_hi
	s_bcnt1_i32_b32 vcc_hi, s96
	v_writelane_b32 v253, s96, 34
	s_add_i32 vcc_hi, vcc_hi, s2
	s_bcnt1_i32_b32 s2, s97
	v_writelane_b32 v253, s97, 35
	v_cmp_gt_u32_e64 s[96:97], v173, v12
	s_add_i32 s2, s2, s79
	s_bcnt1_i32_b32 s79, s96
	v_writelane_b32 v253, s96, 36
	s_add_i32 s79, s79, vcc_lo
	s_bcnt1_i32_b32 vcc_lo, s97
	v_writelane_b32 v253, s97, 37
	v_cmp_eq_u32_e64 s[96:97], v173, v12
	s_add_i32 vcc_lo, vcc_lo, s3
	s_bcnt1_i32_b32 s3, s96
	v_writelane_b32 v253, s96, 38
	s_add_i32 s3, s3, vcc_hi
	s_bcnt1_i32_b32 vcc_hi, s97
	v_writelane_b32 v253, s97, 39
	v_cmp_gt_u32_e64 s[96:97], v180, v12
	s_add_i32 vcc_hi, vcc_hi, s2
	s_bcnt1_i32_b32 s2, s96
	v_writelane_b32 v253, s96, 40
	s_add_i32 s2, s2, s79
	s_bcnt1_i32_b32 s79, s97
	v_writelane_b32 v253, s97, 41
	v_cmp_eq_u32_e64 s[96:97], v180, v12
	s_add_i32 s79, s79, vcc_lo
	s_bcnt1_i32_b32 vcc_lo, s96
	v_writelane_b32 v253, s96, 42
	s_add_i32 vcc_lo, vcc_lo, s3
	s_bcnt1_i32_b32 s3, s97
	v_writelane_b32 v253, s97, 43
	v_cmp_gt_u32_e64 s[96:97], v175, v12
	s_add_i32 s3, s3, vcc_hi
	s_bcnt1_i32_b32 vcc_hi, s96
	v_writelane_b32 v253, s96, 44
	s_add_i32 vcc_hi, vcc_hi, s2
	s_bcnt1_i32_b32 s2, s97
	v_writelane_b32 v253, s97, 45
	v_cmp_eq_u32_e64 s[96:97], v175, v12
	s_add_i32 s2, s2, s79
	s_bcnt1_i32_b32 s79, s96
	v_writelane_b32 v253, s96, 46
	s_add_i32 s79, s79, vcc_lo
	s_bcnt1_i32_b32 vcc_lo, s97
	v_writelane_b32 v253, s97, 47
	v_cmp_gt_u32_e64 s[96:97], v182, v12
	s_add_i32 vcc_lo, vcc_lo, s3
	s_bcnt1_i32_b32 s3, s96
	v_writelane_b32 v253, s96, 48
	s_add_i32 s3, s3, vcc_hi
	s_bcnt1_i32_b32 vcc_hi, s97
	v_writelane_b32 v253, s97, 49
	v_cmp_eq_u32_e64 s[96:97], v182, v12
	s_add_i32 vcc_hi, vcc_hi, s2
	s_bcnt1_i32_b32 s2, s96
	v_writelane_b32 v253, s96, 50
	s_add_i32 s2, s2, s79
	s_bcnt1_i32_b32 s79, s97
	v_writelane_b32 v253, s97, 51
	v_cmp_gt_u32_e64 s[96:97], v177, v12
	s_add_i32 s79, s79, vcc_lo
	s_bcnt1_i32_b32 vcc_lo, s96
	v_writelane_b32 v253, s96, 52
	s_add_i32 vcc_lo, vcc_lo, s3
	s_bcnt1_i32_b32 s3, s97
	v_writelane_b32 v253, s97, 53
	v_cmp_eq_u32_e64 s[96:97], v177, v12
	s_add_i32 s3, s3, vcc_hi
	s_bcnt1_i32_b32 vcc_hi, s96
	v_writelane_b32 v253, s96, 54
	s_add_i32 vcc_hi, vcc_hi, s2
	s_bcnt1_i32_b32 s2, s97
	v_writelane_b32 v253, s97, 55
	v_cmp_gt_u32_e64 s[96:97], v184, v12
	s_add_i32 s2, s2, s79
	s_bcnt1_i32_b32 s79, s96
	v_writelane_b32 v253, s96, 56
	s_add_i32 s79, s79, vcc_lo
	s_bcnt1_i32_b32 vcc_lo, s97
	v_writelane_b32 v253, s97, 57
	v_cmp_eq_u32_e64 s[96:97], v184, v12
	s_add_i32 vcc_lo, vcc_lo, s3
	s_bcnt1_i32_b32 s3, s96
	v_writelane_b32 v253, s96, 58
	s_add_i32 s3, s3, vcc_hi
	s_bcnt1_i32_b32 vcc_hi, s97
	v_writelane_b32 v253, s97, 59
	v_cmp_gt_u32_e64 s[96:97], v179, v12
	s_add_i32 vcc_hi, vcc_hi, s2
	s_bcnt1_i32_b32 s2, s96
	v_writelane_b32 v253, s96, 60
	s_add_i32 s2, s2, s79
	s_bcnt1_i32_b32 s79, s97
	v_writelane_b32 v253, s97, 61
	v_cmp_eq_u32_e64 s[96:97], v179, v12
	s_add_i32 s79, s79, vcc_lo
	s_bcnt1_i32_b32 vcc_lo, s96
	v_writelane_b32 v253, s96, 62
	s_add_i32 vcc_lo, vcc_lo, s3
	s_bcnt1_i32_b32 s3, s97
	v_writelane_b32 v253, s97, 63
	v_cmp_gt_u32_e64 s[96:97], v186, v12
	s_add_i32 s3, s3, vcc_hi
	s_bcnt1_i32_b32 vcc_hi, s96
	v_writelane_b32 v254, s96, 0
	s_add_i32 vcc_hi, vcc_hi, s2
	s_bcnt1_i32_b32 s2, s97
	v_writelane_b32 v254, s97, 1
	v_cmp_eq_u32_e64 s[96:97], v186, v12
	s_add_i32 s2, s2, s79
	s_bcnt1_i32_b32 s79, s96
	v_writelane_b32 v254, s96, 2
	s_add_i32 s79, s79, vcc_lo
	s_bcnt1_i32_b32 vcc_lo, s97
	v_writelane_b32 v254, s97, 3
	v_cmp_gt_u32_e64 s[96:97], v181, v12
	s_add_i32 vcc_lo, vcc_lo, s3
	s_bcnt1_i32_b32 s3, s96
	v_writelane_b32 v254, s96, 4
	s_add_i32 s3, s3, vcc_hi
	s_bcnt1_i32_b32 vcc_hi, s97
	v_writelane_b32 v254, s97, 5
	v_cmp_eq_u32_e64 s[96:97], v181, v12
	s_add_i32 vcc_hi, vcc_hi, s2
	s_bcnt1_i32_b32 s2, s96
	v_writelane_b32 v254, s96, 6
	s_add_i32 s2, s2, s79
	s_bcnt1_i32_b32 s79, s97
	v_writelane_b32 v254, s97, 7
	v_cmp_gt_u32_e64 s[96:97], v188, v12
	s_add_i32 s79, s79, vcc_lo
	s_bcnt1_i32_b32 vcc_lo, s96
; __global__ void __launch_bounds__(512, 2) mega_fwd(KArgs a) {
;     ...
;                 const int cgt = (lane < 32) ? g0 : g1, ceq = (lane < 32) ? e0 : e1;
;                 const int need_eq = all_valid ? (1 << 20) : 256 - cgt;
;                 const bool ties = (!all_valid) && (ceq > need_eq);
;                 unsigned w0 = 0u, w1 = 0u;
;                 if (__ballot(ties) == 0ull) {
; #pragma unroll
;                     for (int jj = 0; jj < 64; ++jj) {
;                         const unsigned long long bm = __ballot(key[jj] >= tau);
;                         if (lane == 0) { wscr[jj] = (unsigned)bm; wscr[64 + jj] = (unsigned)(bm >> 32); }
;                     }
;                 } else {
;                     int running = 0;
; #pragma unroll
;                     for (int jj = 0; jj < 64; ++jj) {
;                         const bool e = key[jj] == tau;
;                         const unsigned long long be = __ballot(e);
;                         const unsigned hb = (unsigned)(be >> (32 * qs));
;                         const int rank = running + __popc(hb & ((1u << (lane & 31)) - 1u));
;                         running += __popc(hb);
;                         const bool sel = (key[jj] > tau) || (e && rank < need_eq);
;                         const unsigned long long bm = __ballot(sel);
;                         if (lane == 0) { wscr[jj] = (unsigned)bm; wscr[64 + jj] = (unsigned)(bm >> 32); }
	v_writelane_b32 v254, s96, 8
	s_add_i32 vcc_lo, vcc_lo, s3
	s_bcnt1_i32_b32 s3, s97
	v_writelane_b32 v254, s97, 9
	v_cmp_eq_u32_e64 s[96:97], v188, v12
	s_add_i32 s3, s3, vcc_hi
	s_bcnt1_i32_b32 vcc_hi, s96
	v_writelane_b32 v254, s96, 10
	s_add_i32 vcc_hi, vcc_hi, s2
	s_bcnt1_i32_b32 s2, s97
	v_writelane_b32 v254, s97, 11
	v_cmp_gt_u32_e64 s[96:97], v183, v12
	s_add_i32 s2, s2, s79
	s_bcnt1_i32_b32 s79, s96
	v_writelane_b32 v254, s96, 12
	s_add_i32 s79, s79, vcc_lo
	s_bcnt1_i32_b32 vcc_lo, s97
	v_writelane_b32 v254, s97, 13
	v_cmp_eq_u32_e64 s[96:97], v183, v12
	s_add_i32 vcc_lo, vcc_lo, s3
	s_bcnt1_i32_b32 s3, s96
	v_writelane_b32 v254, s96, 14
	s_add_i32 s3, s3, vcc_hi
	s_bcnt1_i32_b32 vcc_hi, s97
	v_writelane_b32 v254, s97, 15
	v_cmp_gt_u32_e64 s[96:97], v190, v12
	s_add_i32 vcc_hi, vcc_hi, s2
	s_bcnt1_i32_b32 s2, s96
	v_writelane_b32 v254, s96, 16
	s_add_i32 s2, s2, s79
	s_bcnt1_i32_b32 s79, s97
	v_writelane_b32 v254, s97, 17
	v_cmp_eq_u32_e64 s[96:97], v190, v12
	s_add_i32 s79, s79, vcc_lo
	s_bcnt1_i32_b32 vcc_lo, s96
	v_writelane_b32 v254, s96, 18
	s_add_i32 vcc_lo, vcc_lo, s3
	s_bcnt1_i32_b32 s3, s97
	v_writelane_b32 v254, s97, 19
	v_cmp_gt_u32_e64 s[96:97], v185, v12
	s_add_i32 s3, s3, vcc_hi
	s_bcnt1_i32_b32 vcc_hi, s96
	v_writelane_b32 v254, s96, 20
	s_add_i32 s2, vcc_hi, s2
	s_bcnt1_i32_b32 vcc_hi, s97
	v_writelane_b32 v254, s97, 21
	v_cmp_eq_u32_e64 s[96:97], v185, v12
	s_add_i32 s79, vcc_hi, s79
	s_bcnt1_i32_b32 vcc_hi, s96
	s_add_i32 vcc_lo, vcc_hi, vcc_lo
	s_bcnt1_i32_b32 vcc_hi, s97
	s_add_i32 s3, vcc_hi, s3
	v_mov_b32_e32 v10, s79
	v_mov_b32_e32 v11, s2
	v_mov_b32_e32 v13, s3
	v_mov_b32_e32 v14, vcc_lo
	v_cndmask_b32_e64 v10, v10, v11, s[12:13]
	v_cndmask_b32_e64 v11, v13, v14, s[12:13]
	v_sub_u32_e32 v10, 0x100, v10
	v_mov_b32_e32 v13, 0x100000
	v_cndmask_b32_e64 v13, v10, v13, s[86:87]
	s_xor_b64 s[2:3], s[86:87], -1
	v_cmp_gt_i32_e32 vcc, v11, v13
	s_and_b64 s[2:3], s[2:3], vcc
	v_cndmask_b32_e64 v10, 0, 1, s[2:3]
	s_mov_b64 s[2:3], -1
	v_cmp_ne_u32_e32 vcc, 0, v10
	v_readlane_b32 s79, v252, 36
	s_cbranch_vccz .LBB0_3695
	v_cndmask_b32_e64 v10, 0, 1, s[74:75]
	v_cmp_ne_u32_e32 vcc, 0, v10
	s_nop 1
	v_lshrrev_b64 v[10:11], v38, vcc
	v_and_b32_e32 v11, v10, v208
	v_bcnt_u32_b32 v11, v11, 0
	v_cmp_lt_i32_e32 vcc, v11, v13
	s_and_b64 s[2:3], s[74:75], vcc
	s_or_b64 s[2:3], s[84:85], s[2:3]
	v_cndmask_b32_e64 v11, 0, 1, s[2:3]
	v_cmp_ne_u32_e32 vcc, 0, v11
	s_and_saveexec_b64 s[74:75], s[8:9]
	v_mov_b32_e32 v11, s79
	v_mov_b32_e32 v14, vcc_lo
	v_mov_b32_e32 v15, vcc_hi
	ds_write2st64_b32 v11, v14, v15 offset1:1
	s_or_b64 exec, exec, s[74:75]
	v_bcnt_u32_b32 v14, v10, 0
	v_cndmask_b32_e64 v10, 0, 1, s[72:73]
	v_cmp_ne_u32_e32 vcc, 0, v10
	s_nop 1
	v_lshrrev_b64 v[10:11], v38, vcc
	v_and_b32_e32 v11, v10, v208
	v_bcnt_u32_b32 v11, v11, v14
	v_cmp_lt_i32_e32 vcc, v11, v13
	s_and_b64 s[2:3], s[72:73], vcc
	s_or_b64 s[2:3], s[76:77], s[2:3]
	v_cndmask_b32_e64 v11, 0, 1, s[2:3]
	v_cmp_ne_u32_e32 vcc, 0, v11
	s_and_saveexec_b64 s[72:73], s[8:9]
	v_mov_b32_e32 v11, s79
	v_mov_b32_e32 v15, vcc_lo
	v_mov_b32_e32 v16, vcc_hi
	ds_write2_b32 v11, v15, v16 offset0:1 offset1:65
	s_or_b64 exec, exec, s[72:73]
	v_bcnt_u32_b32 v14, v10, v14
	v_cndmask_b32_e64 v10, 0, 1, s[64:65]
	v_cmp_ne_u32_e32 vcc, 0, v10
	s_nop 1
	v_lshrrev_b64 v[10:11], v38, vcc
	v_and_b32_e32 v11, v10, v208
	v_bcnt_u32_b32 v11, v11, v14
	v_cmp_lt_i32_e32 vcc, v11, v13
	s_and_b64 s[2:3], s[64:65], vcc
	s_or_b64 s[2:3], s[68:69], s[2:3]
	v_cndmask_b32_e64 v11, 0, 1, s[2:3]
	v_cmp_ne_u32_e32 vcc, 0, v11
	s_and_saveexec_b64 s[64:65], s[8:9]
	v_mov_b32_e32 v11, s79
	v_mov_b32_e32 v15, vcc_lo
	v_mov_b32_e32 v16, vcc_hi
	ds_write2_b32 v11, v15, v16 offset0:2 offset1:66
	s_or_b64 exec, exec, s[64:65]
	v_bcnt_u32_b32 v14, v10, v14
	v_cndmask_b32_e64 v10, 0, 1, s[56:57]
	v_cmp_ne_u32_e32 vcc, 0, v10
	s_nop 1
	v_lshrrev_b64 v[10:11], v38, vcc
	v_and_b32_e32 v11, v10, v208
	v_bcnt_u32_b32 v11, v11, v14
	v_cmp_lt_i32_e32 vcc, v11, v13
	s_and_b64 s[2:3], s[56:57], vcc
	s_or_b64 s[2:3], s[60:61], s[2:3]
	v_cndmask_b32_e64 v11, 0, 1, s[2:3]
	v_cmp_ne_u32_e32 vcc, 0, v11
	s_and_saveexec_b64 s[56:57], s[8:9]
	v_mov_b32_e32 v11, s79
	v_mov_b32_e32 v15, vcc_lo
	v_mov_b32_e32 v16, vcc_hi
	ds_write2_b32 v11, v15, v16 offset0:3 offset1:67
	s_or_b64 exec, exec, s[56:57]
	v_bcnt_u32_b32 v14, v10, v14
	v_cndmask_b32_e64 v10, 0, 1, s[52:53]
	v_cmp_ne_u32_e32 vcc, 0, v10
	s_nop 1
	v_lshrrev_b64 v[10:11], v38, vcc
	v_and_b32_e32 v11, v10, v208
	v_bcnt_u32_b32 v11, v11, v14
	v_cmp_lt_i32_e32 vcc, v11, v13
	s_and_b64 s[2:3], s[52:53], vcc
	s_or_b64 s[2:3], s[48:49], s[2:3]
	v_cndmask_b32_e64 v11, 0, 1, s[2:3]
	v_cmp_ne_u32_e32 vcc, 0, v11
	s_and_saveexec_b64 s[48:49], s[8:9]
	v_mov_b32_e32 v11, s79
	v_mov_b32_e32 v15, vcc_lo
	v_mov_b32_e32 v16, vcc_hi
	ds_write2_b32 v11, v15, v16 offset0:4 offset1:68
	s_or_b64 exec, exec, s[48:49]
	v_bcnt_u32_b32 v14, v10, v14
	v_cndmask_b32_e64 v10, 0, 1, s[44:45]
	v_cmp_ne_u32_e32 vcc, 0, v10
	s_nop 1
	v_lshrrev_b64 v[10:11], v38, vcc
	v_and_b32_e32 v11, v10, v208
	v_bcnt_u32_b32 v11, v11, v14
	v_cmp_lt_i32_e32 vcc, v11, v13
	s_and_b64 s[2:3], s[44:45], vcc
	s_or_b64 s[2:3], s[40:41], s[2:3]
	v_cndmask_b32_e64 v11, 0, 1, s[2:3]
	v_cmp_ne_u32_e32 vcc, 0, v11
	s_and_saveexec_b64 s[40:41], s[8:9]
	v_mov_b32_e32 v11, s79
	v_mov_b32_e32 v15, vcc_lo
	v_mov_b32_e32 v16, vcc_hi
	ds_write2_b32 v11, v15, v16 offset0:5 offset1:69
	s_or_b64 exec, exec, s[40:41]
	v_bcnt_u32_b32 v14, v10, v14
	v_cndmask_b32_e64 v10, 0, 1, s[36:37]
	v_cmp_ne_u32_e32 vcc, 0, v10
	s_nop 1
	v_lshrrev_b64 v[10:11], v38, vcc
	v_and_b32_e32 v11, v10, v208
	v_bcnt_u32_b32 v11, v11, v14
; __global__ void __launch_bounds__(512, 2) mega_fwd(KArgs a) {
;     ...
;                     int running = 0;
; #pragma unroll
;                     for (int jj = 0; jj < 64; ++jj) {
;                         const bool e = key[jj] == tau;
;                         const unsigned long long be = __ballot(e);
;                         const unsigned hb = (unsigned)(be >> (32 * qs));
;                         const int rank = running + __popc(hb & ((1u << (lane & 31)) - 1u));
;                         running += __popc(hb);
;                         const bool sel = (key[jj] > tau) || (e && rank < need_eq);
;                         const unsigned long long bm = __ballot(sel);
;                         if (lane == 0) { wscr[jj] = (unsigned)bm; wscr[64 + jj] = (unsigned)(bm >> 32); }
;                     }
	v_cmp_lt_i32_e32 vcc, v11, v13
	s_and_b64 s[2:3], s[36:37], vcc
	s_or_b64 s[2:3], s[30:31], s[2:3]
	v_cndmask_b32_e64 v11, 0, 1, s[2:3]
	v_cmp_ne_u32_e32 vcc, 0, v11
	s_and_saveexec_b64 s[30:31], s[8:9]
	v_mov_b32_e32 v11, s79
	v_mov_b32_e32 v15, vcc_lo
	v_mov_b32_e32 v16, vcc_hi
	ds_write2_b32 v11, v15, v16 offset0:6 offset1:70
	s_or_b64 exec, exec, s[30:31]
	v_bcnt_u32_b32 v14, v10, v14
	v_cndmask_b32_e64 v10, 0, 1, s[26:27]
	v_cmp_ne_u32_e32 vcc, 0, v10
	s_nop 1
	v_lshrrev_b64 v[10:11], v38, vcc
	v_and_b32_e32 v11, v10, v208
	v_bcnt_u32_b32 v11, v11, v14
	v_cmp_lt_i32_e32 vcc, v11, v13
	s_and_b64 s[2:3], s[26:27], vcc
	s_or_b64 s[2:3], s[42:43], s[2:3]
	v_cndmask_b32_e64 v11, 0, 1, s[2:3]
	v_cmp_ne_u32_e32 vcc, 0, v11
	s_and_saveexec_b64 s[26:27], s[8:9]
	v_mov_b32_e32 v11, s79
	v_mov_b32_e32 v15, vcc_lo
	v_mov_b32_e32 v16, vcc_hi
	ds_write2_b32 v11, v15, v16 offset0:7 offset1:71
	s_or_b64 exec, exec, s[26:27]
	v_bcnt_u32_b32 v14, v10, v14
	v_cndmask_b32_e64 v10, 0, 1, s[18:19]
	v_cmp_ne_u32_e32 vcc, 0, v10
	s_nop 1
	v_lshrrev_b64 v[10:11], v38, vcc
	v_and_b32_e32 v11, v10, v208
	v_bcnt_u32_b32 v11, v11, v14
	v_cmp_lt_i32_e32 vcc, v11, v13
	s_and_b64 s[2:3], s[18:19], vcc
	s_or_b64 s[2:3], s[38:39], s[2:3]
	v_cndmask_b32_e64 v11, 0, 1, s[2:3]
	v_cmp_ne_u32_e32 vcc, 0, v11
	s_and_saveexec_b64 s[18:19], s[8:9]
	v_mov_b32_e32 v11, s79
	v_mov_b32_e32 v15, vcc_lo
	v_mov_b32_e32 v16, vcc_hi
	ds_write2_b32 v11, v15, v16 offset0:8 offset1:72
	s_or_b64 exec, exec, s[18:19]
	v_bcnt_u32_b32 v14, v10, v14
	v_cndmask_b32_e64 v10, 0, 1, s[10:11]
	v_cmp_ne_u32_e32 vcc, 0, v10
	s_nop 1
	v_lshrrev_b64 v[10:11], v38, vcc
	v_and_b32_e32 v11, v10, v208
	v_bcnt_u32_b32 v11, v11, v14
	v_cmp_lt_i32_e32 vcc, v11, v13
	s_and_b64 s[2:3], s[10:11], vcc
	s_or_b64 s[2:3], s[34:35], s[2:3]
	v_cndmask_b32_e64 v11, 0, 1, s[2:3]
	v_cmp_ne_u32_e32 vcc, 0, v11
	s_and_saveexec_b64 s[10:11], s[8:9]
	v_mov_b32_e32 v11, s79
	v_mov_b32_e32 v15, vcc_lo
	v_mov_b32_e32 v16, vcc_hi
	ds_write2_b32 v11, v15, v16 offset0:9 offset1:73
	s_or_b64 exec, exec, s[10:11]
	v_bcnt_u32_b32 v14, v10, v14
	v_cndmask_b32_e64 v10, 0, 1, s[0:1]
	v_cmp_ne_u32_e32 vcc, 0, v10
	s_nop 1
	v_lshrrev_b64 v[10:11], v38, vcc
	v_and_b32_e32 v11, v10, v208
	v_bcnt_u32_b32 v11, v11, v14
	v_cmp_lt_i32_e32 vcc, v11, v13
	s_and_b64 s[0:1], s[0:1], vcc
	s_or_b64 s[0:1], s[28:29], s[0:1]
	v_cndmask_b32_e64 v11, 0, 1, s[0:1]
	v_cmp_ne_u32_e32 vcc, 0, v11
	s_and_saveexec_b64 s[0:1], s[8:9]
	v_mov_b32_e32 v11, s79
	v_mov_b32_e32 v15, vcc_lo
	v_mov_b32_e32 v16, vcc_hi
	ds_write2_b32 v11, v15, v16 offset0:10 offset1:74
	s_or_b64 exec, exec, s[0:1]
	v_bcnt_u32_b32 v14, v10, v14
	v_cndmask_b32_e64 v10, 0, 1, s[82:83]
	v_cmp_ne_u32_e32 vcc, 0, v10
	s_nop 1
	v_lshrrev_b64 v[10:11], v38, vcc
	v_and_b32_e32 v11, v10, v208
	v_bcnt_u32_b32 v11, v11, v14
	v_cmp_lt_i32_e32 vcc, v11, v13
	s_and_b64 s[0:1], s[82:83], vcc
	s_or_b64 s[0:1], s[94:95], s[0:1]
	v_cndmask_b32_e64 v11, 0, 1, s[0:1]
	v_cmp_ne_u32_e32 vcc, 0, v11
	s_and_saveexec_b64 s[0:1], s[8:9]
	v_mov_b32_e32 v11, s79
	v_mov_b32_e32 v15, vcc_lo
	v_mov_b32_e32 v16, vcc_hi
	ds_write2_b32 v11, v15, v16 offset0:11 offset1:75
	s_or_b64 exec, exec, s[0:1]
	v_bcnt_u32_b32 v14, v10, v14
	v_cndmask_b32_e64 v10, 0, 1, s[24:25]
	v_cmp_ne_u32_e32 vcc, 0, v10
	s_nop 1
	v_lshrrev_b64 v[10:11], v38, vcc
	v_and_b32_e32 v11, v10, v208
	v_bcnt_u32_b32 v11, v11, v14
	v_cmp_lt_i32_e32 vcc, v11, v13
	s_and_b64 s[0:1], s[24:25], vcc
	s_or_b64 s[0:1], s[90:91], s[0:1]
	v_cndmask_b32_e64 v11, 0, 1, s[0:1]
	v_cmp_ne_u32_e32 vcc, 0, v11
	s_and_saveexec_b64 s[0:1], s[8:9]
	v_mov_b32_e32 v11, s79
	v_mov_b32_e32 v15, vcc_lo
	v_mov_b32_e32 v16, vcc_hi
	ds_write2_b32 v11, v15, v16 offset0:12 offset1:76
	s_or_b64 exec, exec, s[0:1]
	v_bcnt_u32_b32 v14, v10, v14
	v_cndmask_b32_e64 v10, 0, 1, s[20:21]
	v_cmp_ne_u32_e32 vcc, 0, v10
	v_readlane_b32 s2, v252, 42
	v_readlane_b32 s3, v252, 43
	v_lshrrev_b64 v[10:11], v38, vcc
	v_and_b32_e32 v11, v10, v208
	v_bcnt_u32_b32 v11, v11, v14
	v_cmp_lt_i32_e32 vcc, v11, v13
	s_and_b64 s[0:1], s[20:21], vcc
	s_or_b64 s[0:1], s[2:3], s[0:1]
	v_cndmask_b32_e64 v11, 0, 1, s[0:1]
	v_cmp_ne_u32_e32 vcc, 0, v11
	s_and_saveexec_b64 s[0:1], s[8:9]
	v_mov_b32_e32 v11, s79
	v_mov_b32_e32 v15, vcc_lo
	v_mov_b32_e32 v16, vcc_hi
	ds_write2_b32 v11, v15, v16 offset0:13 offset1:77
	s_or_b64 exec, exec, s[0:1]
	v_bcnt_u32_b32 v14, v10, v14
	v_cndmask_b32_e64 v10, 0, 1, s[16:17]
	v_cmp_ne_u32_e32 vcc, 0, v10
	v_readlane_b32 s2, v252, 44
	v_readlane_b32 s3, v252, 45
	v_lshrrev_b64 v[10:11], v38, vcc
	v_and_b32_e32 v11, v10, v208
	v_bcnt_u32_b32 v11, v11, v14
	v_cmp_lt_i32_e32 vcc, v11, v13
	s_and_b64 s[0:1], s[16:17], vcc
	s_or_b64 s[0:1], s[2:3], s[0:1]
	v_cndmask_b32_e64 v11, 0, 1, s[0:1]
	v_cmp_ne_u32_e32 vcc, 0, v11
	s_and_saveexec_b64 s[0:1], s[8:9]
	v_mov_b32_e32 v11, s79
	v_mov_b32_e32 v15, vcc_lo
	v_mov_b32_e32 v16, vcc_hi
	ds_write2_b32 v11, v15, v16 offset0:14 offset1:78
	s_or_b64 exec, exec, s[0:1]
	v_bcnt_u32_b32 v14, v10, v14
	v_cndmask_b32_e64 v10, 0, 1, s[88:89]
	v_cmp_ne_u32_e32 vcc, 0, v10
	v_readlane_b32 s2, v252, 46
	v_readlane_b32 s3, v252, 47
	v_lshrrev_b64 v[10:11], v38, vcc
	v_and_b32_e32 v11, v10, v208
	v_bcnt_u32_b32 v11, v11, v14
	v_cmp_lt_i32_e32 vcc, v11, v13
	s_and_b64 s[0:1], s[88:89], vcc
	s_or_b64 s[0:1], s[2:3], s[0:1]
	v_cndmask_b32_e64 v11, 0, 1, s[0:1]
	v_cmp_ne_u32_e32 vcc, 0, v11
	s_and_saveexec_b64 s[0:1], s[8:9]
	v_mov_b32_e32 v11, s79
	v_mov_b32_e32 v15, vcc_lo
	v_mov_b32_e32 v16, vcc_hi
	ds_write2_b32 v11, v15, v16 offset0:15 offset1:79
	s_or_b64 exec, exec, s[0:1]
	v_bcnt_u32_b32 v14, v10, v14
	v_cndmask_b32_e64 v10, 0, 1, s[80:81]
; __global__ void __launch_bounds__(512, 2) mega_fwd(KArgs a) {
;     ...
;                     int running = 0;
; #pragma unroll
;                     for (int jj = 0; jj < 64; ++jj) {
;                         const bool e = key[jj] == tau;
;                         const unsigned long long be = __ballot(e);
;                         const unsigned hb = (unsigned)(be >> (32 * qs));
;                         const int rank = running + __popc(hb & ((1u << (lane & 31)) - 1u));
;                         running += __popc(hb);
;                         const bool sel = (key[jj] > tau) || (e && rank < need_eq);
;                         const unsigned long long bm = __ballot(sel);
;                         if (lane == 0) { wscr[jj] = (unsigned)bm; wscr[64 + jj] = (unsigned)(bm >> 32); }
;                     }
	v_cmp_ne_u32_e32 vcc, 0, v10
	v_readlane_b32 s2, v252, 48
	v_readlane_b32 s3, v252, 49
	v_lshrrev_b64 v[10:11], v38, vcc
	v_and_b32_e32 v11, v10, v208
	v_bcnt_u32_b32 v11, v11, v14
	v_cmp_lt_i32_e32 vcc, v11, v13
	s_and_b64 s[0:1], s[80:81], vcc
	s_or_b64 s[0:1], s[2:3], s[0:1]
	v_cndmask_b32_e64 v11, 0, 1, s[0:1]
	v_cmp_ne_u32_e32 vcc, 0, v11
	s_and_saveexec_b64 s[0:1], s[8:9]
	v_mov_b32_e32 v11, s79
	v_mov_b32_e32 v15, vcc_lo
	v_mov_b32_e32 v16, vcc_hi
	ds_write2_b32 v11, v15, v16 offset0:16 offset1:80
	s_or_b64 exec, exec, s[0:1]
	v_bcnt_u32_b32 v14, v10, v14
	v_cndmask_b32_e64 v10, 0, 1, s[70:71]
	v_cmp_ne_u32_e32 vcc, 0, v10
	v_readlane_b32 s2, v252, 50
	v_readlane_b32 s3, v252, 51
	v_lshrrev_b64 v[10:11], v38, vcc
	v_and_b32_e32 v11, v10, v208
	v_bcnt_u32_b32 v11, v11, v14
	v_cmp_lt_i32_e32 vcc, v11, v13
	s_and_b64 s[0:1], s[70:71], vcc
	s_or_b64 s[0:1], s[2:3], s[0:1]
	v_cndmask_b32_e64 v11, 0, 1, s[0:1]
	v_cmp_ne_u32_e32 vcc, 0, v11
	s_and_saveexec_b64 s[0:1], s[8:9]
	v_mov_b32_e32 v11, s79
	v_mov_b32_e32 v15, vcc_lo
	v_mov_b32_e32 v16, vcc_hi
	ds_write2_b32 v11, v15, v16 offset0:17 offset1:81
	s_or_b64 exec, exec, s[0:1]
	v_bcnt_u32_b32 v14, v10, v14
	v_cndmask_b32_e64 v10, 0, 1, s[66:67]
	v_cmp_ne_u32_e32 vcc, 0, v10
	v_readlane_b32 s2, v252, 52
	v_readlane_b32 s3, v252, 53
	v_lshrrev_b64 v[10:11], v38, vcc
	v_and_b32_e32 v11, v10, v208
	v_bcnt_u32_b32 v11, v11, v14
	v_cmp_lt_i32_e32 vcc, v11, v13
	s_and_b64 s[0:1], s[66:67], vcc
	s_or_b64 s[0:1], s[2:3], s[0:1]
	v_cndmask_b32_e64 v11, 0, 1, s[0:1]
	v_cmp_ne_u32_e32 vcc, 0, v11
	s_and_saveexec_b64 s[0:1], s[8:9]
	v_mov_b32_e32 v11, s79
	v_mov_b32_e32 v15, vcc_lo
	v_mov_b32_e32 v16, vcc_hi
	ds_write2_b32 v11, v15, v16 offset0:18 offset1:82
	s_or_b64 exec, exec, s[0:1]
	v_bcnt_u32_b32 v14, v10, v14
	v_cndmask_b32_e64 v10, 0, 1, s[62:63]
	v_cmp_ne_u32_e32 vcc, 0, v10
	v_readlane_b32 s2, v252, 54
	v_readlane_b32 s3, v252, 55
	v_lshrrev_b64 v[10:11], v38, vcc
	v_and_b32_e32 v11, v10, v208
	v_bcnt_u32_b32 v11, v11, v14
	v_cmp_lt_i32_e32 vcc, v11, v13
	s_and_b64 s[0:1], s[62:63], vcc
	s_or_b64 s[0:1], s[2:3], s[0:1]
	v_cndmask_b32_e64 v11, 0, 1, s[0:1]
	v_cmp_ne_u32_e32 vcc, 0, v11
	s_and_saveexec_b64 s[0:1], s[8:9]
	v_mov_b32_e32 v11, s79
	v_mov_b32_e32 v15, vcc_lo
	v_mov_b32_e32 v16, vcc_hi
	ds_write2_b32 v11, v15, v16 offset0:19 offset1:83
	s_or_b64 exec, exec, s[0:1]
	v_bcnt_u32_b32 v14, v10, v14
	v_cndmask_b32_e64 v10, 0, 1, s[58:59]
	v_cmp_ne_u32_e32 vcc, 0, v10
	v_readlane_b32 s2, v252, 56
	v_readlane_b32 s3, v252, 57
	v_lshrrev_b64 v[10:11], v38, vcc
	v_and_b32_e32 v11, v10, v208
	v_bcnt_u32_b32 v11, v11, v14
	v_cmp_lt_i32_e32 vcc, v11, v13
	s_and_b64 s[0:1], s[58:59], vcc
	s_or_b64 s[0:1], s[2:3], s[0:1]
	v_cndmask_b32_e64 v11, 0, 1, s[0:1]
	v_cmp_ne_u32_e32 vcc, 0, v11
	s_and_saveexec_b64 s[0:1], s[8:9]
	v_mov_b32_e32 v11, s79
	v_mov_b32_e32 v15, vcc_lo
	v_mov_b32_e32 v16, vcc_hi
	ds_write2_b32 v11, v15, v16 offset0:20 offset1:84
	s_or_b64 exec, exec, s[0:1]
	v_bcnt_u32_b32 v14, v10, v14
	v_cndmask_b32_e64 v10, 0, 1, s[54:55]
	v_cmp_ne_u32_e32 vcc, 0, v10
	v_readlane_b32 s2, v252, 58
	v_readlane_b32 s3, v252, 59
	v_lshrrev_b64 v[10:11], v38, vcc
	v_and_b32_e32 v11, v10, v208
	v_bcnt_u32_b32 v11, v11, v14
	v_cmp_lt_i32_e32 vcc, v11, v13
	s_and_b64 s[0:1], s[54:55], vcc
	s_or_b64 s[0:1], s[2:3], s[0:1]
	v_cndmask_b32_e64 v11, 0, 1, s[0:1]
	v_cmp_ne_u32_e32 vcc, 0, v11
	s_and_saveexec_b64 s[0:1], s[8:9]
	v_mov_b32_e32 v11, s79
	v_mov_b32_e32 v15, vcc_lo
	v_mov_b32_e32 v16, vcc_hi
	ds_write2_b32 v11, v15, v16 offset0:21 offset1:85
	s_or_b64 exec, exec, s[0:1]
	v_bcnt_u32_b32 v14, v10, v14
	v_cndmask_b32_e64 v10, 0, 1, s[50:51]
	v_cmp_ne_u32_e32 vcc, 0, v10
	v_readlane_b32 s2, v252, 60
	v_readlane_b32 s3, v252, 61
	v_lshrrev_b64 v[10:11], v38, vcc
	v_and_b32_e32 v11, v10, v208
	v_bcnt_u32_b32 v11, v11, v14
	v_cmp_lt_i32_e32 vcc, v11, v13
	s_and_b64 s[0:1], s[50:51], vcc
	s_or_b64 s[0:1], s[2:3], s[0:1]
	v_cndmask_b32_e64 v11, 0, 1, s[0:1]
	v_cmp_ne_u32_e32 vcc, 0, v11
	s_and_saveexec_b64 s[0:1], s[8:9]
	v_mov_b32_e32 v11, s79
	v_mov_b32_e32 v15, vcc_lo
	v_mov_b32_e32 v16, vcc_hi
	ds_write2_b32 v11, v15, v16 offset0:22 offset1:86
	s_or_b64 exec, exec, s[0:1]
	v_bcnt_u32_b32 v14, v10, v14
	v_cndmask_b32_e64 v10, 0, 1, s[46:47]
	v_cmp_ne_u32_e32 vcc, 0, v10
	v_readlane_b32 s2, v252, 62
	v_readlane_b32 s3, v252, 63
	v_lshrrev_b64 v[10:11], v38, vcc
	v_and_b32_e32 v11, v10, v208
	v_bcnt_u32_b32 v11, v11, v14
	v_cmp_lt_i32_e32 vcc, v11, v13
	s_and_b64 s[0:1], s[46:47], vcc
	s_or_b64 s[0:1], s[2:3], s[0:1]
	v_cndmask_b32_e64 v11, 0, 1, s[0:1]
	v_cmp_ne_u32_e32 vcc, 0, v11
	s_and_saveexec_b64 s[0:1], s[8:9]
	v_mov_b32_e32 v11, s79
	v_mov_b32_e32 v15, vcc_lo
	v_mov_b32_e32 v16, vcc_hi
	ds_write2_b32 v11, v15, v16 offset0:23 offset1:87
	s_or_b64 exec, exec, s[0:1]
	v_bcnt_u32_b32 v14, v10, v14
	v_cndmask_b32_e64 v10, 0, 1, s[22:23]
	v_cmp_ne_u32_e32 vcc, 0, v10
	v_readlane_b32 s2, v255, 0
	v_readlane_b32 s3, v255, 1
	v_lshrrev_b64 v[10:11], v38, vcc
	v_and_b32_e32 v11, v10, v208
	v_bcnt_u32_b32 v11, v11, v14
	v_cmp_lt_i32_e32 vcc, v11, v13
	s_and_b64 s[0:1], s[22:23], vcc
	s_or_b64 s[0:1], s[2:3], s[0:1]
	v_cndmask_b32_e64 v11, 0, 1, s[0:1]
	v_cmp_ne_u32_e32 vcc, 0, v11
	s_and_saveexec_b64 s[0:1], s[8:9]
	v_mov_b32_e32 v11, s79
	v_mov_b32_e32 v15, vcc_lo
	v_mov_b32_e32 v16, vcc_hi
	ds_write2_b32 v11, v15, v16 offset0:24 offset1:88
	s_or_b64 exec, exec, s[0:1]
	v_bcnt_u32_b32 v14, v10, v14
	v_cndmask_b32_e64 v10, 0, 1, s[14:15]
	v_cmp_ne_u32_e32 vcc, 0, v10
	v_readlane_b32 s2, v255, 2
	v_readlane_b32 s3, v255, 3
	v_lshrrev_b64 v[10:11], v38, vcc
	v_and_b32_e32 v11, v10, v208
; __global__ void __launch_bounds__(512, 2) mega_fwd(KArgs a) {
;     ...
;                     int running = 0;
; #pragma unroll
;                     for (int jj = 0; jj < 64; ++jj) {
;                         const bool e = key[jj] == tau;
;                         const unsigned long long be = __ballot(e);
;                         const unsigned hb = (unsigned)(be >> (32 * qs));
;                         const int rank = running + __popc(hb & ((1u << (lane & 31)) - 1u));
;                         running += __popc(hb);
;                         const bool sel = (key[jj] > tau) || (e && rank < need_eq);
;                         const unsigned long long bm = __ballot(sel);
;                         if (lane == 0) { wscr[jj] = (unsigned)bm; wscr[64 + jj] = (unsigned)(bm >> 32); }
;                     }
	v_bcnt_u32_b32 v11, v11, v14
	v_cmp_lt_i32_e32 vcc, v11, v13
	s_and_b64 s[0:1], s[14:15], vcc
	s_or_b64 s[0:1], s[2:3], s[0:1]
	v_cndmask_b32_e64 v11, 0, 1, s[0:1]
	v_cmp_ne_u32_e32 vcc, 0, v11
	s_and_saveexec_b64 s[0:1], s[8:9]
	v_mov_b32_e32 v11, s79
	v_mov_b32_e32 v15, vcc_lo
	v_mov_b32_e32 v16, vcc_hi
	ds_write2_b32 v11, v15, v16 offset0:25 offset1:89
	s_or_b64 exec, exec, s[0:1]
	v_bcnt_u32_b32 v14, v10, v14
	v_cndmask_b32_e64 v10, 0, 1, s[4:5]
	v_cmp_ne_u32_e32 vcc, 0, v10
	v_readlane_b32 s2, v255, 4
	v_readlane_b32 s3, v255, 5
	v_lshrrev_b64 v[10:11], v38, vcc
	v_and_b32_e32 v11, v10, v208
	v_bcnt_u32_b32 v11, v11, v14
	v_cmp_lt_i32_e32 vcc, v11, v13
	s_and_b64 s[0:1], s[4:5], vcc
	s_or_b64 s[0:1], s[2:3], s[0:1]
	v_cndmask_b32_e64 v11, 0, 1, s[0:1]
	v_cmp_ne_u32_e32 vcc, 0, v11
	s_and_saveexec_b64 s[0:1], s[8:9]
	v_mov_b32_e32 v11, s79
	v_mov_b32_e32 v15, vcc_lo
	v_mov_b32_e32 v16, vcc_hi
	ds_write2_b32 v11, v15, v16 offset0:26 offset1:90
	s_or_b64 exec, exec, s[0:1]
	v_readlane_b32 s0, v255, 8
	v_readlane_b32 s1, v255, 9
	v_bcnt_u32_b32 v14, v10, v14
	v_readlane_b32 s2, v255, 6
	v_cndmask_b32_e64 v10, 0, 1, s[0:1]
	v_cmp_ne_u32_e32 vcc, 0, v10
	v_readlane_b32 s3, v255, 7
	s_nop 0
	v_lshrrev_b64 v[10:11], v38, vcc
	v_and_b32_e32 v11, v10, v208
	v_bcnt_u32_b32 v11, v11, v14
	v_cmp_lt_i32_e32 vcc, v11, v13
	s_and_b64 s[0:1], s[0:1], vcc
	s_or_b64 s[0:1], s[2:3], s[0:1]
	v_cndmask_b32_e64 v11, 0, 1, s[0:1]
	v_cmp_ne_u32_e32 vcc, 0, v11
	s_and_saveexec_b64 s[0:1], s[8:9]
	v_mov_b32_e32 v11, s79
	v_mov_b32_e32 v15, vcc_lo
	v_mov_b32_e32 v16, vcc_hi
	ds_write2_b32 v11, v15, v16 offset0:27 offset1:91
	s_or_b64 exec, exec, s[0:1]
	v_bcnt_u32_b32 v14, v10, v14
	v_cndmask_b32_e64 v10, 0, 1, s[6:7]
	v_cmp_ne_u32_e32 vcc, 0, v10
	v_readlane_b32 s2, v255, 10
	v_readlane_b32 s3, v255, 11
	v_lshrrev_b64 v[10:11], v38, vcc
	v_and_b32_e32 v11, v10, v208
	v_bcnt_u32_b32 v11, v11, v14
	v_cmp_lt_i32_e32 vcc, v11, v13
	s_and_b64 s[0:1], s[6:7], vcc
	s_or_b64 s[0:1], s[2:3], s[0:1]
	v_cndmask_b32_e64 v11, 0, 1, s[0:1]
	v_cmp_ne_u32_e32 vcc, 0, v11
	s_and_saveexec_b64 s[0:1], s[8:9]
	v_mov_b32_e32 v11, s79
	v_mov_b32_e32 v15, vcc_lo
	v_mov_b32_e32 v16, vcc_hi
	ds_write2_b32 v11, v15, v16 offset0:28 offset1:92
	s_or_b64 exec, exec, s[0:1]
	v_readlane_b32 s0, v255, 14
	v_readlane_b32 s1, v255, 15
	v_bcnt_u32_b32 v14, v10, v14
	v_readlane_b32 s2, v255, 12
	v_cndmask_b32_e64 v10, 0, 1, s[0:1]
	v_cmp_ne_u32_e32 vcc, 0, v10
	v_readlane_b32 s3, v255, 13
	s_nop 0
	v_lshrrev_b64 v[10:11], v38, vcc
	v_and_b32_e32 v11, v10, v208
	v_bcnt_u32_b32 v11, v11, v14
	v_cmp_lt_i32_e32 vcc, v11, v13
	s_and_b64 s[0:1], s[0:1], vcc
	s_or_b64 s[0:1], s[2:3], s[0:1]
	v_cndmask_b32_e64 v11, 0, 1, s[0:1]
	v_cmp_ne_u32_e32 vcc, 0, v11
	s_and_saveexec_b64 s[0:1], s[8:9]
	v_mov_b32_e32 v11, s79
	v_mov_b32_e32 v15, vcc_lo
	v_mov_b32_e32 v16, vcc_hi
	ds_write2_b32 v11, v15, v16 offset0:29 offset1:93
	s_or_b64 exec, exec, s[0:1]
	v_readlane_b32 s0, v255, 18
	v_readlane_b32 s1, v255, 19
	v_bcnt_u32_b32 v14, v10, v14
	v_readlane_b32 s2, v255, 16
	v_cndmask_b32_e64 v10, 0, 1, s[0:1]
	v_cmp_ne_u32_e32 vcc, 0, v10
	v_readlane_b32 s3, v255, 17
	s_nop 0
	v_lshrrev_b64 v[10:11], v38, vcc
	v_and_b32_e32 v11, v10, v208
	v_bcnt_u32_b32 v11, v11, v14
	v_cmp_lt_i32_e32 vcc, v11, v13
	s_and_b64 s[0:1], s[0:1], vcc
	s_or_b64 s[0:1], s[2:3], s[0:1]
	v_cndmask_b32_e64 v11, 0, 1, s[0:1]
	v_cmp_ne_u32_e32 vcc, 0, v11
	s_and_saveexec_b64 s[0:1], s[8:9]
	v_mov_b32_e32 v11, s79
	v_mov_b32_e32 v15, vcc_lo
	v_mov_b32_e32 v16, vcc_hi
	ds_write2_b32 v11, v15, v16 offset0:30 offset1:94
	s_or_b64 exec, exec, s[0:1]
	v_readlane_b32 s0, v255, 22
	v_readlane_b32 s1, v255, 23
	v_bcnt_u32_b32 v14, v10, v14
	v_readlane_b32 s2, v255, 20
	v_cndmask_b32_e64 v10, 0, 1, s[0:1]
	v_cmp_ne_u32_e32 vcc, 0, v10
	v_readlane_b32 s3, v255, 21
	s_nop 0
	v_lshrrev_b64 v[10:11], v38, vcc
	v_and_b32_e32 v11, v10, v208
	v_bcnt_u32_b32 v11, v11, v14
	v_cmp_lt_i32_e32 vcc, v11, v13
	s_and_b64 s[0:1], s[0:1], vcc
	s_or_b64 s[0:1], s[2:3], s[0:1]
	v_cndmask_b32_e64 v11, 0, 1, s[0:1]
	v_cmp_ne_u32_e32 vcc, 0, v11
	s_and_saveexec_b64 s[0:1], s[8:9]
	v_mov_b32_e32 v11, s79
	v_mov_b32_e32 v15, vcc_lo
	v_mov_b32_e32 v16, vcc_hi
	ds_write2_b32 v11, v15, v16 offset0:31 offset1:95
	s_or_b64 exec, exec, s[0:1]
	v_readlane_b32 s0, v255, 26
	v_readlane_b32 s1, v255, 27
	v_bcnt_u32_b32 v14, v10, v14
	v_readlane_b32 s2, v255, 24
	v_cndmask_b32_e64 v10, 0, 1, s[0:1]
	v_cmp_ne_u32_e32 vcc, 0, v10
	v_readlane_b32 s3, v255, 25
	s_nop 0
	v_lshrrev_b64 v[10:11], v38, vcc
	v_and_b32_e32 v11, v10, v208
	v_bcnt_u32_b32 v11, v11, v14
	v_cmp_lt_i32_e32 vcc, v11, v13
	s_and_b64 s[0:1], s[0:1], vcc
	s_or_b64 s[0:1], s[2:3], s[0:1]
	v_cndmask_b32_e64 v11, 0, 1, s[0:1]
	v_cmp_ne_u32_e32 vcc, 0, v11
	s_and_saveexec_b64 s[0:1], s[8:9]
	v_mov_b32_e32 v11, s79
	v_mov_b32_e32 v15, vcc_lo
	v_mov_b32_e32 v16, vcc_hi
	ds_write2_b32 v11, v15, v16 offset0:32 offset1:96
	s_or_b64 exec, exec, s[0:1]
	v_readlane_b32 s0, v255, 30
	v_readlane_b32 s1, v255, 31
	v_bcnt_u32_b32 v14, v10, v14
	v_readlane_b32 s2, v255, 28
	v_cndmask_b32_e64 v10, 0, 1, s[0:1]
	v_cmp_ne_u32_e32 vcc, 0, v10
	v_readlane_b32 s3, v255, 29
	s_nop 0
	v_lshrrev_b64 v[10:11], v38, vcc
	v_and_b32_e32 v11, v10, v208
	v_bcnt_u32_b32 v11, v11, v14
	v_cmp_lt_i32_e32 vcc, v11, v13
	s_and_b64 s[0:1], s[0:1], vcc
	s_or_b64 s[0:1], s[2:3], s[0:1]
	v_cndmask_b32_e64 v11, 0, 1, s[0:1]
	v_cmp_ne_u32_e32 vcc, 0, v11
	s_and_saveexec_b64 s[0:1], s[8:9]
	v_mov_b32_e32 v11, s79
	v_mov_b32_e32 v15, vcc_lo
	v_mov_b32_e32 v16, vcc_hi
	ds_write2_b32 v11, v15, v16 offset0:33 offset1:97
	s_or_b64 exec, exec, s[0:1]
	v_readlane_b32 s0, v255, 34
; __global__ void __launch_bounds__(512, 2) mega_fwd(KArgs a) {
;     ...
;                     int running = 0;
; #pragma unroll
;                     for (int jj = 0; jj < 64; ++jj) {
;                         const bool e = key[jj] == tau;
;                         const unsigned long long be = __ballot(e);
;                         const unsigned hb = (unsigned)(be >> (32 * qs));
;                         const int rank = running + __popc(hb & ((1u << (lane & 31)) - 1u));
;                         running += __popc(hb);
;                         const bool sel = (key[jj] > tau) || (e && rank < need_eq);
;                         const unsigned long long bm = __ballot(sel);
;                         if (lane == 0) { wscr[jj] = (unsigned)bm; wscr[64 + jj] = (unsigned)(bm >> 32); }
;                     }
	v_readlane_b32 s1, v255, 35
	v_bcnt_u32_b32 v14, v10, v14
	v_readlane_b32 s2, v255, 32
	v_cndmask_b32_e64 v10, 0, 1, s[0:1]
	v_cmp_ne_u32_e32 vcc, 0, v10
	v_readlane_b32 s3, v255, 33
	s_nop 0
	v_lshrrev_b64 v[10:11], v38, vcc
	v_and_b32_e32 v11, v10, v208
	v_bcnt_u32_b32 v11, v11, v14
	v_cmp_lt_i32_e32 vcc, v11, v13
	s_and_b64 s[0:1], s[0:1], vcc
	s_or_b64 s[0:1], s[2:3], s[0:1]
	v_cndmask_b32_e64 v11, 0, 1, s[0:1]
	v_cmp_ne_u32_e32 vcc, 0, v11
	s_and_saveexec_b64 s[0:1], s[8:9]
	v_mov_b32_e32 v11, s79
	v_mov_b32_e32 v15, vcc_lo
	v_mov_b32_e32 v16, vcc_hi
	ds_write2_b32 v11, v15, v16 offset0:34 offset1:98
	s_or_b64 exec, exec, s[0:1]
	v_readlane_b32 s0, v255, 38
	v_readlane_b32 s1, v255, 39
	v_bcnt_u32_b32 v14, v10, v14
	v_readlane_b32 s2, v255, 36
	v_cndmask_b32_e64 v10, 0, 1, s[0:1]
	v_cmp_ne_u32_e32 vcc, 0, v10
	v_readlane_b32 s3, v255, 37
	s_nop 0
	v_lshrrev_b64 v[10:11], v38, vcc
	v_and_b32_e32 v11, v10, v208
	v_bcnt_u32_b32 v11, v11, v14
	v_cmp_lt_i32_e32 vcc, v11, v13
	s_and_b64 s[0:1], s[0:1], vcc
	s_or_b64 s[0:1], s[2:3], s[0:1]
	v_cndmask_b32_e64 v11, 0, 1, s[0:1]
	v_cmp_ne_u32_e32 vcc, 0, v11
	s_and_saveexec_b64 s[0:1], s[8:9]
	v_mov_b32_e32 v11, s79
	v_mov_b32_e32 v15, vcc_lo
	v_mov_b32_e32 v16, vcc_hi
	ds_write2_b32 v11, v15, v16 offset0:35 offset1:99
	s_or_b64 exec, exec, s[0:1]
	v_readlane_b32 s0, v255, 42
	v_readlane_b32 s1, v255, 43
	v_bcnt_u32_b32 v14, v10, v14
	v_readlane_b32 s2, v255, 40
	v_cndmask_b32_e64 v10, 0, 1, s[0:1]
	v_cmp_ne_u32_e32 vcc, 0, v10
	v_readlane_b32 s3, v255, 41
	s_nop 0
	v_lshrrev_b64 v[10:11], v38, vcc
	v_and_b32_e32 v11, v10, v208
	v_bcnt_u32_b32 v11, v11, v14
	v_cmp_lt_i32_e32 vcc, v11, v13
	s_and_b64 s[0:1], s[0:1], vcc
	s_or_b64 s[0:1], s[2:3], s[0:1]
	v_cndmask_b32_e64 v11, 0, 1, s[0:1]
	v_cmp_ne_u32_e32 vcc, 0, v11
	s_and_saveexec_b64 s[0:1], s[8:9]
	v_mov_b32_e32 v11, s79
	v_mov_b32_e32 v15, vcc_lo
	v_mov_b32_e32 v16, vcc_hi
	ds_write2_b32 v11, v15, v16 offset0:36 offset1:100
	s_or_b64 exec, exec, s[0:1]
	v_readlane_b32 s0, v255, 46
	v_readlane_b32 s1, v255, 47
	v_bcnt_u32_b32 v14, v10, v14
	v_readlane_b32 s2, v255, 44
	v_cndmask_b32_e64 v10, 0, 1, s[0:1]
	v_cmp_ne_u32_e32 vcc, 0, v10
	v_readlane_b32 s3, v255, 45
	s_nop 0
	v_lshrrev_b64 v[10:11], v38, vcc
	v_and_b32_e32 v11, v10, v208
	v_bcnt_u32_b32 v11, v11, v14
	v_cmp_lt_i32_e32 vcc, v11, v13
	s_and_b64 s[0:1], s[0:1], vcc
	s_or_b64 s[0:1], s[2:3], s[0:1]
	v_cndmask_b32_e64 v11, 0, 1, s[0:1]
	v_cmp_ne_u32_e32 vcc, 0, v11
	s_and_saveexec_b64 s[0:1], s[8:9]
	v_mov_b32_e32 v11, s79
	v_mov_b32_e32 v15, vcc_lo
	v_mov_b32_e32 v16, vcc_hi
	ds_write2_b32 v11, v15, v16 offset0:37 offset1:101
	s_or_b64 exec, exec, s[0:1]
	v_readlane_b32 s0, v255, 50
	v_readlane_b32 s1, v255, 51
	v_bcnt_u32_b32 v14, v10, v14
	v_readlane_b32 s2, v255, 48
	v_cndmask_b32_e64 v10, 0, 1, s[0:1]
	v_cmp_ne_u32_e32 vcc, 0, v10
	v_readlane_b32 s3, v255, 49
	s_nop 0
	v_lshrrev_b64 v[10:11], v38, vcc
	v_and_b32_e32 v11, v10, v208
	v_bcnt_u32_b32 v11, v11, v14
	v_cmp_lt_i32_e32 vcc, v11, v13
	s_and_b64 s[0:1], s[0:1], vcc
	s_or_b64 s[0:1], s[2:3], s[0:1]
	v_cndmask_b32_e64 v11, 0, 1, s[0:1]
	v_cmp_ne_u32_e32 vcc, 0, v11
	s_and_saveexec_b64 s[0:1], s[8:9]
	v_mov_b32_e32 v11, s79
	v_mov_b32_e32 v15, vcc_lo
	v_mov_b32_e32 v16, vcc_hi
	ds_write2_b32 v11, v15, v16 offset0:38 offset1:102
	s_or_b64 exec, exec, s[0:1]
	v_readlane_b32 s0, v255, 54
	v_readlane_b32 s1, v255, 55
	v_bcnt_u32_b32 v14, v10, v14
	v_readlane_b32 s2, v255, 52
	v_cndmask_b32_e64 v10, 0, 1, s[0:1]
	v_cmp_ne_u32_e32 vcc, 0, v10
	v_readlane_b32 s3, v255, 53
	s_nop 0
	v_lshrrev_b64 v[10:11], v38, vcc
	v_and_b32_e32 v11, v10, v208
	v_bcnt_u32_b32 v11, v11, v14
	v_cmp_lt_i32_e32 vcc, v11, v13
	s_and_b64 s[0:1], s[0:1], vcc
	s_or_b64 s[0:1], s[2:3], s[0:1]
	v_cndmask_b32_e64 v11, 0, 1, s[0:1]
	v_cmp_ne_u32_e32 vcc, 0, v11
	s_and_saveexec_b64 s[0:1], s[8:9]
	v_mov_b32_e32 v11, s79
	v_mov_b32_e32 v15, vcc_lo
	v_mov_b32_e32 v16, vcc_hi
	ds_write2_b32 v11, v15, v16 offset0:39 offset1:103
	s_or_b64 exec, exec, s[0:1]
	v_readlane_b32 s0, v255, 58
	v_readlane_b32 s1, v255, 59
	v_bcnt_u32_b32 v14, v10, v14
	v_readlane_b32 s2, v255, 56
	v_cndmask_b32_e64 v10, 0, 1, s[0:1]
	v_cmp_ne_u32_e32 vcc, 0, v10
	v_readlane_b32 s3, v255, 57
	s_nop 0
	v_lshrrev_b64 v[10:11], v38, vcc
	v_and_b32_e32 v11, v10, v208
	v_bcnt_u32_b32 v11, v11, v14
	v_cmp_lt_i32_e32 vcc, v11, v13
	s_and_b64 s[0:1], s[0:1], vcc
	s_or_b64 s[0:1], s[2:3], s[0:1]
	v_cndmask_b32_e64 v11, 0, 1, s[0:1]
	v_cmp_ne_u32_e32 vcc, 0, v11
	s_and_saveexec_b64 s[0:1], s[8:9]
	v_mov_b32_e32 v11, s79
	v_mov_b32_e32 v15, vcc_lo
	v_mov_b32_e32 v16, vcc_hi
	ds_write2_b32 v11, v15, v16 offset0:40 offset1:104
	s_or_b64 exec, exec, s[0:1]
	v_readlane_b32 s0, v255, 62
	v_readlane_b32 s1, v255, 63
	v_bcnt_u32_b32 v14, v10, v14
	v_readlane_b32 s2, v255, 60
	v_cndmask_b32_e64 v10, 0, 1, s[0:1]
	v_cmp_ne_u32_e32 vcc, 0, v10
	v_readlane_b32 s3, v255, 61
	s_nop 0
	v_lshrrev_b64 v[10:11], v38, vcc
	v_and_b32_e32 v11, v10, v208
	v_bcnt_u32_b32 v11, v11, v14
	v_cmp_lt_i32_e32 vcc, v11, v13
	s_and_b64 s[0:1], s[0:1], vcc
	s_or_b64 s[0:1], s[2:3], s[0:1]
	v_cndmask_b32_e64 v11, 0, 1, s[0:1]
	v_cmp_ne_u32_e32 vcc, 0, v11
	s_and_saveexec_b64 s[0:1], s[8:9]
	v_mov_b32_e32 v11, s79
	v_mov_b32_e32 v15, vcc_lo
	v_mov_b32_e32 v16, vcc_hi
	ds_write2_b32 v11, v15, v16 offset0:41 offset1:105
	s_or_b64 exec, exec, s[0:1]
	v_readlane_b32 s0, v253, 2
	v_readlane_b32 s1, v253, 3
	v_bcnt_u32_b32 v14, v10, v14
	v_readlane_b32 s2, v253, 0
	v_cndmask_b32_e64 v10, 0, 1, s[0:1]
	v_cmp_ne_u32_e32 vcc, 0, v10
	v_readlane_b32 s3, v253, 1
	s_nop 0
	v_lshrrev_b64 v[10:11], v38, vcc
	v_and_b32_e32 v11, v10, v208
; __global__ void __launch_bounds__(512, 2) mega_fwd(KArgs a) {
;     ...
;                     int running = 0;
; #pragma unroll
;                     for (int jj = 0; jj < 64; ++jj) {
;                         const bool e = key[jj] == tau;
;                         const unsigned long long be = __ballot(e);
;                         const unsigned hb = (unsigned)(be >> (32 * qs));
;                         const int rank = running + __popc(hb & ((1u << (lane & 31)) - 1u));
;                         running += __popc(hb);
;                         const bool sel = (key[jj] > tau) || (e && rank < need_eq);
;                         const unsigned long long bm = __ballot(sel);
;                         if (lane == 0) { wscr[jj] = (unsigned)bm; wscr[64 + jj] = (unsigned)(bm >> 32); }
;                     }
	v_bcnt_u32_b32 v11, v11, v14
	v_cmp_lt_i32_e32 vcc, v11, v13
	s_and_b64 s[0:1], s[0:1], vcc
	s_or_b64 s[0:1], s[2:3], s[0:1]
	v_cndmask_b32_e64 v11, 0, 1, s[0:1]
	v_cmp_ne_u32_e32 vcc, 0, v11
	s_and_saveexec_b64 s[0:1], s[8:9]
	v_mov_b32_e32 v11, s79
	v_mov_b32_e32 v15, vcc_lo
	v_mov_b32_e32 v16, vcc_hi
	ds_write2_b32 v11, v15, v16 offset0:42 offset1:106
	s_or_b64 exec, exec, s[0:1]
	v_readlane_b32 s0, v253, 6
	v_readlane_b32 s1, v253, 7
	v_bcnt_u32_b32 v14, v10, v14
	v_readlane_b32 s2, v253, 4
	v_cndmask_b32_e64 v10, 0, 1, s[0:1]
	v_cmp_ne_u32_e32 vcc, 0, v10
	v_readlane_b32 s3, v253, 5
	s_nop 0
	v_lshrrev_b64 v[10:11], v38, vcc
	v_and_b32_e32 v11, v10, v208
	v_bcnt_u32_b32 v11, v11, v14
	v_cmp_lt_i32_e32 vcc, v11, v13
	s_and_b64 s[0:1], s[0:1], vcc
	s_or_b64 s[0:1], s[2:3], s[0:1]
	v_cndmask_b32_e64 v11, 0, 1, s[0:1]
	v_cmp_ne_u32_e32 vcc, 0, v11
	s_and_saveexec_b64 s[0:1], s[8:9]
	v_mov_b32_e32 v11, s79
	v_mov_b32_e32 v15, vcc_lo
	v_mov_b32_e32 v16, vcc_hi
	ds_write2_b32 v11, v15, v16 offset0:43 offset1:107
	s_or_b64 exec, exec, s[0:1]
	v_readlane_b32 s0, v253, 10
	v_readlane_b32 s1, v253, 11
	v_bcnt_u32_b32 v14, v10, v14
	v_readlane_b32 s2, v253, 8
	v_cndmask_b32_e64 v10, 0, 1, s[0:1]
	v_cmp_ne_u32_e32 vcc, 0, v10
	v_readlane_b32 s3, v253, 9
	s_nop 0
	v_lshrrev_b64 v[10:11], v38, vcc
	v_and_b32_e32 v11, v10, v208
	v_bcnt_u32_b32 v11, v11, v14
	v_cmp_lt_i32_e32 vcc, v11, v13
	s_and_b64 s[0:1], s[0:1], vcc
	s_or_b64 s[0:1], s[2:3], s[0:1]
	v_cndmask_b32_e64 v11, 0, 1, s[0:1]
	v_cmp_ne_u32_e32 vcc, 0, v11
	s_and_saveexec_b64 s[0:1], s[8:9]
	v_mov_b32_e32 v11, s79
	v_mov_b32_e32 v15, vcc_lo
	v_mov_b32_e32 v16, vcc_hi
	ds_write2_b32 v11, v15, v16 offset0:44 offset1:108
	s_or_b64 exec, exec, s[0:1]
	v_readlane_b32 s0, v253, 14
	v_readlane_b32 s1, v253, 15
	v_bcnt_u32_b32 v14, v10, v14
	v_readlane_b32 s2, v253, 12
	v_cndmask_b32_e64 v10, 0, 1, s[0:1]
	v_cmp_ne_u32_e32 vcc, 0, v10
	v_readlane_b32 s3, v253, 13
	s_nop 0
	v_lshrrev_b64 v[10:11], v38, vcc
	v_and_b32_e32 v11, v10, v208
	v_bcnt_u32_b32 v11, v11, v14
	v_cmp_lt_i32_e32 vcc, v11, v13
	s_and_b64 s[0:1], s[0:1], vcc
	s_or_b64 s[0:1], s[2:3], s[0:1]
	v_cndmask_b32_e64 v11, 0, 1, s[0:1]
	v_cmp_ne_u32_e32 vcc, 0, v11
	s_and_saveexec_b64 s[0:1], s[8:9]
	v_mov_b32_e32 v11, s79
	v_mov_b32_e32 v15, vcc_lo
	v_mov_b32_e32 v16, vcc_hi
	ds_write2_b32 v11, v15, v16 offset0:45 offset1:109
	s_or_b64 exec, exec, s[0:1]
	v_readlane_b32 s0, v253, 18
	v_readlane_b32 s1, v253, 19
	v_bcnt_u32_b32 v14, v10, v14
	v_readlane_b32 s2, v253, 16
	v_cndmask_b32_e64 v10, 0, 1, s[0:1]
	v_cmp_ne_u32_e32 vcc, 0, v10
	v_readlane_b32 s3, v253, 17
	s_nop 0
	v_lshrrev_b64 v[10:11], v38, vcc
	v_and_b32_e32 v11, v10, v208
	v_bcnt_u32_b32 v11, v11, v14
	v_cmp_lt_i32_e32 vcc, v11, v13
	s_and_b64 s[0:1], s[0:1], vcc
	s_or_b64 s[0:1], s[2:3], s[0:1]
	v_cndmask_b32_e64 v11, 0, 1, s[0:1]
	v_cmp_ne_u32_e32 vcc, 0, v11
	s_and_saveexec_b64 s[0:1], s[8:9]
	v_mov_b32_e32 v11, s79
	v_mov_b32_e32 v15, vcc_lo
	v_mov_b32_e32 v16, vcc_hi
	ds_write2_b32 v11, v15, v16 offset0:46 offset1:110
	s_or_b64 exec, exec, s[0:1]
	v_readlane_b32 s0, v253, 22
	v_readlane_b32 s1, v253, 23
	v_bcnt_u32_b32 v14, v10, v14
	v_readlane_b32 s2, v253, 20
	v_cndmask_b32_e64 v10, 0, 1, s[0:1]
	v_cmp_ne_u32_e32 vcc, 0, v10
	v_readlane_b32 s3, v253, 21
	s_nop 0
	v_lshrrev_b64 v[10:11], v38, vcc
	v_and_b32_e32 v11, v10, v208
	v_bcnt_u32_b32 v11, v11, v14
	v_cmp_lt_i32_e32 vcc, v11, v13
	s_and_b64 s[0:1], s[0:1], vcc
	s_or_b64 s[0:1], s[2:3], s[0:1]
	v_cndmask_b32_e64 v11, 0, 1, s[0:1]
	v_cmp_ne_u32_e32 vcc, 0, v11
	s_and_saveexec_b64 s[0:1], s[8:9]
	v_mov_b32_e32 v11, s79
	v_mov_b32_e32 v15, vcc_lo
	v_mov_b32_e32 v16, vcc_hi
	ds_write2_b32 v11, v15, v16 offset0:47 offset1:111
	s_or_b64 exec, exec, s[0:1]
	v_readlane_b32 s0, v253, 26
	v_readlane_b32 s1, v253, 27
	v_bcnt_u32_b32 v14, v10, v14
	v_readlane_b32 s2, v253, 24
	v_cndmask_b32_e64 v10, 0, 1, s[0:1]
	v_cmp_ne_u32_e32 vcc, 0, v10
	v_readlane_b32 s3, v253, 25
	s_nop 0
	v_lshrrev_b64 v[10:11], v38, vcc
	v_and_b32_e32 v11, v10, v208
	v_bcnt_u32_b32 v11, v11, v14
	v_cmp_lt_i32_e32 vcc, v11, v13
	s_and_b64 s[0:1], s[0:1], vcc
	s_or_b64 s[0:1], s[2:3], s[0:1]
	v_cndmask_b32_e64 v11, 0, 1, s[0:1]
	v_cmp_ne_u32_e32 vcc, 0, v11
	s_and_saveexec_b64 s[0:1], s[8:9]
	v_mov_b32_e32 v11, s79
	v_mov_b32_e32 v15, vcc_lo
	v_mov_b32_e32 v16, vcc_hi
	ds_write2_b32 v11, v15, v16 offset0:48 offset1:112
	s_or_b64 exec, exec, s[0:1]
	v_readlane_b32 s0, v253, 30
	v_readlane_b32 s1, v253, 31
	v_bcnt_u32_b32 v14, v10, v14
	v_readlane_b32 s2, v253, 28
	v_cndmask_b32_e64 v10, 0, 1, s[0:1]
	v_cmp_ne_u32_e32 vcc, 0, v10
	v_readlane_b32 s3, v253, 29
	s_nop 0
	v_lshrrev_b64 v[10:11], v38, vcc
	v_and_b32_e32 v11, v10, v208
	v_bcnt_u32_b32 v11, v11, v14
	v_cmp_lt_i32_e32 vcc, v11, v13
	s_and_b64 s[0:1], s[0:1], vcc
	s_or_b64 s[0:1], s[2:3], s[0:1]
	v_cndmask_b32_e64 v11, 0, 1, s[0:1]
	v_cmp_ne_u32_e32 vcc, 0, v11
	s_and_saveexec_b64 s[0:1], s[8:9]
	v_mov_b32_e32 v11, s79
	v_mov_b32_e32 v15, vcc_lo
	v_mov_b32_e32 v16, vcc_hi
	ds_write2_b32 v11, v15, v16 offset0:49 offset1:113
	s_or_b64 exec, exec, s[0:1]
	v_readlane_b32 s0, v253, 34
	v_readlane_b32 s1, v253, 35
	v_bcnt_u32_b32 v14, v10, v14
	v_readlane_b32 s2, v253, 32
	v_cndmask_b32_e64 v10, 0, 1, s[0:1]
	v_cmp_ne_u32_e32 vcc, 0, v10
	v_readlane_b32 s3, v253, 33
	s_nop 0
	v_lshrrev_b64 v[10:11], v38, vcc
	v_and_b32_e32 v11, v10, v208
	v_bcnt_u32_b32 v11, v11, v14
	v_cmp_lt_i32_e32 vcc, v11, v13
	s_and_b64 s[0:1], s[0:1], vcc
	s_or_b64 s[0:1], s[2:3], s[0:1]
	v_cndmask_b32_e64 v11, 0, 1, s[0:1]
	v_cmp_ne_u32_e32 vcc, 0, v11
	s_and_saveexec_b64 s[0:1], s[8:9]
	v_mov_b32_e32 v11, s79
; __global__ void __launch_bounds__(512, 2) mega_fwd(KArgs a) {
;     ...
;                     int running = 0;
; #pragma unroll
;                     for (int jj = 0; jj < 64; ++jj) {
;                         const bool e = key[jj] == tau;
;                         const unsigned long long be = __ballot(e);
;                         const unsigned hb = (unsigned)(be >> (32 * qs));
;                         const int rank = running + __popc(hb & ((1u << (lane & 31)) - 1u));
;                         running += __popc(hb);
;                         const bool sel = (key[jj] > tau) || (e && rank < need_eq);
;                         const unsigned long long bm = __ballot(sel);
;                         if (lane == 0) { wscr[jj] = (unsigned)bm; wscr[64 + jj] = (unsigned)(bm >> 32); }
;                     }
	v_mov_b32_e32 v15, vcc_lo
	v_mov_b32_e32 v16, vcc_hi
	ds_write2_b32 v11, v15, v16 offset0:50 offset1:114
	s_or_b64 exec, exec, s[0:1]
	v_readlane_b32 s0, v253, 38
	v_readlane_b32 s1, v253, 39
	v_bcnt_u32_b32 v14, v10, v14
	v_readlane_b32 s2, v253, 36
	v_cndmask_b32_e64 v10, 0, 1, s[0:1]
	v_cmp_ne_u32_e32 vcc, 0, v10
	v_readlane_b32 s3, v253, 37
	s_nop 0
	v_lshrrev_b64 v[10:11], v38, vcc
	v_and_b32_e32 v11, v10, v208
	v_bcnt_u32_b32 v11, v11, v14
	v_cmp_lt_i32_e32 vcc, v11, v13
	s_and_b64 s[0:1], s[0:1], vcc
	s_or_b64 s[0:1], s[2:3], s[0:1]
	v_cndmask_b32_e64 v11, 0, 1, s[0:1]
	v_cmp_ne_u32_e32 vcc, 0, v11
	s_and_saveexec_b64 s[0:1], s[8:9]
	v_mov_b32_e32 v11, s79
	v_mov_b32_e32 v15, vcc_lo
	v_mov_b32_e32 v16, vcc_hi
	ds_write2_b32 v11, v15, v16 offset0:51 offset1:115
	s_or_b64 exec, exec, s[0:1]
	v_readlane_b32 s0, v253, 42
	v_readlane_b32 s1, v253, 43
	v_bcnt_u32_b32 v14, v10, v14
	v_readlane_b32 s2, v253, 40
	v_cndmask_b32_e64 v10, 0, 1, s[0:1]
	v_cmp_ne_u32_e32 vcc, 0, v10
	v_readlane_b32 s3, v253, 41
	s_nop 0
	v_lshrrev_b64 v[10:11], v38, vcc
	v_and_b32_e32 v11, v10, v208
	v_bcnt_u32_b32 v11, v11, v14
	v_cmp_lt_i32_e32 vcc, v11, v13
	s_and_b64 s[0:1], s[0:1], vcc
	s_or_b64 s[0:1], s[2:3], s[0:1]
	v_cndmask_b32_e64 v11, 0, 1, s[0:1]
	v_cmp_ne_u32_e32 vcc, 0, v11
	s_and_saveexec_b64 s[0:1], s[8:9]
	v_mov_b32_e32 v11, s79
	v_mov_b32_e32 v15, vcc_lo
	v_mov_b32_e32 v16, vcc_hi
	ds_write2_b32 v11, v15, v16 offset0:52 offset1:116
	s_or_b64 exec, exec, s[0:1]
	v_readlane_b32 s0, v253, 46
	v_readlane_b32 s1, v253, 47
	v_bcnt_u32_b32 v14, v10, v14
	v_readlane_b32 s2, v253, 44
	v_cndmask_b32_e64 v10, 0, 1, s[0:1]
	v_cmp_ne_u32_e32 vcc, 0, v10
	v_readlane_b32 s3, v253, 45
	s_nop 0
	v_lshrrev_b64 v[10:11], v38, vcc
	v_and_b32_e32 v11, v10, v208
	v_bcnt_u32_b32 v11, v11, v14
	v_cmp_lt_i32_e32 vcc, v11, v13
	s_and_b64 s[0:1], s[0:1], vcc
	s_or_b64 s[0:1], s[2:3], s[0:1]
	v_cndmask_b32_e64 v11, 0, 1, s[0:1]
	v_cmp_ne_u32_e32 vcc, 0, v11
	s_and_saveexec_b64 s[0:1], s[8:9]
	v_mov_b32_e32 v11, s79
	v_mov_b32_e32 v15, vcc_lo
	v_mov_b32_e32 v16, vcc_hi
	ds_write2_b32 v11, v15, v16 offset0:53 offset1:117
	s_or_b64 exec, exec, s[0:1]
	v_readlane_b32 s0, v253, 50
	v_readlane_b32 s1, v253, 51
	v_bcnt_u32_b32 v14, v10, v14
	v_readlane_b32 s2, v253, 48
	v_cndmask_b32_e64 v10, 0, 1, s[0:1]
	v_cmp_ne_u32_e32 vcc, 0, v10
	v_readlane_b32 s3, v253, 49
	s_nop 0
	v_lshrrev_b64 v[10:11], v38, vcc
	v_and_b32_e32 v11, v10, v208
	v_bcnt_u32_b32 v11, v11, v14
	v_cmp_lt_i32_e32 vcc, v11, v13
	s_and_b64 s[0:1], s[0:1], vcc
	s_or_b64 s[0:1], s[2:3], s[0:1]
	v_cndmask_b32_e64 v11, 0, 1, s[0:1]
	v_cmp_ne_u32_e32 vcc, 0, v11
	s_and_saveexec_b64 s[0:1], s[8:9]
	v_mov_b32_e32 v11, s79
	v_mov_b32_e32 v15, vcc_lo
	v_mov_b32_e32 v16, vcc_hi
	ds_write2_b32 v11, v15, v16 offset0:54 offset1:118
	s_or_b64 exec, exec, s[0:1]
	v_readlane_b32 s0, v253, 54
	v_readlane_b32 s1, v253, 55
	v_bcnt_u32_b32 v14, v10, v14
	v_readlane_b32 s2, v253, 52
	v_cndmask_b32_e64 v10, 0, 1, s[0:1]
	v_cmp_ne_u32_e32 vcc, 0, v10
	v_readlane_b32 s3, v253, 53
	s_nop 0
	v_lshrrev_b64 v[10:11], v38, vcc
	v_and_b32_e32 v11, v10, v208
	v_bcnt_u32_b32 v11, v11, v14
	v_cmp_lt_i32_e32 vcc, v11, v13
	s_and_b64 s[0:1], s[0:1], vcc
	s_or_b64 s[0:1], s[2:3], s[0:1]
	v_cndmask_b32_e64 v11, 0, 1, s[0:1]
	v_cmp_ne_u32_e32 vcc, 0, v11
	s_and_saveexec_b64 s[0:1], s[8:9]
	v_mov_b32_e32 v11, s79
	v_mov_b32_e32 v15, vcc_lo
	v_mov_b32_e32 v16, vcc_hi
	ds_write2_b32 v11, v15, v16 offset0:55 offset1:119
	s_or_b64 exec, exec, s[0:1]
	v_readlane_b32 s0, v253, 58
	v_readlane_b32 s1, v253, 59
	v_bcnt_u32_b32 v14, v10, v14
	v_readlane_b32 s2, v253, 56
	v_cndmask_b32_e64 v10, 0, 1, s[0:1]
	v_cmp_ne_u32_e32 vcc, 0, v10
	v_readlane_b32 s3, v253, 57
	s_nop 0
	v_lshrrev_b64 v[10:11], v38, vcc
	v_and_b32_e32 v11, v10, v208
	v_bcnt_u32_b32 v11, v11, v14
	v_cmp_lt_i32_e32 vcc, v11, v13
	s_and_b64 s[0:1], s[0:1], vcc
	s_or_b64 s[0:1], s[2:3], s[0:1]
	v_cndmask_b32_e64 v11, 0, 1, s[0:1]
	v_cmp_ne_u32_e32 vcc, 0, v11
	s_and_saveexec_b64 s[0:1], s[8:9]
	v_mov_b32_e32 v11, s79
	v_mov_b32_e32 v15, vcc_lo
	v_mov_b32_e32 v16, vcc_hi
	ds_write2_b32 v11, v15, v16 offset0:56 offset1:120
	s_or_b64 exec, exec, s[0:1]
	v_readlane_b32 s0, v253, 62
	v_readlane_b32 s1, v253, 63
	v_bcnt_u32_b32 v14, v10, v14
	v_readlane_b32 s2, v253, 60
	v_cndmask_b32_e64 v10, 0, 1, s[0:1]
	v_cmp_ne_u32_e32 vcc, 0, v10
	v_readlane_b32 s3, v253, 61
	s_nop 0
	v_lshrrev_b64 v[10:11], v38, vcc
; __global__ void __launch_bounds__(512, 2) mega_fwd(KArgs a) {
;     ...
;                     int running = 0;
; #pragma unroll
;                     for (int jj = 0; jj < 64; ++jj) {
;                         const bool e = key[jj] == tau;
;                         const unsigned long long be = __ballot(e);
;                         const unsigned hb = (unsigned)(be >> (32 * qs));
;                         const int rank = running + __popc(hb & ((1u << (lane & 31)) - 1u));
;                         running += __popc(hb);
;                         const bool sel = (key[jj] > tau) || (e && rank < need_eq);
;                         const unsigned long long bm = __ballot(sel);
;                         if (lane == 0) { wscr[jj] = (unsigned)bm; wscr[64 + jj] = (unsigned)(bm >> 32); }
;                     }
	v_and_b32_e32 v11, v10, v208
	v_bcnt_u32_b32 v11, v11, v14
	v_cmp_lt_i32_e32 vcc, v11, v13
	s_and_b64 s[0:1], s[0:1], vcc
	s_or_b64 s[0:1], s[2:3], s[0:1]
	v_cndmask_b32_e64 v11, 0, 1, s[0:1]
	v_cmp_ne_u32_e32 vcc, 0, v11
	s_and_saveexec_b64 s[0:1], s[8:9]
	v_mov_b32_e32 v11, s79
	v_mov_b32_e32 v15, vcc_lo
	v_mov_b32_e32 v16, vcc_hi
	ds_write2_b32 v11, v15, v16 offset0:57 offset1:121
	s_or_b64 exec, exec, s[0:1]
	v_readlane_b32 s0, v254, 2
	v_readlane_b32 s1, v254, 3
	v_bcnt_u32_b32 v14, v10, v14
	v_readlane_b32 s2, v254, 0
	v_cndmask_b32_e64 v10, 0, 1, s[0:1]
	v_cmp_ne_u32_e32 vcc, 0, v10
	v_readlane_b32 s3, v254, 1
	s_nop 0
	v_lshrrev_b64 v[10:11], v38, vcc
	v_and_b32_e32 v11, v10, v208
	v_bcnt_u32_b32 v11, v11, v14
	v_cmp_lt_i32_e32 vcc, v11, v13
	s_and_b64 s[0:1], s[0:1], vcc
	s_or_b64 s[0:1], s[2:3], s[0:1]
	v_cndmask_b32_e64 v11, 0, 1, s[0:1]
	v_cmp_ne_u32_e32 vcc, 0, v11
	s_and_saveexec_b64 s[0:1], s[8:9]
	v_mov_b32_e32 v11, s79
	v_mov_b32_e32 v15, vcc_lo
	v_mov_b32_e32 v16, vcc_hi
	ds_write2_b32 v11, v15, v16 offset0:58 offset1:122
	s_or_b64 exec, exec, s[0:1]
	v_readlane_b32 s0, v254, 6
	v_readlane_b32 s1, v254, 7
	v_bcnt_u32_b32 v14, v10, v14
	v_readlane_b32 s2, v254, 4
	v_cndmask_b32_e64 v10, 0, 1, s[0:1]
	v_cmp_ne_u32_e32 vcc, 0, v10
	v_readlane_b32 s3, v254, 5
	s_nop 0
	v_lshrrev_b64 v[10:11], v38, vcc
	v_and_b32_e32 v11, v10, v208
	v_bcnt_u32_b32 v11, v11, v14
	v_cmp_lt_i32_e32 vcc, v11, v13
	s_and_b64 s[0:1], s[0:1], vcc
	s_or_b64 s[0:1], s[2:3], s[0:1]
	v_cndmask_b32_e64 v11, 0, 1, s[0:1]
	v_cmp_ne_u32_e32 vcc, 0, v11
	s_and_saveexec_b64 s[0:1], s[8:9]
	v_mov_b32_e32 v11, s79
	v_mov_b32_e32 v15, vcc_lo
	v_mov_b32_e32 v16, vcc_hi
	ds_write2_b32 v11, v15, v16 offset0:59 offset1:123
	s_or_b64 exec, exec, s[0:1]
	v_readlane_b32 s0, v254, 10
	v_readlane_b32 s1, v254, 11
	v_bcnt_u32_b32 v14, v10, v14
	v_readlane_b32 s2, v254, 8
	v_cndmask_b32_e64 v10, 0, 1, s[0:1]
	v_cmp_ne_u32_e32 vcc, 0, v10
	v_readlane_b32 s3, v254, 9
	s_nop 0
	v_lshrrev_b64 v[10:11], v38, vcc
	v_and_b32_e32 v11, v10, v208
	v_bcnt_u32_b32 v11, v11, v14
	v_cmp_lt_i32_e32 vcc, v11, v13
	s_and_b64 s[0:1], s[0:1], vcc
	s_or_b64 s[0:1], s[2:3], s[0:1]
	v_cndmask_b32_e64 v11, 0, 1, s[0:1]
	v_cmp_ne_u32_e32 vcc, 0, v11
	s_and_saveexec_b64 s[0:1], s[8:9]
	v_mov_b32_e32 v11, s79
	v_mov_b32_e32 v15, vcc_lo
	v_mov_b32_e32 v16, vcc_hi
	ds_write2_b32 v11, v15, v16 offset0:60 offset1:124
	s_or_b64 exec, exec, s[0:1]
	v_readlane_b32 s0, v254, 14
	v_readlane_b32 s1, v254, 15
	v_bcnt_u32_b32 v14, v10, v14
	v_readlane_b32 s2, v254, 12
	v_cndmask_b32_e64 v10, 0, 1, s[0:1]
	v_cmp_ne_u32_e32 vcc, 0, v10
	v_readlane_b32 s3, v254, 13
	s_nop 0
	v_lshrrev_b64 v[10:11], v38, vcc
	v_and_b32_e32 v11, v10, v208
	v_bcnt_u32_b32 v11, v11, v14
	v_cmp_lt_i32_e32 vcc, v11, v13
	s_and_b64 s[0:1], s[0:1], vcc
	s_or_b64 s[0:1], s[2:3], s[0:1]
	v_cndmask_b32_e64 v11, 0, 1, s[0:1]
	v_cmp_ne_u32_e32 vcc, 0, v11
	s_and_saveexec_b64 s[0:1], s[8:9]
	v_mov_b32_e32 v11, s79
	v_mov_b32_e32 v15, vcc_lo
	v_mov_b32_e32 v16, vcc_hi
	ds_write2_b32 v11, v15, v16 offset0:61 offset1:125
	s_or_b64 exec, exec, s[0:1]
	v_readlane_b32 s0, v254, 18
	v_readlane_b32 s1, v254, 19
	v_bcnt_u32_b32 v14, v10, v14
	v_readlane_b32 s2, v254, 16
	v_cndmask_b32_e64 v10, 0, 1, s[0:1]
	v_cmp_ne_u32_e32 vcc, 0, v10
	v_readlane_b32 s3, v254, 17
	s_nop 0
	v_lshrrev_b64 v[10:11], v38, vcc
	v_and_b32_e32 v11, v10, v208
	v_bcnt_u32_b32 v11, v11, v14
	v_cmp_lt_i32_e32 vcc, v11, v13
	s_and_b64 s[0:1], s[0:1], vcc
	s_or_b64 s[0:1], s[2:3], s[0:1]
	v_cndmask_b32_e64 v11, 0, 1, s[0:1]
	v_cmp_ne_u32_e32 vcc, 0, v11
	s_and_saveexec_b64 s[0:1], s[8:9]
	v_mov_b32_e32 v11, s79
	v_mov_b32_e32 v15, vcc_lo
	v_mov_b32_e32 v16, vcc_hi
	ds_write2_b32 v11, v15, v16 offset0:62 offset1:126
	s_or_b64 exec, exec, s[0:1]
	v_bcnt_u32_b32 v14, v10, v14
	v_cndmask_b32_e64 v10, 0, 1, s[96:97]
	v_cmp_ne_u32_e32 vcc, 0, v10
	v_readlane_b32 s2, v254, 20
	v_readlane_b32 s3, v254, 21
	v_lshrrev_b64 v[10:11], v38, vcc
	v_and_b32_e32 v10, v10, v208
	v_bcnt_u32_b32 v10, v10, v14
	v_cmp_lt_i32_e32 vcc, v10, v13
	s_and_b64 s[0:1], s[96:97], vcc
	s_or_b64 s[0:1], s[2:3], s[0:1]
	v_cndmask_b32_e64 v10, 0, 1, s[0:1]
	v_cmp_ne_u32_e32 vcc, 0, v10
	s_and_saveexec_b64 s[0:1], s[8:9]
	v_mov_b32_e32 v10, s79
	v_mov_b32_e32 v11, vcc_lo
	v_mov_b32_e32 v13, vcc_hi
	ds_write2_b32 v10, v11, v13 offset0:63 offset1:127
	s_or_b64 exec, exec, s[0:1]
	s_mov_b64 s[2:3], 0
